# GEMM K loops: the s_setprio 0 / s_setprio 1 pair in the middle of each 32-MFMA block removed (block stays at priority 1 throughout); first raise and final drop kept
# baseline (speedup 1.0000x reference)
.LBB0_289:
	ds_read_b128 v[170:173], v167
	ds_read_b128 v[174:177], v167 offset:1024
	ds_read_b128 v[178:181], v167 offset:2048
	ds_read_b128 v[182:185], v167 offset:3072
	ds_read_b128 v[186:189], v168
	ds_read_b128 v[190:193], v168 offset:1024
	ds_read_b128 v[194:197], v168 offset:2048
	ds_read_b128 v[198:201], v168 offset:3072
	s_add_u32 s26, s24, 0xfffc0080
	s_addc_u32 s27, s25, -1
	s_cmp_eq_u32 s54, 12
	s_cselect_b32 s29, s13, s27
	s_cselect_b32 s28, s50, s26
	s_cselect_b32 s27, s15, s53
	s_cselect_b32 s26, s51, s52
	v_lshl_add_u64 v[164:165], s[24:25], 0, v[158:159]
	s_add_i32 m0, s21, 0xc000
	ds_read_b128 v[210:213], v169
	ds_read_b128 v[214:217], v169 offset:1024
	ds_read_b128 v[218:221], v169 offset:2048
	ds_read_b128 v[222:225], v169 offset:3072
	ds_read_b128 v[226:229], v169 offset:4096
	ds_read_b128 v[230:233], v169 offset:5120
	ds_read_b128 v[234:237], v169 offset:6144
	ds_read_b128 v[238:241], v169 offset:7168
	global_load_lds_dwordx4 v[164:165], off
	v_lshl_add_u64 v[164:165], s[24:25], 0, v[156:157]
	s_add_i32 m0, s21, 0xe000
	s_nop 0
	global_load_lds_dwordx4 v[164:165], off
	s_waitcnt vmcnt(8)
	s_waitcnt lgkmcnt(0)
	s_barrier
	s_setprio 1
	s_waitcnt lgkmcnt(0)
	v_mfma_f32_16x16x32_bf16 v[124:127], v[170:173], v[210:213], v[124:127]
	v_mfma_f32_16x16x32_bf16 v[116:119], v[178:181], v[210:213], v[116:119]
	v_mfma_f32_16x16x32_bf16 v[108:111], v[170:173], v[218:221], v[108:111]
	v_mfma_f32_16x16x32_bf16 v[100:103], v[178:181], v[218:221], v[100:103]
	v_mfma_f32_16x16x32_bf16 v[92:95], v[170:173], v[226:229], v[92:95]
	v_mfma_f32_16x16x32_bf16 v[84:87], v[178:181], v[226:229], v[84:87]
	v_mfma_f32_16x16x32_bf16 v[76:79], v[170:173], v[234:237], v[76:79]
	v_mfma_f32_16x16x32_bf16 v[68:71], v[178:181], v[234:237], v[68:71]
	v_mfma_f32_16x16x32_bf16 v[124:127], v[174:177], v[214:217], v[124:127]
	v_mfma_f32_16x16x32_bf16 v[116:119], v[182:185], v[214:217], v[116:119]
	v_mfma_f32_16x16x32_bf16 v[108:111], v[174:177], v[222:225], v[108:111]
	v_mfma_f32_16x16x32_bf16 v[100:103], v[182:185], v[222:225], v[100:103]
	v_mfma_f32_16x16x32_bf16 v[92:95], v[174:177], v[230:233], v[92:95]
	v_mfma_f32_16x16x32_bf16 v[84:87], v[182:185], v[230:233], v[84:87]
	v_mfma_f32_16x16x32_bf16 v[76:79], v[174:177], v[238:241], v[76:79]
	v_mfma_f32_16x16x32_bf16 v[68:71], v[182:185], v[238:241], v[68:71]
	v_mfma_f32_16x16x32_bf16 v[120:123], v[186:189], v[210:213], v[120:123]
	v_mfma_f32_16x16x32_bf16 v[112:115], v[194:197], v[210:213], v[112:115]
	v_mfma_f32_16x16x32_bf16 v[104:107], v[186:189], v[218:221], v[104:107]
	v_mfma_f32_16x16x32_bf16 v[96:99], v[194:197], v[218:221], v[96:99]
	v_mfma_f32_16x16x32_bf16 v[88:91], v[186:189], v[226:229], v[88:91]
	v_mfma_f32_16x16x32_bf16 v[80:83], v[194:197], v[226:229], v[80:83]
	v_mfma_f32_16x16x32_bf16 v[72:75], v[186:189], v[234:237], v[72:75]
	v_mfma_f32_16x16x32_bf16 v[64:67], v[194:197], v[234:237], v[64:67]
	v_mfma_f32_16x16x32_bf16 v[120:123], v[190:193], v[214:217], v[120:123]
	v_mfma_f32_16x16x32_bf16 v[112:115], v[198:201], v[214:217], v[112:115]
	v_mfma_f32_16x16x32_bf16 v[104:107], v[190:193], v[222:225], v[104:107]
	v_mfma_f32_16x16x32_bf16 v[96:99], v[198:201], v[222:225], v[96:99]
	v_mfma_f32_16x16x32_bf16 v[88:91], v[190:193], v[230:233], v[88:91]
	v_mfma_f32_16x16x32_bf16 v[80:83], v[198:201], v[230:233], v[80:83]
	v_mfma_f32_16x16x32_bf16 v[72:75], v[190:193], v[238:241], v[72:75]
	v_mfma_f32_16x16x32_bf16 v[64:67], v[198:201], v[238:241], v[64:67]
	s_setprio 0
	s_barrier
	s_add_i32 s55, s48, s38
	v_lshl_add_u64 v[164:165], s[26:27], 0, v[134:135]
	s_mov_b32 m0, s55
	ds_read_b128 v[210:213], v169 offset:16384
	ds_read_b128 v[214:217], v169 offset:17408
	ds_read_b128 v[218:221], v169 offset:18432
	ds_read_b128 v[222:225], v169 offset:19456
	ds_read_b128 v[226:229], v169 offset:20480
	ds_read_b128 v[230:233], v169 offset:21504
	ds_read_b128 v[234:237], v169 offset:22528
	ds_read_b128 v[238:241], v169 offset:23552
	global_load_lds_dwordx4 v[164:165], off
	s_add_i32 m0, s55, 0x2000
	s_add_u32 s56, s26, 0x4000
	v_lshl_add_u64 v[164:165], s[26:27], 0, v[130:131]
	s_addc_u32 s57, s27, 0
	s_add_i32 s55, s49, s38
	global_load_lds_dwordx4 v[164:165], off
	v_lshl_add_u64 v[164:165], s[56:57], 0, v[134:135]
	s_mov_b32 m0, s55
	v_lshl_add_u64 v[242:243], s[28:29], 0, v[132:133]
	global_load_lds_dwordx4 v[164:165], off
	v_lshl_add_u64 v[164:165], s[56:57], 0, v[130:131]
	s_add_i32 m0, s55, 0x2000
	s_nop 0
	global_load_lds_dwordx4 v[164:165], off
	v_lshl_add_u64 v[164:165], s[28:29], 0, v[136:137]
	s_mov_b32 m0, s21
	s_nop 0
	global_load_lds_dwordx4 v[164:165], off
	s_mov_b32 m0, s23
	s_nop 0
	global_load_lds_dwordx4 v[242:243], off
	s_waitcnt vmcnt(8)
	s_waitcnt lgkmcnt(0)
	s_barrier
	s_setprio 1
	s_waitcnt lgkmcnt(0)
	v_mfma_f32_16x16x32_bf16 v[60:63], v[170:173], v[210:213], v[60:63]
	v_mfma_f32_16x16x32_bf16 v[52:55], v[178:181], v[210:213], v[52:55]
	v_mfma_f32_16x16x32_bf16 v[44:47], v[170:173], v[218:221], v[44:47]
	v_mfma_f32_16x16x32_bf16 v[36:39], v[178:181], v[218:221], v[36:39]
	v_mfma_f32_16x16x32_bf16 v[28:31], v[170:173], v[226:229], v[28:31]
	v_mfma_f32_16x16x32_bf16 v[20:23], v[178:181], v[226:229], v[20:23]
	v_mfma_f32_16x16x32_bf16 v[12:15], v[170:173], v[234:237], v[12:15]
	v_mfma_f32_16x16x32_bf16 v[4:7], v[178:181], v[234:237], v[4:7]
	v_mfma_f32_16x16x32_bf16 v[60:63], v[174:177], v[214:217], v[60:63]
	v_mfma_f32_16x16x32_bf16 v[52:55], v[182:185], v[214:217], v[52:55]
	v_mfma_f32_16x16x32_bf16 v[44:47], v[174:177], v[222:225], v[44:47]
	v_mfma_f32_16x16x32_bf16 v[36:39], v[182:185], v[222:225], v[36:39]
	v_mfma_f32_16x16x32_bf16 v[28:31], v[174:177], v[230:233], v[28:31]
	v_mfma_f32_16x16x32_bf16 v[20:23], v[182:185], v[230:233], v[20:23]
	v_mfma_f32_16x16x32_bf16 v[12:15], v[174:177], v[238:241], v[12:15]
	v_mfma_f32_16x16x32_bf16 v[4:7], v[182:185], v[238:241], v[4:7]
	v_mfma_f32_16x16x32_bf16 v[56:59], v[186:189], v[210:213], v[56:59]
	v_mfma_f32_16x16x32_bf16 v[48:51], v[194:197], v[210:213], v[48:51]
	v_mfma_f32_16x16x32_bf16 v[40:43], v[186:189], v[218:221], v[40:43]
	v_mfma_f32_16x16x32_bf16 v[32:35], v[194:197], v[218:221], v[32:35]
	v_mfma_f32_16x16x32_bf16 v[24:27], v[186:189], v[226:229], v[24:27]
	v_mfma_f32_16x16x32_bf16 v[16:19], v[194:197], v[226:229], v[16:19]
	v_mfma_f32_16x16x32_bf16 v[8:11], v[186:189], v[234:237], v[8:11]
	v_mfma_f32_16x16x32_bf16 v[0:3], v[194:197], v[234:237], v[0:3]
	v_mfma_f32_16x16x32_bf16 v[56:59], v[190:193], v[214:217], v[56:59]
	v_mfma_f32_16x16x32_bf16 v[48:51], v[198:201], v[214:217], v[48:51]
	v_mfma_f32_16x16x32_bf16 v[40:43], v[190:193], v[222:225], v[40:43]
	v_mfma_f32_16x16x32_bf16 v[32:35], v[198:201], v[222:225], v[32:35]
	v_mfma_f32_16x16x32_bf16 v[24:27], v[190:193], v[230:233], v[24:27]
	v_mfma_f32_16x16x32_bf16 v[16:19], v[198:201], v[230:233], v[16:19]
	v_mfma_f32_16x16x32_bf16 v[8:11], v[190:193], v[238:241], v[8:11]
	v_mfma_f32_16x16x32_bf16 v[0:3], v[198:201], v[238:241], v[0:3]
	s_setprio 0
	s_barrier
	s_add_i32 s55, 0, 0x18000
	s_add_i32 s56, 0, 0x1c000
	v_add_u32_e32 v182, s55, v129
	v_add_u32_e32 v198, s56, v129
	ds_read_b128 v[170:173], v182
	ds_read_b128 v[174:177], v182 offset:1024
	ds_read_b128 v[178:181], v182 offset:2048
	ds_read_b128 v[182:185], v182 offset:3072
	ds_read_b128 v[186:189], v198
	ds_read_b128 v[190:193], v198 offset:1024
	ds_read_b128 v[194:197], v198 offset:2048
	ds_read_b128 v[198:201], v198 offset:3072
	s_add_u32 s28, s28, 0x40000
	s_addc_u32 s29, s29, 0
	s_mov_b32 m0, s41
	v_lshl_add_u64 v[244:245], s[28:29], 0, v[136:137]
	ds_read_b128 v[210:213], v169 offset:32768
	ds_read_b128 v[214:217], v169 offset:33792
	ds_read_b128 v[218:221], v169 offset:34816
	ds_read_b128 v[222:225], v169 offset:35840
	ds_read_b128 v[226:229], v169 offset:36864
	ds_read_b128 v[230:233], v169 offset:37888
	ds_read_b128 v[234:237], v169 offset:38912
	ds_read_b128 v[238:241], v169 offset:39936
	global_load_lds_dwordx4 v[244:245], off
	v_lshl_add_u64 v[244:245], s[28:29], 0, v[132:133]
	s_mov_b32 m0, s42
	s_nop 0
	global_load_lds_dwordx4 v[244:245], off
	s_waitcnt vmcnt(8)
	s_waitcnt lgkmcnt(0)
	s_barrier
	s_setprio 1
	s_waitcnt lgkmcnt(0)
	v_mfma_f32_16x16x32_bf16 v[124:127], v[170:173], v[210:213], v[124:127]
	v_mfma_f32_16x16x32_bf16 v[116:119], v[178:181], v[210:213], v[116:119]
	v_mfma_f32_16x16x32_bf16 v[108:111], v[170:173], v[218:221], v[108:111]
	v_mfma_f32_16x16x32_bf16 v[100:103], v[178:181], v[218:221], v[100:103]
	v_mfma_f32_16x16x32_bf16 v[92:95], v[170:173], v[226:229], v[92:95]
	v_mfma_f32_16x16x32_bf16 v[84:87], v[178:181], v[226:229], v[84:87]
	v_mfma_f32_16x16x32_bf16 v[76:79], v[170:173], v[234:237], v[76:79]
	v_mfma_f32_16x16x32_bf16 v[68:71], v[178:181], v[234:237], v[68:71]
	v_mfma_f32_16x16x32_bf16 v[124:127], v[174:177], v[214:217], v[124:127]
	v_mfma_f32_16x16x32_bf16 v[116:119], v[182:185], v[214:217], v[116:119]
	v_mfma_f32_16x16x32_bf16 v[108:111], v[174:177], v[222:225], v[108:111]
	v_mfma_f32_16x16x32_bf16 v[100:103], v[182:185], v[222:225], v[100:103]
	v_mfma_f32_16x16x32_bf16 v[92:95], v[174:177], v[230:233], v[92:95]
	v_mfma_f32_16x16x32_bf16 v[84:87], v[182:185], v[230:233], v[84:87]
	v_mfma_f32_16x16x32_bf16 v[76:79], v[174:177], v[238:241], v[76:79]
	v_mfma_f32_16x16x32_bf16 v[68:71], v[182:185], v[238:241], v[68:71]
	v_mfma_f32_16x16x32_bf16 v[120:123], v[186:189], v[210:213], v[120:123]
	v_mfma_f32_16x16x32_bf16 v[112:115], v[194:197], v[210:213], v[112:115]
	v_mfma_f32_16x16x32_bf16 v[104:107], v[186:189], v[218:221], v[104:107]
	v_mfma_f32_16x16x32_bf16 v[96:99], v[194:197], v[218:221], v[96:99]
	v_mfma_f32_16x16x32_bf16 v[88:91], v[186:189], v[226:229], v[88:91]
	v_mfma_f32_16x16x32_bf16 v[80:83], v[194:197], v[226:229], v[80:83]
	v_mfma_f32_16x16x32_bf16 v[72:75], v[186:189], v[234:237], v[72:75]
	v_mfma_f32_16x16x32_bf16 v[64:67], v[194:197], v[234:237], v[64:67]
	v_mfma_f32_16x16x32_bf16 v[120:123], v[190:193], v[214:217], v[120:123]
	v_mfma_f32_16x16x32_bf16 v[112:115], v[198:201], v[214:217], v[112:115]
	v_mfma_f32_16x16x32_bf16 v[104:107], v[190:193], v[222:225], v[104:107]
	v_mfma_f32_16x16x32_bf16 v[96:99], v[198:201], v[222:225], v[96:99]
	v_mfma_f32_16x16x32_bf16 v[88:91], v[190:193], v[230:233], v[88:91]
	v_mfma_f32_16x16x32_bf16 v[80:83], v[198:201], v[230:233], v[80:83]
	v_mfma_f32_16x16x32_bf16 v[72:75], v[190:193], v[238:241], v[72:75]
	v_mfma_f32_16x16x32_bf16 v[64:67], v[198:201], v[238:241], v[64:67]
	s_setprio 0
	s_barrier
	s_add_u32 s28, s26, 0x8000
	s_addc_u32 s29, s27, 0
	s_add_i32 s55, s55, s38
	v_lshl_add_u64 v[244:245], s[28:29], 0, v[134:135]
	s_mov_b32 m0, s55
	ds_read_b128 v[210:213], v169 offset:49152
	ds_read_b128 v[214:217], v169 offset:50176
	ds_read_b128 v[218:221], v169 offset:51200
	ds_read_b128 v[222:225], v169 offset:52224
	ds_read_b128 v[226:229], v169 offset:53248
	ds_read_b128 v[230:233], v169 offset:54272
	ds_read_b128 v[234:237], v169 offset:55296
	ds_read_b128 v[238:241], v169 offset:56320
	global_load_lds_dwordx4 v[244:245], off
	s_add_i32 m0, s55, 0x2000
	s_add_u32 s26, s26, 0xc000
	v_lshl_add_u64 v[244:245], s[28:29], 0, v[130:131]
	s_addc_u32 s27, s27, 0
	s_add_i32 s28, s56, s38
	global_load_lds_dwordx4 v[244:245], off
	v_lshl_add_u64 v[244:245], s[26:27], 0, v[134:135]
	s_mov_b32 m0, s28
	v_lshl_add_u64 v[164:165], v[164:165], 0, s[8:9]
	global_load_lds_dwordx4 v[244:245], off
	v_lshl_add_u64 v[244:245], s[26:27], 0, v[130:131]
	s_add_i32 m0, s28, 0x2000
	s_nop 0
	global_load_lds_dwordx4 v[244:245], off
	s_mov_b32 m0, s45
	s_nop 0
	global_load_lds_dwordx4 v[164:165], off
	v_lshl_add_u64 v[164:165], v[242:243], 0, s[8:9]
	s_mov_b32 m0, s46
	s_nop 0
	global_load_lds_dwordx4 v[164:165], off
	s_waitcnt vmcnt(8)
	s_waitcnt lgkmcnt(0)
	s_barrier
	s_setprio 1
	s_waitcnt lgkmcnt(0)
	v_mfma_f32_16x16x32_bf16 v[60:63], v[170:173], v[210:213], v[60:63]
	v_mfma_f32_16x16x32_bf16 v[52:55], v[178:181], v[210:213], v[52:55]
	v_mfma_f32_16x16x32_bf16 v[44:47], v[170:173], v[218:221], v[44:47]
	v_mfma_f32_16x16x32_bf16 v[36:39], v[178:181], v[218:221], v[36:39]
	v_mfma_f32_16x16x32_bf16 v[28:31], v[170:173], v[226:229], v[28:31]
	v_mfma_f32_16x16x32_bf16 v[20:23], v[178:181], v[226:229], v[20:23]
	v_mfma_f32_16x16x32_bf16 v[12:15], v[170:173], v[234:237], v[12:15]
	v_mfma_f32_16x16x32_bf16 v[4:7], v[178:181], v[234:237], v[4:7]
	v_mfma_f32_16x16x32_bf16 v[60:63], v[174:177], v[214:217], v[60:63]
	v_mfma_f32_16x16x32_bf16 v[52:55], v[182:185], v[214:217], v[52:55]
	v_mfma_f32_16x16x32_bf16 v[44:47], v[174:177], v[222:225], v[44:47]
	v_mfma_f32_16x16x32_bf16 v[36:39], v[182:185], v[222:225], v[36:39]
	v_mfma_f32_16x16x32_bf16 v[28:31], v[174:177], v[230:233], v[28:31]
	v_mfma_f32_16x16x32_bf16 v[20:23], v[182:185], v[230:233], v[20:23]
	v_mfma_f32_16x16x32_bf16 v[12:15], v[174:177], v[238:241], v[12:15]
	v_mfma_f32_16x16x32_bf16 v[4:7], v[182:185], v[238:241], v[4:7]
	v_mfma_f32_16x16x32_bf16 v[56:59], v[186:189], v[210:213], v[56:59]
	v_mfma_f32_16x16x32_bf16 v[48:51], v[194:197], v[210:213], v[48:51]
	v_mfma_f32_16x16x32_bf16 v[40:43], v[186:189], v[218:221], v[40:43]
	v_mfma_f32_16x16x32_bf16 v[32:35], v[194:197], v[218:221], v[32:35]
	v_mfma_f32_16x16x32_bf16 v[24:27], v[186:189], v[226:229], v[24:27]
	v_mfma_f32_16x16x32_bf16 v[16:19], v[194:197], v[226:229], v[16:19]
	v_mfma_f32_16x16x32_bf16 v[8:11], v[186:189], v[234:237], v[8:11]
	v_mfma_f32_16x16x32_bf16 v[0:3], v[194:197], v[234:237], v[0:3]
	v_mfma_f32_16x16x32_bf16 v[56:59], v[190:193], v[214:217], v[56:59]
	v_mfma_f32_16x16x32_bf16 v[48:51], v[198:201], v[214:217], v[48:51]
	v_mfma_f32_16x16x32_bf16 v[40:43], v[190:193], v[222:225], v[40:43]
	v_mfma_f32_16x16x32_bf16 v[32:35], v[198:201], v[222:225], v[32:35]
	v_mfma_f32_16x16x32_bf16 v[24:27], v[190:193], v[230:233], v[24:27]
	v_mfma_f32_16x16x32_bf16 v[16:19], v[198:201], v[230:233], v[16:19]
	v_mfma_f32_16x16x32_bf16 v[8:11], v[190:193], v[238:241], v[8:11]
	v_mfma_f32_16x16x32_bf16 v[0:3], v[198:201], v[238:241], v[0:3]
	s_setprio 0
	s_barrier
	s_add_i32 s54, s54, 2
	s_add_u32 s52, s52, 0x10000
	s_addc_u32 s53, s53, 0
	s_add_u32 s24, s24, 0x100
	s_addc_u32 s25, s25, 0
	s_cmp_gt_u32 s54, 13
	s_cbranch_scc0 .LBB0_289
	s_and_b64 vcc, exec, s[10:11]
	s_cbranch_vccz .LBB0_292
	s_barrier

.LBB0_408:
	v_add_u32_e32 v168, s71, v182
	v_add_u32_e32 v204, s72, v182
	ds_read_b128 v[156:159], v168
	ds_read_b128 v[160:163], v168 offset:1024
	ds_read_b128 v[164:167], v168 offset:2048
	ds_read_b128 v[168:171], v168 offset:3072
	ds_read_b128 v[172:175], v204
	ds_read_b128 v[176:179], v204 offset:1024
	ds_read_b128 v[212:215], v204 offset:2048
	ds_read_b128 v[216:219], v204 offset:3072
	s_add_u32 s40, s38, 0x4000
	s_addc_u32 s41, s39, 0
	s_cmp_eq_u32 s49, 40
	s_cselect_b32 s44, s0, s40
	s_cselect_b32 s45, s1, s41
	s_cselect_b32 s42, s36, s47
	s_cselect_b32 s43, s37, s48
	s_add_u32 s40, s44, 0x8000
	s_addc_u32 s41, s45, 0
	v_lshl_add_u64 v[252:253], s[38:39], 0, v[150:151]
	s_add_i32 m0, s58, 0xc000
	ds_read_b128 v[220:223], v199
	ds_read_b128 v[224:227], v199 offset:1024
	ds_read_b128 v[228:231], v199 offset:2048
	ds_read_b128 v[232:235], v199 offset:3072
	ds_read_b128 v[236:239], v199 offset:4096
	ds_read_b128 v[240:243], v199 offset:5120
	ds_read_b128 v[244:247], v199 offset:6144
	ds_read_b128 v[248:251], v199 offset:7168
	global_load_lds_dwordx4 v[252:253], off
	v_lshl_add_u64 v[252:253], s[38:39], 0, v[148:149]
	s_add_i32 m0, s58, 0xe000
	s_nop 0
	global_load_lds_dwordx4 v[252:253], off
	s_waitcnt vmcnt(8)
	s_waitcnt lgkmcnt(0)
	s_barrier
	s_setprio 1
	s_waitcnt lgkmcnt(0)
	v_mfma_f32_16x16x32_bf16 v[124:127], v[156:159], v[220:223], v[124:127]
	v_mfma_f32_16x16x32_bf16 v[120:123], v[164:167], v[220:223], v[120:123]
	v_mfma_f32_16x16x32_bf16 v[116:119], v[156:159], v[228:231], v[116:119]
	v_mfma_f32_16x16x32_bf16 v[108:111], v[164:167], v[228:231], v[108:111]
	v_mfma_f32_16x16x32_bf16 v[92:95], v[156:159], v[236:239], v[92:95]
	v_mfma_f32_16x16x32_bf16 v[88:91], v[164:167], v[236:239], v[88:91]
	v_mfma_f32_16x16x32_bf16 v[84:87], v[156:159], v[244:247], v[84:87]
	v_mfma_f32_16x16x32_bf16 v[76:79], v[164:167], v[244:247], v[76:79]
	v_mfma_f32_16x16x32_bf16 v[124:127], v[160:163], v[224:227], v[124:127]
	v_mfma_f32_16x16x32_bf16 v[120:123], v[168:171], v[224:227], v[120:123]
	v_mfma_f32_16x16x32_bf16 v[116:119], v[160:163], v[232:235], v[116:119]
	v_mfma_f32_16x16x32_bf16 v[108:111], v[168:171], v[232:235], v[108:111]
	v_mfma_f32_16x16x32_bf16 v[92:95], v[160:163], v[240:243], v[92:95]
	v_mfma_f32_16x16x32_bf16 v[88:91], v[168:171], v[240:243], v[88:91]
	v_mfma_f32_16x16x32_bf16 v[84:87], v[160:163], v[248:251], v[84:87]
	v_mfma_f32_16x16x32_bf16 v[76:79], v[168:171], v[248:251], v[76:79]
	v_mfma_f32_16x16x32_bf16 v[112:115], v[172:175], v[220:223], v[112:115]
	v_mfma_f32_16x16x32_bf16 v[104:107], v[212:215], v[220:223], v[104:107]
	v_mfma_f32_16x16x32_bf16 v[100:103], v[172:175], v[228:231], v[100:103]
	v_mfma_f32_16x16x32_bf16 v[96:99], v[212:215], v[228:231], v[96:99]
	v_mfma_f32_16x16x32_bf16 v[80:83], v[172:175], v[236:239], v[80:83]
	v_mfma_f32_16x16x32_bf16 v[72:75], v[212:215], v[236:239], v[72:75]
	v_mfma_f32_16x16x32_bf16 v[68:71], v[172:175], v[244:247], v[68:71]
	v_mfma_f32_16x16x32_bf16 v[64:67], v[212:215], v[244:247], v[64:67]
	v_mfma_f32_16x16x32_bf16 v[112:115], v[176:179], v[224:227], v[112:115]
	v_mfma_f32_16x16x32_bf16 v[104:107], v[216:219], v[224:227], v[104:107]
	v_mfma_f32_16x16x32_bf16 v[100:103], v[176:179], v[232:235], v[100:103]
	v_mfma_f32_16x16x32_bf16 v[96:99], v[216:219], v[232:235], v[96:99]
	v_mfma_f32_16x16x32_bf16 v[80:83], v[176:179], v[240:243], v[80:83]
	v_mfma_f32_16x16x32_bf16 v[72:75], v[216:219], v[240:243], v[72:75]
	v_mfma_f32_16x16x32_bf16 v[68:71], v[176:179], v[248:251], v[68:71]
	v_mfma_f32_16x16x32_bf16 v[64:67], v[216:219], v[248:251], v[64:67]
	s_setprio 0
	s_barrier
	s_add_i32 s50, s71, s57
	v_lshl_add_u64 v[252:253], s[42:43], 0, v[128:129]
	s_mov_b32 m0, s50
	ds_read_b128 v[220:223], v199 offset:16384
	ds_read_b128 v[224:227], v199 offset:17408
	ds_read_b128 v[228:231], v199 offset:18432
	ds_read_b128 v[232:235], v199 offset:19456
	ds_read_b128 v[236:239], v199 offset:20480
	ds_read_b128 v[240:243], v199 offset:21504
	ds_read_b128 v[244:247], v199 offset:22528
	ds_read_b128 v[248:251], v199 offset:23552
	global_load_lds_dwordx4 v[252:253], off
	s_add_i32 m0, s50, 0x2000
	s_add_u32 s50, s42, 0x4000
	v_lshl_add_u64 v[252:253], s[42:43], 0, v[130:131]
	s_addc_u32 s51, s43, 0
	s_add_i32 s52, s72, s57
	global_load_lds_dwordx4 v[252:253], off
	v_lshl_add_u64 v[252:253], s[50:51], 0, v[128:129]
	s_mov_b32 m0, s52
	s_nop 0
	global_load_lds_dwordx4 v[252:253], off
	v_lshl_add_u64 v[252:253], s[50:51], 0, v[130:131]
	s_add_i32 m0, s52, 0x2000
	s_nop 0
	global_load_lds_dwordx4 v[252:253], off
	v_lshl_add_u64 v[252:253], s[44:45], 0, v[128:129]
	s_mov_b32 m0, s58
	s_nop 0
	global_load_lds_dwordx4 v[252:253], off
	v_lshl_add_u64 v[252:253], s[44:45], 0, v[130:131]
	s_mov_b32 m0, s59
	s_nop 0
	global_load_lds_dwordx4 v[252:253], off
	s_waitcnt vmcnt(8)
	s_waitcnt lgkmcnt(0)
	s_barrier
	s_setprio 1
	s_waitcnt lgkmcnt(0)
	v_mfma_f32_16x16x32_bf16 v[60:63], v[156:159], v[220:223], v[60:63]
	v_mfma_f32_16x16x32_bf16 v[56:59], v[164:167], v[220:223], v[56:59]
	v_mfma_f32_16x16x32_bf16 v[52:55], v[156:159], v[228:231], v[52:55]
	v_mfma_f32_16x16x32_bf16 v[44:47], v[164:167], v[228:231], v[44:47]
	v_mfma_f32_16x16x32_bf16 v[32:35], v[156:159], v[236:239], v[32:35]
	v_mfma_f32_16x16x32_bf16 v[24:27], v[164:167], v[236:239], v[24:27]
	v_mfma_f32_16x16x32_bf16 v[20:23], v[156:159], v[244:247], v[20:23]
	v_mfma_f32_16x16x32_bf16 v[12:15], v[164:167], v[244:247], v[12:15]
	v_mfma_f32_16x16x32_bf16 v[60:63], v[160:163], v[224:227], v[60:63]
	v_mfma_f32_16x16x32_bf16 v[56:59], v[168:171], v[224:227], v[56:59]
	v_mfma_f32_16x16x32_bf16 v[52:55], v[160:163], v[232:235], v[52:55]
	v_mfma_f32_16x16x32_bf16 v[44:47], v[168:171], v[232:235], v[44:47]
	v_mfma_f32_16x16x32_bf16 v[32:35], v[160:163], v[240:243], v[32:35]
	v_mfma_f32_16x16x32_bf16 v[24:27], v[168:171], v[240:243], v[24:27]
	v_mfma_f32_16x16x32_bf16 v[20:23], v[160:163], v[248:251], v[20:23]
	v_mfma_f32_16x16x32_bf16 v[12:15], v[168:171], v[248:251], v[12:15]
	v_mfma_f32_16x16x32_bf16 v[48:51], v[172:175], v[220:223], v[48:51]
	v_mfma_f32_16x16x32_bf16 v[40:43], v[212:215], v[220:223], v[40:43]
	v_mfma_f32_16x16x32_bf16 v[36:39], v[172:175], v[228:231], v[36:39]
	v_mfma_f32_16x16x32_bf16 v[28:31], v[212:215], v[228:231], v[28:31]
	v_mfma_f32_16x16x32_bf16 v[16:19], v[172:175], v[236:239], v[16:19]
	v_mfma_f32_16x16x32_bf16 v[8:11], v[212:215], v[236:239], v[8:11]
	v_mfma_f32_16x16x32_bf16 v[4:7], v[172:175], v[244:247], v[4:7]
	v_mfma_f32_16x16x32_bf16 v[0:3], v[212:215], v[244:247], v[0:3]
	v_mfma_f32_16x16x32_bf16 v[48:51], v[176:179], v[224:227], v[48:51]
	v_mfma_f32_16x16x32_bf16 v[40:43], v[216:219], v[224:227], v[40:43]
	v_mfma_f32_16x16x32_bf16 v[36:39], v[176:179], v[232:235], v[36:39]
	v_mfma_f32_16x16x32_bf16 v[28:31], v[216:219], v[232:235], v[28:31]
	v_mfma_f32_16x16x32_bf16 v[16:19], v[176:179], v[240:243], v[16:19]
	v_mfma_f32_16x16x32_bf16 v[8:11], v[216:219], v[240:243], v[8:11]
	v_mfma_f32_16x16x32_bf16 v[4:7], v[176:179], v[248:251], v[4:7]
	v_mfma_f32_16x16x32_bf16 v[0:3], v[216:219], v[248:251], v[0:3]
	s_setprio 0
	s_barrier
	s_add_i32 s50, 0, 0x18000
	s_add_i32 s51, 0, 0x1c000
	v_add_u32_e32 v168, s50, v182
	v_add_u32_e32 v204, s51, v182
	ds_read_b128 v[156:159], v168
	ds_read_b128 v[160:163], v168 offset:1024
	ds_read_b128 v[164:167], v168 offset:2048
	ds_read_b128 v[168:171], v168 offset:3072
	ds_read_b128 v[172:175], v204
	ds_read_b128 v[176:179], v204 offset:1024
	ds_read_b128 v[212:215], v204 offset:2048
	ds_read_b128 v[216:219], v204 offset:3072
	s_add_u32 s44, s44, 0x4000
	s_addc_u32 s45, s45, 0
	s_mov_b32 m0, s60
	v_lshl_add_u64 v[252:253], s[44:45], 0, v[128:129]
	ds_read_b128 v[220:223], v199 offset:32768
	ds_read_b128 v[224:227], v199 offset:33792
	ds_read_b128 v[228:231], v199 offset:34816
	ds_read_b128 v[232:235], v199 offset:35840
	ds_read_b128 v[236:239], v199 offset:36864
	ds_read_b128 v[240:243], v199 offset:37888
	ds_read_b128 v[244:247], v199 offset:38912
	ds_read_b128 v[248:251], v199 offset:39936
	global_load_lds_dwordx4 v[252:253], off
	v_lshl_add_u64 v[252:253], s[44:45], 0, v[130:131]
	s_mov_b32 m0, s61
	s_nop 0
	global_load_lds_dwordx4 v[252:253], off
	s_waitcnt vmcnt(8)
	s_waitcnt lgkmcnt(0)
	s_barrier
	s_setprio 1
	s_waitcnt lgkmcnt(0)
	v_mfma_f32_16x16x32_bf16 v[124:127], v[156:159], v[220:223], v[124:127]
	v_mfma_f32_16x16x32_bf16 v[120:123], v[164:167], v[220:223], v[120:123]
	v_mfma_f32_16x16x32_bf16 v[116:119], v[156:159], v[228:231], v[116:119]
	v_mfma_f32_16x16x32_bf16 v[108:111], v[164:167], v[228:231], v[108:111]
	v_mfma_f32_16x16x32_bf16 v[92:95], v[156:159], v[236:239], v[92:95]
	v_mfma_f32_16x16x32_bf16 v[88:91], v[164:167], v[236:239], v[88:91]
	v_mfma_f32_16x16x32_bf16 v[84:87], v[156:159], v[244:247], v[84:87]
	v_mfma_f32_16x16x32_bf16 v[76:79], v[164:167], v[244:247], v[76:79]
	v_mfma_f32_16x16x32_bf16 v[124:127], v[160:163], v[224:227], v[124:127]
	v_mfma_f32_16x16x32_bf16 v[120:123], v[168:171], v[224:227], v[120:123]
	v_mfma_f32_16x16x32_bf16 v[116:119], v[160:163], v[232:235], v[116:119]
	v_mfma_f32_16x16x32_bf16 v[108:111], v[168:171], v[232:235], v[108:111]
	v_mfma_f32_16x16x32_bf16 v[92:95], v[160:163], v[240:243], v[92:95]
	v_mfma_f32_16x16x32_bf16 v[88:91], v[168:171], v[240:243], v[88:91]
	v_mfma_f32_16x16x32_bf16 v[84:87], v[160:163], v[248:251], v[84:87]
	v_mfma_f32_16x16x32_bf16 v[76:79], v[168:171], v[248:251], v[76:79]
	v_mfma_f32_16x16x32_bf16 v[112:115], v[172:175], v[220:223], v[112:115]
	v_mfma_f32_16x16x32_bf16 v[104:107], v[212:215], v[220:223], v[104:107]
	v_mfma_f32_16x16x32_bf16 v[100:103], v[172:175], v[228:231], v[100:103]
	v_mfma_f32_16x16x32_bf16 v[96:99], v[212:215], v[228:231], v[96:99]
	v_mfma_f32_16x16x32_bf16 v[80:83], v[172:175], v[236:239], v[80:83]
	v_mfma_f32_16x16x32_bf16 v[72:75], v[212:215], v[236:239], v[72:75]
	v_mfma_f32_16x16x32_bf16 v[68:71], v[172:175], v[244:247], v[68:71]
	v_mfma_f32_16x16x32_bf16 v[64:67], v[212:215], v[244:247], v[64:67]
	v_mfma_f32_16x16x32_bf16 v[112:115], v[176:179], v[224:227], v[112:115]
	v_mfma_f32_16x16x32_bf16 v[104:107], v[216:219], v[224:227], v[104:107]
	v_mfma_f32_16x16x32_bf16 v[100:103], v[176:179], v[232:235], v[100:103]
	v_mfma_f32_16x16x32_bf16 v[96:99], v[216:219], v[232:235], v[96:99]
	v_mfma_f32_16x16x32_bf16 v[80:83], v[176:179], v[240:243], v[80:83]
	v_mfma_f32_16x16x32_bf16 v[72:75], v[216:219], v[240:243], v[72:75]
	v_mfma_f32_16x16x32_bf16 v[68:71], v[176:179], v[248:251], v[68:71]
	v_mfma_f32_16x16x32_bf16 v[64:67], v[216:219], v[248:251], v[64:67]
	s_setprio 0
	s_barrier
	s_add_u32 s44, s42, 0x8000
	s_addc_u32 s45, s43, 0
	s_add_i32 s50, s50, s57
	v_lshl_add_u64 v[252:253], s[44:45], 0, v[128:129]
	s_mov_b32 m0, s50
	ds_read_b128 v[220:223], v199 offset:49152
	ds_read_b128 v[224:227], v199 offset:50176
	ds_read_b128 v[228:231], v199 offset:51200
	ds_read_b128 v[232:235], v199 offset:52224
	ds_read_b128 v[236:239], v199 offset:53248
	ds_read_b128 v[240:243], v199 offset:54272
	ds_read_b128 v[244:247], v199 offset:55296
	ds_read_b128 v[248:251], v199 offset:56320
	global_load_lds_dwordx4 v[252:253], off
	s_add_i32 m0, s50, 0x2000
	s_add_u32 s42, s42, 0xc000
	v_lshl_add_u64 v[252:253], s[44:45], 0, v[130:131]
	s_addc_u32 s43, s43, 0
	s_add_i32 s44, s51, s57
	global_load_lds_dwordx4 v[252:253], off
	v_lshl_add_u64 v[252:253], s[42:43], 0, v[128:129]
	s_mov_b32 m0, s44
	s_nop 0
	global_load_lds_dwordx4 v[252:253], off
	v_lshl_add_u64 v[252:253], s[42:43], 0, v[130:131]
	s_add_i32 m0, s44, 0x2000
	s_nop 0
	global_load_lds_dwordx4 v[252:253], off
	v_lshl_add_u64 v[252:253], s[40:41], 0, v[128:129]
	s_mov_b32 m0, s67
	s_nop 0
	global_load_lds_dwordx4 v[252:253], off
	v_lshl_add_u64 v[252:253], s[40:41], 0, v[130:131]
	s_mov_b32 m0, s68
	s_nop 0
	global_load_lds_dwordx4 v[252:253], off
	s_waitcnt vmcnt(8)
	s_waitcnt lgkmcnt(0)
	s_barrier
	s_setprio 1
	s_waitcnt lgkmcnt(0)
	v_mfma_f32_16x16x32_bf16 v[60:63], v[156:159], v[220:223], v[60:63]
	v_mfma_f32_16x16x32_bf16 v[56:59], v[164:167], v[220:223], v[56:59]
	v_mfma_f32_16x16x32_bf16 v[52:55], v[156:159], v[228:231], v[52:55]
	v_mfma_f32_16x16x32_bf16 v[44:47], v[164:167], v[228:231], v[44:47]
	v_mfma_f32_16x16x32_bf16 v[32:35], v[156:159], v[236:239], v[32:35]
	v_mfma_f32_16x16x32_bf16 v[24:27], v[164:167], v[236:239], v[24:27]
	v_mfma_f32_16x16x32_bf16 v[20:23], v[156:159], v[244:247], v[20:23]
	v_mfma_f32_16x16x32_bf16 v[12:15], v[164:167], v[244:247], v[12:15]
	v_mfma_f32_16x16x32_bf16 v[60:63], v[160:163], v[224:227], v[60:63]
	v_mfma_f32_16x16x32_bf16 v[56:59], v[168:171], v[224:227], v[56:59]
	v_mfma_f32_16x16x32_bf16 v[52:55], v[160:163], v[232:235], v[52:55]
	v_mfma_f32_16x16x32_bf16 v[44:47], v[168:171], v[232:235], v[44:47]
	v_mfma_f32_16x16x32_bf16 v[32:35], v[160:163], v[240:243], v[32:35]
	v_mfma_f32_16x16x32_bf16 v[24:27], v[168:171], v[240:243], v[24:27]
	v_mfma_f32_16x16x32_bf16 v[20:23], v[160:163], v[248:251], v[20:23]
	v_mfma_f32_16x16x32_bf16 v[12:15], v[168:171], v[248:251], v[12:15]
	v_mfma_f32_16x16x32_bf16 v[48:51], v[172:175], v[220:223], v[48:51]
	v_mfma_f32_16x16x32_bf16 v[40:43], v[212:215], v[220:223], v[40:43]
	v_mfma_f32_16x16x32_bf16 v[36:39], v[172:175], v[228:231], v[36:39]
	v_mfma_f32_16x16x32_bf16 v[28:31], v[212:215], v[228:231], v[28:31]
	v_mfma_f32_16x16x32_bf16 v[16:19], v[172:175], v[236:239], v[16:19]
	v_mfma_f32_16x16x32_bf16 v[8:11], v[212:215], v[236:239], v[8:11]
	v_mfma_f32_16x16x32_bf16 v[4:7], v[172:175], v[244:247], v[4:7]
	v_mfma_f32_16x16x32_bf16 v[0:3], v[212:215], v[244:247], v[0:3]
	v_mfma_f32_16x16x32_bf16 v[48:51], v[176:179], v[224:227], v[48:51]
	v_mfma_f32_16x16x32_bf16 v[40:43], v[216:219], v[224:227], v[40:43]
	v_mfma_f32_16x16x32_bf16 v[36:39], v[176:179], v[232:235], v[36:39]
	v_mfma_f32_16x16x32_bf16 v[28:31], v[216:219], v[232:235], v[28:31]
	v_mfma_f32_16x16x32_bf16 v[16:19], v[176:179], v[240:243], v[16:19]
	v_mfma_f32_16x16x32_bf16 v[8:11], v[216:219], v[240:243], v[8:11]
	v_mfma_f32_16x16x32_bf16 v[4:7], v[176:179], v[248:251], v[4:7]
	v_mfma_f32_16x16x32_bf16 v[0:3], v[216:219], v[248:251], v[0:3]
	s_setprio 0
	s_barrier
	s_add_i32 s49, s49, 2
	s_add_u32 s47, s47, 0x10000
	s_addc_u32 s48, s48, 0
	s_add_u32 s38, s38, 0x10000
	s_addc_u32 s39, s39, 0
	s_cmp_gt_u32 s49, 41
	s_cbranch_scc0 .LBB0_408
	s_and_b64 vcc, exec, s[14:15]
	s_cbranch_vccz .LBB0_411
	s_barrier

.LBB0_492:
	ds_read_b128 v[128:131], v212
	ds_read_b128 v[132:135], v212 offset:1024
	ds_read_b128 v[136:139], v212 offset:2048
	ds_read_b128 v[140:143], v212 offset:3072
	ds_read_b128 v[144:147], v213
	ds_read_b128 v[148:151], v213 offset:1024
	ds_read_b128 v[152:155], v213 offset:2048
	ds_read_b128 v[156:159], v213 offset:3072
	s_add_u32 s34, s30, 0xfffc0080
	s_addc_u32 s35, s31, -1
	s_cmp_eq_u32 s39, 12
	s_cselect_b32 s37, s1, s35
	s_cselect_b32 s36, s7, s34
	s_cselect_b32 s35, s10, s38
	s_cselect_b32 s34, s23, s25
	v_lshl_add_u64 v[200:201], s[30:31], 0, v[190:191]
	s_add_i32 m0, s47, 0xc000
	ds_read_b128 v[160:163], v214
	ds_read_b128 v[164:167], v214 offset:1024
	ds_read_b128 v[196:199], v214 offset:2048
	ds_read_b128 v[216:219], v214 offset:3072
	ds_read_b128 v[220:223], v214 offset:4096
	ds_read_b128 v[224:227], v214 offset:5120
	ds_read_b128 v[228:231], v214 offset:6144
	ds_read_b128 v[232:235], v214 offset:7168
	global_load_lds_dwordx4 v[200:201], off
	v_lshl_add_u64 v[200:201], s[30:31], 0, v[188:189]
	s_add_i32 m0, s47, 0xe000
	s_nop 0
	global_load_lds_dwordx4 v[200:201], off
	s_waitcnt vmcnt(8)
	s_waitcnt lgkmcnt(0)
	s_barrier
	s_setprio 1
	s_waitcnt lgkmcnt(0)
	v_mfma_f32_16x16x32_bf16 v[124:127], v[128:131], v[160:163], v[124:127]
	v_mfma_f32_16x16x32_bf16 v[120:123], v[136:139], v[160:163], v[120:123]
	v_mfma_f32_16x16x32_bf16 v[116:119], v[128:131], v[196:199], v[116:119]
	v_mfma_f32_16x16x32_bf16 v[112:115], v[136:139], v[196:199], v[112:115]
	v_mfma_f32_16x16x32_bf16 v[108:111], v[128:131], v[220:223], v[108:111]
	v_mfma_f32_16x16x32_bf16 v[104:107], v[136:139], v[220:223], v[104:107]
	v_mfma_f32_16x16x32_bf16 v[100:103], v[128:131], v[228:231], v[100:103]
	v_mfma_f32_16x16x32_bf16 v[96:99], v[136:139], v[228:231], v[96:99]
	v_mfma_f32_16x16x32_bf16 v[124:127], v[132:135], v[164:167], v[124:127]
	v_mfma_f32_16x16x32_bf16 v[120:123], v[140:143], v[164:167], v[120:123]
	v_mfma_f32_16x16x32_bf16 v[116:119], v[132:135], v[216:219], v[116:119]
	v_mfma_f32_16x16x32_bf16 v[112:115], v[140:143], v[216:219], v[112:115]
	v_mfma_f32_16x16x32_bf16 v[108:111], v[132:135], v[224:227], v[108:111]
	v_mfma_f32_16x16x32_bf16 v[104:107], v[140:143], v[224:227], v[104:107]
	v_mfma_f32_16x16x32_bf16 v[100:103], v[132:135], v[232:235], v[100:103]
	v_mfma_f32_16x16x32_bf16 v[96:99], v[140:143], v[232:235], v[96:99]
	v_mfma_f32_16x16x32_bf16 v[60:63], v[144:147], v[160:163], v[60:63]
	v_mfma_f32_16x16x32_bf16 v[56:59], v[152:155], v[160:163], v[56:59]
	v_mfma_f32_16x16x32_bf16 v[52:55], v[144:147], v[196:199], v[52:55]
	v_mfma_f32_16x16x32_bf16 v[48:51], v[152:155], v[196:199], v[48:51]
	v_mfma_f32_16x16x32_bf16 v[44:47], v[144:147], v[220:223], v[44:47]
	v_mfma_f32_16x16x32_bf16 v[40:43], v[152:155], v[220:223], v[40:43]
	v_mfma_f32_16x16x32_bf16 v[36:39], v[144:147], v[228:231], v[36:39]
	v_mfma_f32_16x16x32_bf16 v[32:35], v[152:155], v[228:231], v[32:35]
	v_mfma_f32_16x16x32_bf16 v[60:63], v[148:151], v[164:167], v[60:63]
	v_mfma_f32_16x16x32_bf16 v[56:59], v[156:159], v[164:167], v[56:59]
	v_mfma_f32_16x16x32_bf16 v[52:55], v[148:151], v[216:219], v[52:55]
	v_mfma_f32_16x16x32_bf16 v[48:51], v[156:159], v[216:219], v[48:51]
	v_mfma_f32_16x16x32_bf16 v[44:47], v[148:151], v[224:227], v[44:47]
	v_mfma_f32_16x16x32_bf16 v[40:43], v[156:159], v[224:227], v[40:43]
	v_mfma_f32_16x16x32_bf16 v[36:39], v[148:151], v[232:235], v[36:39]
	v_mfma_f32_16x16x32_bf16 v[32:35], v[156:159], v[232:235], v[32:35]
	s_setprio 0
	s_barrier
	s_add_i32 s66, s61, s46
	v_lshl_add_u64 v[200:201], s[34:35], 0, v[172:173]
	s_mov_b32 m0, s66
	ds_read_b128 v[160:163], v214 offset:16384
	ds_read_b128 v[164:167], v214 offset:17408
	ds_read_b128 v[196:199], v214 offset:18432
	ds_read_b128 v[216:219], v214 offset:19456
	ds_read_b128 v[220:223], v214 offset:20480
	ds_read_b128 v[224:227], v214 offset:21504
	ds_read_b128 v[228:231], v214 offset:22528
	ds_read_b128 v[232:235], v214 offset:23552
	global_load_lds_dwordx4 v[200:201], off
	s_add_i32 m0, s66, 0x2000
	s_add_u32 s66, s34, 0x4000
	v_lshl_add_u64 v[200:201], s[34:35], 0, v[176:177]
	s_addc_u32 s67, s35, 0
	s_add_i32 s68, s62, s46
	global_load_lds_dwordx4 v[200:201], off
	v_lshl_add_u64 v[200:201], s[66:67], 0, v[172:173]
	s_mov_b32 m0, s68
	v_lshl_add_u64 v[236:237], s[36:37], 0, v[174:175]
	global_load_lds_dwordx4 v[200:201], off
	v_lshl_add_u64 v[200:201], s[66:67], 0, v[176:177]
	s_add_i32 m0, s68, 0x2000
	s_nop 0
	global_load_lds_dwordx4 v[200:201], off
	v_lshl_add_u64 v[200:201], s[36:37], 0, v[170:171]
	s_mov_b32 m0, s47
	s_nop 0
	global_load_lds_dwordx4 v[200:201], off
	s_mov_b32 m0, s48
	s_nop 0
	global_load_lds_dwordx4 v[236:237], off
	s_waitcnt vmcnt(8)
	s_waitcnt lgkmcnt(0)
	s_barrier
	s_setprio 1
	s_waitcnt lgkmcnt(0)
	v_mfma_f32_16x16x32_bf16 v[92:95], v[128:131], v[160:163], v[92:95]
	v_mfma_f32_16x16x32_bf16 v[88:91], v[136:139], v[160:163], v[88:91]
	v_mfma_f32_16x16x32_bf16 v[84:87], v[128:131], v[196:199], v[84:87]
	v_mfma_f32_16x16x32_bf16 v[80:83], v[136:139], v[196:199], v[80:83]
	v_mfma_f32_16x16x32_bf16 v[76:79], v[128:131], v[220:223], v[76:79]
	v_mfma_f32_16x16x32_bf16 v[72:75], v[136:139], v[220:223], v[72:75]
	v_mfma_f32_16x16x32_bf16 v[68:71], v[128:131], v[228:231], v[68:71]
	v_mfma_f32_16x16x32_bf16 v[64:67], v[136:139], v[228:231], v[64:67]
	v_mfma_f32_16x16x32_bf16 v[92:95], v[132:135], v[164:167], v[92:95]
	v_mfma_f32_16x16x32_bf16 v[88:91], v[140:143], v[164:167], v[88:91]
	v_mfma_f32_16x16x32_bf16 v[84:87], v[132:135], v[216:219], v[84:87]
	v_mfma_f32_16x16x32_bf16 v[80:83], v[140:143], v[216:219], v[80:83]
	v_mfma_f32_16x16x32_bf16 v[76:79], v[132:135], v[224:227], v[76:79]
	v_mfma_f32_16x16x32_bf16 v[72:75], v[140:143], v[224:227], v[72:75]
	v_mfma_f32_16x16x32_bf16 v[68:71], v[132:135], v[232:235], v[68:71]
	v_mfma_f32_16x16x32_bf16 v[64:67], v[140:143], v[232:235], v[64:67]
	v_mfma_f32_16x16x32_bf16 v[28:31], v[144:147], v[160:163], v[28:31]
	v_mfma_f32_16x16x32_bf16 v[24:27], v[152:155], v[160:163], v[24:27]
	v_mfma_f32_16x16x32_bf16 v[20:23], v[144:147], v[196:199], v[20:23]
	v_mfma_f32_16x16x32_bf16 v[16:19], v[152:155], v[196:199], v[16:19]
	v_mfma_f32_16x16x32_bf16 v[12:15], v[144:147], v[220:223], v[12:15]
	v_mfma_f32_16x16x32_bf16 v[8:11], v[152:155], v[220:223], v[8:11]
	v_mfma_f32_16x16x32_bf16 v[4:7], v[144:147], v[228:231], v[4:7]
	v_mfma_f32_16x16x32_bf16 v[0:3], v[152:155], v[228:231], v[0:3]
	v_mfma_f32_16x16x32_bf16 v[28:31], v[148:151], v[164:167], v[28:31]
	v_mfma_f32_16x16x32_bf16 v[24:27], v[156:159], v[164:167], v[24:27]
	v_mfma_f32_16x16x32_bf16 v[20:23], v[148:151], v[216:219], v[20:23]
	v_mfma_f32_16x16x32_bf16 v[16:19], v[156:159], v[216:219], v[16:19]
	v_mfma_f32_16x16x32_bf16 v[12:15], v[148:151], v[224:227], v[12:15]
	v_mfma_f32_16x16x32_bf16 v[8:11], v[156:159], v[224:227], v[8:11]
	v_mfma_f32_16x16x32_bf16 v[4:7], v[148:151], v[232:235], v[4:7]
	v_mfma_f32_16x16x32_bf16 v[0:3], v[156:159], v[232:235], v[0:3]
	s_setprio 0
	s_barrier
	s_add_i32 s66, 0, 0x18000
	s_add_i32 s67, 0, 0x1c000
	v_add_u32_e32 v140, s66, v210
	v_add_u32_e32 v156, s67, v210
	ds_read_b128 v[128:131], v140
	ds_read_b128 v[132:135], v140 offset:1024
	ds_read_b128 v[136:139], v140 offset:2048
	ds_read_b128 v[140:143], v140 offset:3072
	ds_read_b128 v[144:147], v156
	ds_read_b128 v[148:151], v156 offset:1024
	ds_read_b128 v[152:155], v156 offset:2048
	ds_read_b128 v[156:159], v156 offset:3072
	s_add_u32 s36, s36, 0x40000
	s_addc_u32 s37, s37, 0
	s_mov_b32 m0, s49
	v_lshl_add_u64 v[238:239], s[36:37], 0, v[170:171]
	ds_read_b128 v[160:163], v214 offset:32768
	ds_read_b128 v[164:167], v214 offset:33792
	ds_read_b128 v[196:199], v214 offset:34816
	ds_read_b128 v[216:219], v214 offset:35840
	ds_read_b128 v[220:223], v214 offset:36864
	ds_read_b128 v[224:227], v214 offset:37888
	ds_read_b128 v[228:231], v214 offset:38912
	ds_read_b128 v[232:235], v214 offset:39936
	global_load_lds_dwordx4 v[238:239], off
	v_lshl_add_u64 v[238:239], s[36:37], 0, v[174:175]
	s_mov_b32 m0, s50
	s_nop 0
	global_load_lds_dwordx4 v[238:239], off
	s_waitcnt vmcnt(8)
	s_waitcnt lgkmcnt(0)
	s_barrier
	s_setprio 1
	s_waitcnt lgkmcnt(0)
	v_mfma_f32_16x16x32_bf16 v[124:127], v[128:131], v[160:163], v[124:127]
	v_mfma_f32_16x16x32_bf16 v[120:123], v[136:139], v[160:163], v[120:123]
	v_mfma_f32_16x16x32_bf16 v[116:119], v[128:131], v[196:199], v[116:119]
	v_mfma_f32_16x16x32_bf16 v[112:115], v[136:139], v[196:199], v[112:115]
	v_mfma_f32_16x16x32_bf16 v[108:111], v[128:131], v[220:223], v[108:111]
	v_mfma_f32_16x16x32_bf16 v[104:107], v[136:139], v[220:223], v[104:107]
	v_mfma_f32_16x16x32_bf16 v[100:103], v[128:131], v[228:231], v[100:103]
	v_mfma_f32_16x16x32_bf16 v[96:99], v[136:139], v[228:231], v[96:99]
	v_mfma_f32_16x16x32_bf16 v[124:127], v[132:135], v[164:167], v[124:127]
	v_mfma_f32_16x16x32_bf16 v[120:123], v[140:143], v[164:167], v[120:123]
	v_mfma_f32_16x16x32_bf16 v[116:119], v[132:135], v[216:219], v[116:119]
	v_mfma_f32_16x16x32_bf16 v[112:115], v[140:143], v[216:219], v[112:115]
	v_mfma_f32_16x16x32_bf16 v[108:111], v[132:135], v[224:227], v[108:111]
	v_mfma_f32_16x16x32_bf16 v[104:107], v[140:143], v[224:227], v[104:107]
	v_mfma_f32_16x16x32_bf16 v[100:103], v[132:135], v[232:235], v[100:103]
	v_mfma_f32_16x16x32_bf16 v[96:99], v[140:143], v[232:235], v[96:99]
	v_mfma_f32_16x16x32_bf16 v[60:63], v[144:147], v[160:163], v[60:63]
	v_mfma_f32_16x16x32_bf16 v[56:59], v[152:155], v[160:163], v[56:59]
	v_mfma_f32_16x16x32_bf16 v[52:55], v[144:147], v[196:199], v[52:55]
	v_mfma_f32_16x16x32_bf16 v[48:51], v[152:155], v[196:199], v[48:51]
	v_mfma_f32_16x16x32_bf16 v[44:47], v[144:147], v[220:223], v[44:47]
	v_mfma_f32_16x16x32_bf16 v[40:43], v[152:155], v[220:223], v[40:43]
	v_mfma_f32_16x16x32_bf16 v[36:39], v[144:147], v[228:231], v[36:39]
	v_mfma_f32_16x16x32_bf16 v[32:35], v[152:155], v[228:231], v[32:35]
	v_mfma_f32_16x16x32_bf16 v[60:63], v[148:151], v[164:167], v[60:63]
	v_mfma_f32_16x16x32_bf16 v[56:59], v[156:159], v[164:167], v[56:59]
	v_mfma_f32_16x16x32_bf16 v[52:55], v[148:151], v[216:219], v[52:55]
	v_mfma_f32_16x16x32_bf16 v[48:51], v[156:159], v[216:219], v[48:51]
	v_mfma_f32_16x16x32_bf16 v[44:47], v[148:151], v[224:227], v[44:47]
	v_mfma_f32_16x16x32_bf16 v[40:43], v[156:159], v[224:227], v[40:43]
	v_mfma_f32_16x16x32_bf16 v[36:39], v[148:151], v[232:235], v[36:39]
	v_mfma_f32_16x16x32_bf16 v[32:35], v[156:159], v[232:235], v[32:35]
	s_setprio 0
	s_barrier
	s_add_u32 s36, s34, 0x8000
	s_addc_u32 s37, s35, 0
	s_add_i32 s66, s66, s46
	v_lshl_add_u64 v[238:239], s[36:37], 0, v[172:173]
	s_mov_b32 m0, s66
	ds_read_b128 v[160:163], v214 offset:49152
	ds_read_b128 v[164:167], v214 offset:50176
	ds_read_b128 v[196:199], v214 offset:51200
	ds_read_b128 v[216:219], v214 offset:52224
	ds_read_b128 v[220:223], v214 offset:53248
	ds_read_b128 v[224:227], v214 offset:54272
	ds_read_b128 v[228:231], v214 offset:55296
	ds_read_b128 v[232:235], v214 offset:56320
	global_load_lds_dwordx4 v[238:239], off
	s_add_i32 m0, s66, 0x2000
	s_add_u32 s34, s34, 0xc000
	v_lshl_add_u64 v[238:239], s[36:37], 0, v[176:177]
	s_addc_u32 s35, s35, 0
	s_add_i32 s36, s67, s46
	global_load_lds_dwordx4 v[238:239], off
	v_lshl_add_u64 v[238:239], s[34:35], 0, v[172:173]
	s_mov_b32 m0, s36
	v_lshl_add_u64 v[200:201], v[200:201], 0, s[16:17]
	global_load_lds_dwordx4 v[238:239], off
	v_lshl_add_u64 v[238:239], s[34:35], 0, v[176:177]
	s_add_i32 m0, s36, 0x2000
	s_nop 0
	global_load_lds_dwordx4 v[238:239], off
	s_mov_b32 m0, s55
	s_nop 0
	global_load_lds_dwordx4 v[200:201], off
	v_lshl_add_u64 v[200:201], v[236:237], 0, s[16:17]
	s_mov_b32 m0, s56
	s_nop 0
	global_load_lds_dwordx4 v[200:201], off
	s_waitcnt vmcnt(8)
	s_waitcnt lgkmcnt(0)
	s_barrier
	s_setprio 1
	s_waitcnt lgkmcnt(0)
	v_mfma_f32_16x16x32_bf16 v[92:95], v[128:131], v[160:163], v[92:95]
	v_mfma_f32_16x16x32_bf16 v[88:91], v[136:139], v[160:163], v[88:91]
	v_mfma_f32_16x16x32_bf16 v[84:87], v[128:131], v[196:199], v[84:87]
	v_mfma_f32_16x16x32_bf16 v[80:83], v[136:139], v[196:199], v[80:83]
	v_mfma_f32_16x16x32_bf16 v[76:79], v[128:131], v[220:223], v[76:79]
	v_mfma_f32_16x16x32_bf16 v[72:75], v[136:139], v[220:223], v[72:75]
	v_mfma_f32_16x16x32_bf16 v[68:71], v[128:131], v[228:231], v[68:71]
	v_mfma_f32_16x16x32_bf16 v[64:67], v[136:139], v[228:231], v[64:67]
	v_mfma_f32_16x16x32_bf16 v[92:95], v[132:135], v[164:167], v[92:95]
	v_mfma_f32_16x16x32_bf16 v[88:91], v[140:143], v[164:167], v[88:91]
	v_mfma_f32_16x16x32_bf16 v[84:87], v[132:135], v[216:219], v[84:87]
	v_mfma_f32_16x16x32_bf16 v[80:83], v[140:143], v[216:219], v[80:83]
	v_mfma_f32_16x16x32_bf16 v[76:79], v[132:135], v[224:227], v[76:79]
	v_mfma_f32_16x16x32_bf16 v[72:75], v[140:143], v[224:227], v[72:75]
	v_mfma_f32_16x16x32_bf16 v[68:71], v[132:135], v[232:235], v[68:71]
	v_mfma_f32_16x16x32_bf16 v[64:67], v[140:143], v[232:235], v[64:67]
	v_mfma_f32_16x16x32_bf16 v[28:31], v[144:147], v[160:163], v[28:31]
	v_mfma_f32_16x16x32_bf16 v[24:27], v[152:155], v[160:163], v[24:27]
	v_mfma_f32_16x16x32_bf16 v[20:23], v[144:147], v[196:199], v[20:23]
	v_mfma_f32_16x16x32_bf16 v[16:19], v[152:155], v[196:199], v[16:19]
	v_mfma_f32_16x16x32_bf16 v[12:15], v[144:147], v[220:223], v[12:15]
	v_mfma_f32_16x16x32_bf16 v[8:11], v[152:155], v[220:223], v[8:11]
	v_mfma_f32_16x16x32_bf16 v[4:7], v[144:147], v[228:231], v[4:7]
	v_mfma_f32_16x16x32_bf16 v[0:3], v[152:155], v[228:231], v[0:3]
	v_mfma_f32_16x16x32_bf16 v[28:31], v[148:151], v[164:167], v[28:31]
	v_mfma_f32_16x16x32_bf16 v[24:27], v[156:159], v[164:167], v[24:27]
	v_mfma_f32_16x16x32_bf16 v[20:23], v[148:151], v[216:219], v[20:23]
	v_mfma_f32_16x16x32_bf16 v[16:19], v[156:159], v[216:219], v[16:19]
	v_mfma_f32_16x16x32_bf16 v[12:15], v[148:151], v[224:227], v[12:15]
	v_mfma_f32_16x16x32_bf16 v[8:11], v[156:159], v[224:227], v[8:11]
	v_mfma_f32_16x16x32_bf16 v[4:7], v[148:151], v[232:235], v[4:7]
	v_mfma_f32_16x16x32_bf16 v[0:3], v[156:159], v[232:235], v[0:3]
	s_setprio 0
	s_barrier
	s_add_i32 s39, s39, 2
	s_add_u32 s25, s25, 0x10000
	s_addc_u32 s38, s38, 0
	s_add_u32 s30, s30, 0x100
	s_addc_u32 s31, s31, 0
	s_cmp_gt_u32 s39, 13
	s_cbranch_scc0 .LBB0_492
	s_and_b64 vcc, exec, s[18:19]
	s_cbranch_vccz .LBB0_503
	s_barrier
	v_lshl_add_u32 v216, s0, 8, v169
	s_cmp_gt_i32 s6, 4
	s_mov_b64 s[0:1], -1
	s_cbranch_scc1 .LBB0_504

.LBB0_1071:
	ds_read_b128 v[128:131], v170
	ds_read_b128 v[148:151], v170 offset:1024
	ds_read_b128 v[152:155], v170 offset:2048
	ds_read_b128 v[174:177], v170 offset:3072
	ds_read_b128 v[178:181], v171
	ds_read_b128 v[182:185], v171 offset:1024
	ds_read_b128 v[186:189], v171 offset:2048
	ds_read_b128 v[190:193], v171 offset:3072
	s_add_u32 s30, s28, 0xfffe0080
	s_addc_u32 s31, s29, -1
	s_cmp_eq_u32 s56, 4
	s_cselect_b32 s35, s17, s31
	s_cselect_b32 s34, s52, s30
	s_cselect_b32 s31, s19, s55
	s_cselect_b32 s30, s53, s54
	v_lshl_add_u64 v[234:235], s[28:29], 0, v[142:143]
	s_add_i32 m0, s25, 0xc000
	ds_read_b128 v[194:197], v172
	ds_read_b128 v[198:201], v172 offset:1024
	ds_read_b128 v[210:213], v172 offset:2048
	ds_read_b128 v[214:217], v172 offset:3072
	ds_read_b128 v[218:221], v172 offset:4096
	ds_read_b128 v[222:225], v172 offset:5120
	ds_read_b128 v[226:229], v172 offset:6144
	ds_read_b128 v[230:233], v172 offset:7168
	global_load_lds_dwordx4 v[234:235], off
	v_lshl_add_u64 v[234:235], s[28:29], 0, v[140:141]
	s_add_i32 m0, s25, 0xe000
	s_nop 0
	global_load_lds_dwordx4 v[234:235], off
	s_waitcnt vmcnt(8)
	s_waitcnt lgkmcnt(0)
	s_barrier
	s_setprio 1
	s_waitcnt lgkmcnt(0)
	v_mfma_f32_16x16x32_bf16 v[124:127], v[128:131], v[194:197], v[124:127]
	v_mfma_f32_16x16x32_bf16 v[120:123], v[152:155], v[194:197], v[120:123]
	v_mfma_f32_16x16x32_bf16 v[116:119], v[128:131], v[210:213], v[116:119]
	v_mfma_f32_16x16x32_bf16 v[112:115], v[152:155], v[210:213], v[112:115]
	v_mfma_f32_16x16x32_bf16 v[92:95], v[128:131], v[218:221], v[92:95]
	v_mfma_f32_16x16x32_bf16 v[88:91], v[152:155], v[218:221], v[88:91]
	v_mfma_f32_16x16x32_bf16 v[84:87], v[128:131], v[226:229], v[84:87]
	v_mfma_f32_16x16x32_bf16 v[72:75], v[152:155], v[226:229], v[72:75]
	v_mfma_f32_16x16x32_bf16 v[124:127], v[148:151], v[198:201], v[124:127]
	v_mfma_f32_16x16x32_bf16 v[120:123], v[174:177], v[198:201], v[120:123]
	v_mfma_f32_16x16x32_bf16 v[116:119], v[148:151], v[214:217], v[116:119]
	v_mfma_f32_16x16x32_bf16 v[112:115], v[174:177], v[214:217], v[112:115]
	v_mfma_f32_16x16x32_bf16 v[92:95], v[148:151], v[222:225], v[92:95]
	v_mfma_f32_16x16x32_bf16 v[88:91], v[174:177], v[222:225], v[88:91]
	v_mfma_f32_16x16x32_bf16 v[84:87], v[148:151], v[230:233], v[84:87]
	v_mfma_f32_16x16x32_bf16 v[72:75], v[174:177], v[230:233], v[72:75]
	v_mfma_f32_16x16x32_bf16 v[108:111], v[178:181], v[194:197], v[108:111]
	v_mfma_f32_16x16x32_bf16 v[104:107], v[186:189], v[194:197], v[104:107]
	v_mfma_f32_16x16x32_bf16 v[100:103], v[178:181], v[210:213], v[100:103]
	v_mfma_f32_16x16x32_bf16 v[96:99], v[186:189], v[210:213], v[96:99]
	v_mfma_f32_16x16x32_bf16 v[80:83], v[178:181], v[218:221], v[80:83]
	v_mfma_f32_16x16x32_bf16 v[76:79], v[186:189], v[218:221], v[76:79]
	v_mfma_f32_16x16x32_bf16 v[68:71], v[178:181], v[226:229], v[68:71]
	v_mfma_f32_16x16x32_bf16 v[64:67], v[186:189], v[226:229], v[64:67]
	v_mfma_f32_16x16x32_bf16 v[108:111], v[182:185], v[198:201], v[108:111]
	v_mfma_f32_16x16x32_bf16 v[104:107], v[190:193], v[198:201], v[104:107]
	v_mfma_f32_16x16x32_bf16 v[100:103], v[182:185], v[214:217], v[100:103]
	v_mfma_f32_16x16x32_bf16 v[96:99], v[190:193], v[214:217], v[96:99]
	v_mfma_f32_16x16x32_bf16 v[80:83], v[182:185], v[222:225], v[80:83]
	v_mfma_f32_16x16x32_bf16 v[76:79], v[190:193], v[222:225], v[76:79]
	v_mfma_f32_16x16x32_bf16 v[68:71], v[182:185], v[230:233], v[68:71]
	v_mfma_f32_16x16x32_bf16 v[64:67], v[190:193], v[230:233], v[64:67]
	s_setprio 0
	s_barrier
	s_add_i32 s57, s49, s42
	v_lshl_add_u64 v[234:235], s[30:31], 0, v[134:135]
	s_mov_b32 m0, s57
	ds_read_b128 v[194:197], v172 offset:16384
	ds_read_b128 v[198:201], v172 offset:17408
	ds_read_b128 v[210:213], v172 offset:18432
	ds_read_b128 v[214:217], v172 offset:19456
	ds_read_b128 v[218:221], v172 offset:20480
	ds_read_b128 v[222:225], v172 offset:21504
	ds_read_b128 v[226:229], v172 offset:22528
	ds_read_b128 v[230:233], v172 offset:23552
	global_load_lds_dwordx4 v[234:235], off
	s_add_i32 m0, s57, 0x2000
	s_add_u32 s58, s30, 0x4000
	v_lshl_add_u64 v[234:235], s[30:31], 0, v[138:139]
	s_addc_u32 s59, s31, 0
	s_add_i32 s57, s50, s42
	global_load_lds_dwordx4 v[234:235], off
	v_lshl_add_u64 v[234:235], s[58:59], 0, v[134:135]
	s_mov_b32 m0, s57
	v_lshl_add_u64 v[236:237], s[34:35], 0, v[136:137]
	global_load_lds_dwordx4 v[234:235], off
	v_lshl_add_u64 v[234:235], s[58:59], 0, v[138:139]
	s_add_i32 m0, s57, 0x2000
	s_nop 0
	global_load_lds_dwordx4 v[234:235], off
	v_lshl_add_u64 v[234:235], s[34:35], 0, v[132:133]
	s_mov_b32 m0, s25
	s_nop 0
	global_load_lds_dwordx4 v[234:235], off
	s_mov_b32 m0, s27
	s_nop 0
	global_load_lds_dwordx4 v[236:237], off
	s_waitcnt vmcnt(8)
	s_waitcnt lgkmcnt(0)
	s_barrier
	s_setprio 1
	s_waitcnt lgkmcnt(0)
	v_mfma_f32_16x16x32_bf16 v[60:63], v[128:131], v[194:197], v[60:63]
	v_mfma_f32_16x16x32_bf16 v[56:59], v[152:155], v[194:197], v[56:59]
	v_mfma_f32_16x16x32_bf16 v[48:51], v[128:131], v[210:213], v[48:51]
	v_mfma_f32_16x16x32_bf16 v[40:43], v[152:155], v[210:213], v[40:43]
	v_mfma_f32_16x16x32_bf16 v[32:35], v[128:131], v[218:221], v[32:35]
	v_mfma_f32_16x16x32_bf16 v[24:27], v[152:155], v[218:221], v[24:27]
	v_mfma_f32_16x16x32_bf16 v[16:19], v[128:131], v[226:229], v[16:19]
	v_mfma_f32_16x16x32_bf16 v[8:11], v[152:155], v[226:229], v[8:11]
	v_mfma_f32_16x16x32_bf16 v[60:63], v[148:151], v[198:201], v[60:63]
	v_mfma_f32_16x16x32_bf16 v[56:59], v[174:177], v[198:201], v[56:59]
	v_mfma_f32_16x16x32_bf16 v[48:51], v[148:151], v[214:217], v[48:51]
	v_mfma_f32_16x16x32_bf16 v[40:43], v[174:177], v[214:217], v[40:43]
	v_mfma_f32_16x16x32_bf16 v[32:35], v[148:151], v[222:225], v[32:35]
	v_mfma_f32_16x16x32_bf16 v[24:27], v[174:177], v[222:225], v[24:27]
	v_mfma_f32_16x16x32_bf16 v[16:19], v[148:151], v[230:233], v[16:19]
	v_mfma_f32_16x16x32_bf16 v[8:11], v[174:177], v[230:233], v[8:11]
	v_mfma_f32_16x16x32_bf16 v[52:55], v[178:181], v[194:197], v[52:55]
	v_mfma_f32_16x16x32_bf16 v[44:47], v[186:189], v[194:197], v[44:47]
	v_mfma_f32_16x16x32_bf16 v[36:39], v[178:181], v[210:213], v[36:39]
	v_mfma_f32_16x16x32_bf16 v[28:31], v[186:189], v[210:213], v[28:31]
	v_mfma_f32_16x16x32_bf16 v[20:23], v[178:181], v[218:221], v[20:23]
	v_mfma_f32_16x16x32_bf16 v[12:15], v[186:189], v[218:221], v[12:15]
	v_mfma_f32_16x16x32_bf16 v[4:7], v[178:181], v[226:229], v[4:7]
	v_mfma_f32_16x16x32_bf16 v[0:3], v[186:189], v[226:229], v[0:3]
	v_mfma_f32_16x16x32_bf16 v[52:55], v[182:185], v[198:201], v[52:55]
	v_mfma_f32_16x16x32_bf16 v[44:47], v[190:193], v[198:201], v[44:47]
	v_mfma_f32_16x16x32_bf16 v[36:39], v[182:185], v[214:217], v[36:39]
	v_mfma_f32_16x16x32_bf16 v[28:31], v[190:193], v[214:217], v[28:31]
	v_mfma_f32_16x16x32_bf16 v[20:23], v[182:185], v[222:225], v[20:23]
	v_mfma_f32_16x16x32_bf16 v[12:15], v[190:193], v[222:225], v[12:15]
	v_mfma_f32_16x16x32_bf16 v[4:7], v[182:185], v[230:233], v[4:7]
	v_mfma_f32_16x16x32_bf16 v[0:3], v[190:193], v[230:233], v[0:3]
	s_setprio 0
	s_barrier
	s_add_i32 s57, 0, 0x18000
	v_add_u32_e32 v173, s57, v168
	s_add_i32 s58, 0, 0x1c000
	ds_read_b128 v[128:131], v173
	ds_read_b128 v[148:151], v173 offset:1024
	ds_read_b128 v[152:155], v173 offset:2048
	ds_read_b128 v[174:177], v173 offset:3072
	v_add_u32_e32 v173, s58, v168
	ds_read_b128 v[178:181], v173
	ds_read_b128 v[182:185], v173 offset:1024
	ds_read_b128 v[186:189], v173 offset:2048
	ds_read_b128 v[190:193], v173 offset:3072
	s_add_u32 s34, s34, 0x20000
	s_addc_u32 s35, s35, 0
	s_mov_b32 m0, s43
	v_lshl_add_u64 v[238:239], s[34:35], 0, v[132:133]
	ds_read_b128 v[194:197], v172 offset:32768
	ds_read_b128 v[198:201], v172 offset:33792
	ds_read_b128 v[210:213], v172 offset:34816
	ds_read_b128 v[214:217], v172 offset:35840
	ds_read_b128 v[218:221], v172 offset:36864
	ds_read_b128 v[222:225], v172 offset:37888
	ds_read_b128 v[226:229], v172 offset:38912
	ds_read_b128 v[230:233], v172 offset:39936
	global_load_lds_dwordx4 v[238:239], off
	v_lshl_add_u64 v[238:239], s[34:35], 0, v[136:137]
	s_mov_b32 m0, s44
	s_nop 0
	global_load_lds_dwordx4 v[238:239], off
	s_waitcnt vmcnt(8)
	s_waitcnt lgkmcnt(0)
	s_barrier
	s_setprio 1
	s_waitcnt lgkmcnt(0)
	v_mfma_f32_16x16x32_bf16 v[124:127], v[128:131], v[194:197], v[124:127]
	v_mfma_f32_16x16x32_bf16 v[120:123], v[152:155], v[194:197], v[120:123]
	v_mfma_f32_16x16x32_bf16 v[116:119], v[128:131], v[210:213], v[116:119]
	v_mfma_f32_16x16x32_bf16 v[112:115], v[152:155], v[210:213], v[112:115]
	v_mfma_f32_16x16x32_bf16 v[92:95], v[128:131], v[218:221], v[92:95]
	v_mfma_f32_16x16x32_bf16 v[88:91], v[152:155], v[218:221], v[88:91]
	v_mfma_f32_16x16x32_bf16 v[84:87], v[128:131], v[226:229], v[84:87]
	v_mfma_f32_16x16x32_bf16 v[72:75], v[152:155], v[226:229], v[72:75]
	v_mfma_f32_16x16x32_bf16 v[124:127], v[148:151], v[198:201], v[124:127]
	v_mfma_f32_16x16x32_bf16 v[120:123], v[174:177], v[198:201], v[120:123]
	v_mfma_f32_16x16x32_bf16 v[116:119], v[148:151], v[214:217], v[116:119]
	v_mfma_f32_16x16x32_bf16 v[112:115], v[174:177], v[214:217], v[112:115]
	v_mfma_f32_16x16x32_bf16 v[92:95], v[148:151], v[222:225], v[92:95]
	v_mfma_f32_16x16x32_bf16 v[88:91], v[174:177], v[222:225], v[88:91]
	v_mfma_f32_16x16x32_bf16 v[84:87], v[148:151], v[230:233], v[84:87]
	v_mfma_f32_16x16x32_bf16 v[72:75], v[174:177], v[230:233], v[72:75]
	v_mfma_f32_16x16x32_bf16 v[108:111], v[178:181], v[194:197], v[108:111]
	v_mfma_f32_16x16x32_bf16 v[104:107], v[186:189], v[194:197], v[104:107]
	v_mfma_f32_16x16x32_bf16 v[100:103], v[178:181], v[210:213], v[100:103]
	v_mfma_f32_16x16x32_bf16 v[96:99], v[186:189], v[210:213], v[96:99]
	v_mfma_f32_16x16x32_bf16 v[80:83], v[178:181], v[218:221], v[80:83]
	v_mfma_f32_16x16x32_bf16 v[76:79], v[186:189], v[218:221], v[76:79]
	v_mfma_f32_16x16x32_bf16 v[68:71], v[178:181], v[226:229], v[68:71]
	v_mfma_f32_16x16x32_bf16 v[64:67], v[186:189], v[226:229], v[64:67]
	v_mfma_f32_16x16x32_bf16 v[108:111], v[182:185], v[198:201], v[108:111]
	v_mfma_f32_16x16x32_bf16 v[104:107], v[190:193], v[198:201], v[104:107]
	v_mfma_f32_16x16x32_bf16 v[100:103], v[182:185], v[214:217], v[100:103]
	v_mfma_f32_16x16x32_bf16 v[96:99], v[190:193], v[214:217], v[96:99]
	v_mfma_f32_16x16x32_bf16 v[80:83], v[182:185], v[222:225], v[80:83]
	v_mfma_f32_16x16x32_bf16 v[76:79], v[190:193], v[222:225], v[76:79]
	v_mfma_f32_16x16x32_bf16 v[68:71], v[182:185], v[230:233], v[68:71]
	v_mfma_f32_16x16x32_bf16 v[64:67], v[190:193], v[230:233], v[64:67]
	s_setprio 0
	s_barrier
	s_add_u32 s34, s30, 0x8000
	s_addc_u32 s35, s31, 0
	s_add_i32 s57, s57, s42
	v_lshl_add_u64 v[238:239], s[34:35], 0, v[134:135]
	s_mov_b32 m0, s57
	ds_read_b128 v[194:197], v172 offset:49152
	ds_read_b128 v[198:201], v172 offset:50176
	ds_read_b128 v[210:213], v172 offset:51200
	ds_read_b128 v[214:217], v172 offset:52224
	ds_read_b128 v[218:221], v172 offset:53248
	ds_read_b128 v[222:225], v172 offset:54272
	ds_read_b128 v[226:229], v172 offset:55296
	ds_read_b128 v[230:233], v172 offset:56320
	global_load_lds_dwordx4 v[238:239], off
	s_add_i32 m0, s57, 0x2000
	s_add_u32 s30, s30, 0xc000
	v_lshl_add_u64 v[238:239], s[34:35], 0, v[138:139]
	s_addc_u32 s31, s31, 0
	s_add_i32 s34, s58, s42
	global_load_lds_dwordx4 v[238:239], off
	v_lshl_add_u64 v[238:239], s[30:31], 0, v[134:135]
	s_mov_b32 m0, s34
	v_lshl_add_u64 v[234:235], v[234:235], 0, s[12:13]
	global_load_lds_dwordx4 v[238:239], off
	v_lshl_add_u64 v[238:239], s[30:31], 0, v[138:139]
	s_add_i32 m0, s34, 0x2000
	s_nop 0
	global_load_lds_dwordx4 v[238:239], off
	s_mov_b32 m0, s46
	s_nop 0
	global_load_lds_dwordx4 v[234:235], off
	v_lshl_add_u64 v[234:235], v[236:237], 0, s[12:13]
	s_mov_b32 m0, s47
	s_nop 0
	global_load_lds_dwordx4 v[234:235], off
	s_waitcnt vmcnt(8)
	s_waitcnt lgkmcnt(0)
	s_barrier
	s_setprio 1
	s_waitcnt lgkmcnt(0)
	v_mfma_f32_16x16x32_bf16 v[60:63], v[128:131], v[194:197], v[60:63]
	v_mfma_f32_16x16x32_bf16 v[56:59], v[152:155], v[194:197], v[56:59]
	v_mfma_f32_16x16x32_bf16 v[48:51], v[128:131], v[210:213], v[48:51]
	v_mfma_f32_16x16x32_bf16 v[40:43], v[152:155], v[210:213], v[40:43]
	v_mfma_f32_16x16x32_bf16 v[32:35], v[128:131], v[218:221], v[32:35]
	v_mfma_f32_16x16x32_bf16 v[24:27], v[152:155], v[218:221], v[24:27]
	v_mfma_f32_16x16x32_bf16 v[16:19], v[128:131], v[226:229], v[16:19]
	v_mfma_f32_16x16x32_bf16 v[8:11], v[152:155], v[226:229], v[8:11]
	v_mfma_f32_16x16x32_bf16 v[60:63], v[148:151], v[198:201], v[60:63]
	v_mfma_f32_16x16x32_bf16 v[56:59], v[174:177], v[198:201], v[56:59]
	v_mfma_f32_16x16x32_bf16 v[48:51], v[148:151], v[214:217], v[48:51]
	v_mfma_f32_16x16x32_bf16 v[40:43], v[174:177], v[214:217], v[40:43]
	v_mfma_f32_16x16x32_bf16 v[32:35], v[148:151], v[222:225], v[32:35]
	v_mfma_f32_16x16x32_bf16 v[24:27], v[174:177], v[222:225], v[24:27]
	v_mfma_f32_16x16x32_bf16 v[16:19], v[148:151], v[230:233], v[16:19]
	v_mfma_f32_16x16x32_bf16 v[8:11], v[174:177], v[230:233], v[8:11]
	v_mfma_f32_16x16x32_bf16 v[52:55], v[178:181], v[194:197], v[52:55]
	v_mfma_f32_16x16x32_bf16 v[44:47], v[186:189], v[194:197], v[44:47]
	v_mfma_f32_16x16x32_bf16 v[36:39], v[178:181], v[210:213], v[36:39]
	v_mfma_f32_16x16x32_bf16 v[28:31], v[186:189], v[210:213], v[28:31]
	v_mfma_f32_16x16x32_bf16 v[20:23], v[178:181], v[218:221], v[20:23]
	v_mfma_f32_16x16x32_bf16 v[12:15], v[186:189], v[218:221], v[12:15]
	v_mfma_f32_16x16x32_bf16 v[4:7], v[178:181], v[226:229], v[4:7]
	v_mfma_f32_16x16x32_bf16 v[0:3], v[186:189], v[226:229], v[0:3]
	v_mfma_f32_16x16x32_bf16 v[52:55], v[182:185], v[198:201], v[52:55]
	v_mfma_f32_16x16x32_bf16 v[44:47], v[190:193], v[198:201], v[44:47]
	v_mfma_f32_16x16x32_bf16 v[36:39], v[182:185], v[214:217], v[36:39]
	v_mfma_f32_16x16x32_bf16 v[28:31], v[190:193], v[214:217], v[28:31]
	v_mfma_f32_16x16x32_bf16 v[20:23], v[182:185], v[222:225], v[20:23]
	v_mfma_f32_16x16x32_bf16 v[12:15], v[190:193], v[222:225], v[12:15]
	v_mfma_f32_16x16x32_bf16 v[4:7], v[182:185], v[230:233], v[4:7]
	v_mfma_f32_16x16x32_bf16 v[0:3], v[190:193], v[230:233], v[0:3]
	s_setprio 0
	s_barrier
	s_add_i32 s56, s56, 2
	s_add_u32 s54, s54, 0x10000
	s_addc_u32 s55, s55, 0
	s_add_u32 s28, s28, 0x100
	s_addc_u32 s29, s29, 0
	s_cmp_gt_u32 s56, 5
	s_cbranch_scc0 .LBB0_1071
	s_and_b64 vcc, exec, s[14:15]
	s_cbranch_vccz .LBB0_1074
	s_barrier

.LBB0_1095:
	ds_read_b128 v[144:147], v155
	ds_read_b128 v[148:151], v155 offset:1024
	ds_read_b128 v[158:161], v155 offset:2048
	ds_read_b128 v[162:165], v155 offset:3072
	ds_read_b128 v[166:169], v156
	ds_read_b128 v[170:173], v156 offset:1024
	ds_read_b128 v[174:177], v156 offset:2048
	ds_read_b128 v[178:181], v156 offset:3072
	s_add_u32 s28, s26, 0xfffe0080
	s_addc_u32 s29, s27, -1
	s_cmp_eq_u32 s54, 4
	s_cselect_b32 s31, s15, s29
	s_cselect_b32 s30, s50, s28
	s_cselect_b32 s29, s17, s53
	s_cselect_b32 s28, s51, s52
	v_lshl_add_u64 v[222:223], s[26:27], 0, v[130:131]
	s_add_i32 m0, s23, 0xc000
	ds_read_b128 v[182:185], v157
	ds_read_b128 v[186:189], v157 offset:1024
	ds_read_b128 v[190:193], v157 offset:2048
	ds_read_b128 v[194:197], v157 offset:3072
	ds_read_b128 v[198:201], v157 offset:4096
	ds_read_b128 v[210:213], v157 offset:5120
	ds_read_b128 v[214:217], v157 offset:6144
	ds_read_b128 v[218:221], v157 offset:7168
	global_load_lds_dwordx4 v[222:223], off
	v_lshl_add_u64 v[222:223], s[26:27], 0, v[128:129]
	s_add_i32 m0, s23, 0xe000
	s_nop 0
	global_load_lds_dwordx4 v[222:223], off
	s_waitcnt vmcnt(8)
	s_waitcnt lgkmcnt(0)
	s_barrier
	s_setprio 1
	s_waitcnt lgkmcnt(0)
	v_mfma_f32_16x16x32_bf16 v[124:127], v[144:147], v[182:185], v[124:127]
	v_mfma_f32_16x16x32_bf16 v[120:123], v[158:161], v[182:185], v[120:123]
	v_mfma_f32_16x16x32_bf16 v[112:115], v[144:147], v[190:193], v[112:115]
	v_mfma_f32_16x16x32_bf16 v[104:107], v[158:161], v[190:193], v[104:107]
	v_mfma_f32_16x16x32_bf16 v[92:95], v[144:147], v[198:201], v[92:95]
	v_mfma_f32_16x16x32_bf16 v[88:91], v[158:161], v[198:201], v[88:91]
	v_mfma_f32_16x16x32_bf16 v[80:83], v[144:147], v[214:217], v[80:83]
	v_mfma_f32_16x16x32_bf16 v[72:75], v[158:161], v[214:217], v[72:75]
	v_mfma_f32_16x16x32_bf16 v[124:127], v[148:151], v[186:189], v[124:127]
	v_mfma_f32_16x16x32_bf16 v[120:123], v[162:165], v[186:189], v[120:123]
	v_mfma_f32_16x16x32_bf16 v[112:115], v[148:151], v[194:197], v[112:115]
	v_mfma_f32_16x16x32_bf16 v[104:107], v[162:165], v[194:197], v[104:107]
	v_mfma_f32_16x16x32_bf16 v[92:95], v[148:151], v[210:213], v[92:95]
	v_mfma_f32_16x16x32_bf16 v[88:91], v[162:165], v[210:213], v[88:91]
	v_mfma_f32_16x16x32_bf16 v[80:83], v[148:151], v[218:221], v[80:83]
	v_mfma_f32_16x16x32_bf16 v[72:75], v[162:165], v[218:221], v[72:75]
	v_mfma_f32_16x16x32_bf16 v[116:119], v[166:169], v[182:185], v[116:119]
	v_mfma_f32_16x16x32_bf16 v[108:111], v[174:177], v[182:185], v[108:111]
	v_mfma_f32_16x16x32_bf16 v[100:103], v[166:169], v[190:193], v[100:103]
	v_mfma_f32_16x16x32_bf16 v[96:99], v[174:177], v[190:193], v[96:99]
	v_mfma_f32_16x16x32_bf16 v[84:87], v[166:169], v[198:201], v[84:87]
	v_mfma_f32_16x16x32_bf16 v[76:79], v[174:177], v[198:201], v[76:79]
	v_mfma_f32_16x16x32_bf16 v[68:71], v[166:169], v[214:217], v[68:71]
	v_mfma_f32_16x16x32_bf16 v[64:67], v[174:177], v[214:217], v[64:67]
	v_mfma_f32_16x16x32_bf16 v[116:119], v[170:173], v[186:189], v[116:119]
	v_mfma_f32_16x16x32_bf16 v[108:111], v[178:181], v[186:189], v[108:111]
	v_mfma_f32_16x16x32_bf16 v[100:103], v[170:173], v[194:197], v[100:103]
	v_mfma_f32_16x16x32_bf16 v[96:99], v[178:181], v[194:197], v[96:99]
	v_mfma_f32_16x16x32_bf16 v[84:87], v[170:173], v[210:213], v[84:87]
	v_mfma_f32_16x16x32_bf16 v[76:79], v[178:181], v[210:213], v[76:79]
	v_mfma_f32_16x16x32_bf16 v[68:71], v[170:173], v[218:221], v[68:71]
	v_mfma_f32_16x16x32_bf16 v[64:67], v[178:181], v[218:221], v[64:67]
	s_setprio 0
	s_barrier
	s_add_i32 s55, s47, s40
	v_lshl_add_u64 v[222:223], s[28:29], 0, v[134:135]
	s_mov_b32 m0, s55
	ds_read_b128 v[182:185], v157 offset:16384
	ds_read_b128 v[186:189], v157 offset:17408
	ds_read_b128 v[190:193], v157 offset:18432
	ds_read_b128 v[194:197], v157 offset:19456
	ds_read_b128 v[198:201], v157 offset:20480
	ds_read_b128 v[210:213], v157 offset:21504
	ds_read_b128 v[214:217], v157 offset:22528
	ds_read_b128 v[218:221], v157 offset:23552
	global_load_lds_dwordx4 v[222:223], off
	s_add_i32 m0, s55, 0x2000
	s_add_u32 s56, s28, 0x4000
	v_lshl_add_u64 v[222:223], s[28:29], 0, v[138:139]
	s_addc_u32 s57, s29, 0
	s_add_i32 s55, s48, s40
	global_load_lds_dwordx4 v[222:223], off
	v_lshl_add_u64 v[222:223], s[56:57], 0, v[134:135]
	s_mov_b32 m0, s55
	v_lshl_add_u64 v[224:225], s[30:31], 0, v[136:137]
	global_load_lds_dwordx4 v[222:223], off
	v_lshl_add_u64 v[222:223], s[56:57], 0, v[138:139]
	s_add_i32 m0, s55, 0x2000
	s_nop 0
	global_load_lds_dwordx4 v[222:223], off
	v_lshl_add_u64 v[222:223], s[30:31], 0, v[132:133]
	s_mov_b32 m0, s23
	s_nop 0
	global_load_lds_dwordx4 v[222:223], off
	s_mov_b32 m0, s25
	s_nop 0
	global_load_lds_dwordx4 v[224:225], off
	s_waitcnt vmcnt(8)
	s_waitcnt lgkmcnt(0)
	s_barrier
	s_setprio 1
	s_waitcnt lgkmcnt(0)
	v_mfma_f32_16x16x32_bf16 v[60:63], v[144:147], v[182:185], v[60:63]
	v_mfma_f32_16x16x32_bf16 v[56:59], v[158:161], v[182:185], v[56:59]
	v_mfma_f32_16x16x32_bf16 v[48:51], v[144:147], v[190:193], v[48:51]
	v_mfma_f32_16x16x32_bf16 v[40:43], v[158:161], v[190:193], v[40:43]
	v_mfma_f32_16x16x32_bf16 v[28:31], v[144:147], v[198:201], v[28:31]
	v_mfma_f32_16x16x32_bf16 v[24:27], v[158:161], v[198:201], v[24:27]
	v_mfma_f32_16x16x32_bf16 v[16:19], v[144:147], v[214:217], v[16:19]
	v_mfma_f32_16x16x32_bf16 v[8:11], v[158:161], v[214:217], v[8:11]
	v_mfma_f32_16x16x32_bf16 v[60:63], v[148:151], v[186:189], v[60:63]
	v_mfma_f32_16x16x32_bf16 v[56:59], v[162:165], v[186:189], v[56:59]
	v_mfma_f32_16x16x32_bf16 v[48:51], v[148:151], v[194:197], v[48:51]
	v_mfma_f32_16x16x32_bf16 v[40:43], v[162:165], v[194:197], v[40:43]
	v_mfma_f32_16x16x32_bf16 v[28:31], v[148:151], v[210:213], v[28:31]
	v_mfma_f32_16x16x32_bf16 v[24:27], v[162:165], v[210:213], v[24:27]
	v_mfma_f32_16x16x32_bf16 v[16:19], v[148:151], v[218:221], v[16:19]
	v_mfma_f32_16x16x32_bf16 v[8:11], v[162:165], v[218:221], v[8:11]
	v_mfma_f32_16x16x32_bf16 v[52:55], v[166:169], v[182:185], v[52:55]
	v_mfma_f32_16x16x32_bf16 v[44:47], v[174:177], v[182:185], v[44:47]
	v_mfma_f32_16x16x32_bf16 v[36:39], v[166:169], v[190:193], v[36:39]
	v_mfma_f32_16x16x32_bf16 v[32:35], v[174:177], v[190:193], v[32:35]
	v_mfma_f32_16x16x32_bf16 v[20:23], v[166:169], v[198:201], v[20:23]
	v_mfma_f32_16x16x32_bf16 v[12:15], v[174:177], v[198:201], v[12:15]
	v_mfma_f32_16x16x32_bf16 v[4:7], v[166:169], v[214:217], v[4:7]
	v_mfma_f32_16x16x32_bf16 v[0:3], v[174:177], v[214:217], v[0:3]
	v_mfma_f32_16x16x32_bf16 v[52:55], v[170:173], v[186:189], v[52:55]
	v_mfma_f32_16x16x32_bf16 v[44:47], v[178:181], v[186:189], v[44:47]
	v_mfma_f32_16x16x32_bf16 v[36:39], v[170:173], v[194:197], v[36:39]
	v_mfma_f32_16x16x32_bf16 v[32:35], v[178:181], v[194:197], v[32:35]
	v_mfma_f32_16x16x32_bf16 v[20:23], v[170:173], v[210:213], v[20:23]
	v_mfma_f32_16x16x32_bf16 v[12:15], v[178:181], v[210:213], v[12:15]
	v_mfma_f32_16x16x32_bf16 v[4:7], v[170:173], v[218:221], v[4:7]
	v_mfma_f32_16x16x32_bf16 v[0:3], v[178:181], v[218:221], v[0:3]
	s_setprio 0
	s_barrier
	s_add_i32 s55, 0, 0x18000
	s_add_i32 s56, 0, 0x1c000
	v_add_u32_e32 v162, s55, v153
	v_add_u32_e32 v178, s56, v153
	ds_read_b128 v[144:147], v162
	ds_read_b128 v[148:151], v162 offset:1024
	ds_read_b128 v[158:161], v162 offset:2048
	ds_read_b128 v[162:165], v162 offset:3072
	ds_read_b128 v[166:169], v178
	ds_read_b128 v[170:173], v178 offset:1024
	ds_read_b128 v[174:177], v178 offset:2048
	ds_read_b128 v[178:181], v178 offset:3072
	s_add_u32 s30, s30, 0x20000
	s_addc_u32 s31, s31, 0
	s_mov_b32 m0, s41
	v_lshl_add_u64 v[226:227], s[30:31], 0, v[132:133]
	ds_read_b128 v[182:185], v157 offset:32768
	ds_read_b128 v[186:189], v157 offset:33792
	ds_read_b128 v[190:193], v157 offset:34816
	ds_read_b128 v[194:197], v157 offset:35840
	ds_read_b128 v[198:201], v157 offset:36864
	ds_read_b128 v[210:213], v157 offset:37888
	ds_read_b128 v[214:217], v157 offset:38912
	ds_read_b128 v[218:221], v157 offset:39936
	global_load_lds_dwordx4 v[226:227], off
	v_lshl_add_u64 v[226:227], s[30:31], 0, v[136:137]
	s_mov_b32 m0, s42
	s_nop 0
	global_load_lds_dwordx4 v[226:227], off
	s_waitcnt vmcnt(8)
	s_waitcnt lgkmcnt(0)
	s_barrier
	s_setprio 1
	s_waitcnt lgkmcnt(0)
	v_mfma_f32_16x16x32_bf16 v[124:127], v[144:147], v[182:185], v[124:127]
	v_mfma_f32_16x16x32_bf16 v[120:123], v[158:161], v[182:185], v[120:123]
	v_mfma_f32_16x16x32_bf16 v[112:115], v[144:147], v[190:193], v[112:115]
	v_mfma_f32_16x16x32_bf16 v[104:107], v[158:161], v[190:193], v[104:107]
	v_mfma_f32_16x16x32_bf16 v[92:95], v[144:147], v[198:201], v[92:95]
	v_mfma_f32_16x16x32_bf16 v[88:91], v[158:161], v[198:201], v[88:91]
	v_mfma_f32_16x16x32_bf16 v[80:83], v[144:147], v[214:217], v[80:83]
	v_mfma_f32_16x16x32_bf16 v[72:75], v[158:161], v[214:217], v[72:75]
	v_mfma_f32_16x16x32_bf16 v[124:127], v[148:151], v[186:189], v[124:127]
	v_mfma_f32_16x16x32_bf16 v[120:123], v[162:165], v[186:189], v[120:123]
	v_mfma_f32_16x16x32_bf16 v[112:115], v[148:151], v[194:197], v[112:115]
	v_mfma_f32_16x16x32_bf16 v[104:107], v[162:165], v[194:197], v[104:107]
	v_mfma_f32_16x16x32_bf16 v[92:95], v[148:151], v[210:213], v[92:95]
	v_mfma_f32_16x16x32_bf16 v[88:91], v[162:165], v[210:213], v[88:91]
	v_mfma_f32_16x16x32_bf16 v[80:83], v[148:151], v[218:221], v[80:83]
	v_mfma_f32_16x16x32_bf16 v[72:75], v[162:165], v[218:221], v[72:75]
	v_mfma_f32_16x16x32_bf16 v[116:119], v[166:169], v[182:185], v[116:119]
	v_mfma_f32_16x16x32_bf16 v[108:111], v[174:177], v[182:185], v[108:111]
	v_mfma_f32_16x16x32_bf16 v[100:103], v[166:169], v[190:193], v[100:103]
	v_mfma_f32_16x16x32_bf16 v[96:99], v[174:177], v[190:193], v[96:99]
	v_mfma_f32_16x16x32_bf16 v[84:87], v[166:169], v[198:201], v[84:87]
	v_mfma_f32_16x16x32_bf16 v[76:79], v[174:177], v[198:201], v[76:79]
	v_mfma_f32_16x16x32_bf16 v[68:71], v[166:169], v[214:217], v[68:71]
	v_mfma_f32_16x16x32_bf16 v[64:67], v[174:177], v[214:217], v[64:67]
	v_mfma_f32_16x16x32_bf16 v[116:119], v[170:173], v[186:189], v[116:119]
	v_mfma_f32_16x16x32_bf16 v[108:111], v[178:181], v[186:189], v[108:111]
	v_mfma_f32_16x16x32_bf16 v[100:103], v[170:173], v[194:197], v[100:103]
	v_mfma_f32_16x16x32_bf16 v[96:99], v[178:181], v[194:197], v[96:99]
	v_mfma_f32_16x16x32_bf16 v[84:87], v[170:173], v[210:213], v[84:87]
	v_mfma_f32_16x16x32_bf16 v[76:79], v[178:181], v[210:213], v[76:79]
	v_mfma_f32_16x16x32_bf16 v[68:71], v[170:173], v[218:221], v[68:71]
	v_mfma_f32_16x16x32_bf16 v[64:67], v[178:181], v[218:221], v[64:67]
	s_setprio 0
	s_barrier
	s_add_u32 s30, s28, 0x8000
	s_addc_u32 s31, s29, 0
	s_add_i32 s55, s55, s40
	v_lshl_add_u64 v[226:227], s[30:31], 0, v[134:135]
	s_mov_b32 m0, s55
	ds_read_b128 v[182:185], v157 offset:49152
	ds_read_b128 v[186:189], v157 offset:50176
	ds_read_b128 v[190:193], v157 offset:51200
	ds_read_b128 v[194:197], v157 offset:52224
	ds_read_b128 v[198:201], v157 offset:53248
	ds_read_b128 v[210:213], v157 offset:54272
	ds_read_b128 v[214:217], v157 offset:55296
	ds_read_b128 v[218:221], v157 offset:56320
	global_load_lds_dwordx4 v[226:227], off
	s_add_i32 m0, s55, 0x2000
	s_add_u32 s28, s28, 0xc000
	v_lshl_add_u64 v[226:227], s[30:31], 0, v[138:139]
	s_addc_u32 s29, s29, 0
	s_add_i32 s30, s56, s40
	global_load_lds_dwordx4 v[226:227], off
	v_lshl_add_u64 v[226:227], s[28:29], 0, v[134:135]
	s_mov_b32 m0, s30
	v_lshl_add_u64 v[222:223], v[222:223], 0, s[8:9]
	global_load_lds_dwordx4 v[226:227], off
	v_lshl_add_u64 v[226:227], s[28:29], 0, v[138:139]
	s_add_i32 m0, s30, 0x2000
	s_nop 0
	global_load_lds_dwordx4 v[226:227], off
	s_mov_b32 m0, s44
	s_nop 0
	global_load_lds_dwordx4 v[222:223], off
	v_lshl_add_u64 v[222:223], v[224:225], 0, s[8:9]
	s_mov_b32 m0, s45
	s_nop 0
	global_load_lds_dwordx4 v[222:223], off
	s_waitcnt vmcnt(8)
	s_waitcnt lgkmcnt(0)
	s_barrier
	s_setprio 1
	s_waitcnt lgkmcnt(0)
	v_mfma_f32_16x16x32_bf16 v[60:63], v[144:147], v[182:185], v[60:63]
	v_mfma_f32_16x16x32_bf16 v[56:59], v[158:161], v[182:185], v[56:59]
	v_mfma_f32_16x16x32_bf16 v[48:51], v[144:147], v[190:193], v[48:51]
	v_mfma_f32_16x16x32_bf16 v[40:43], v[158:161], v[190:193], v[40:43]
	v_mfma_f32_16x16x32_bf16 v[28:31], v[144:147], v[198:201], v[28:31]
	v_mfma_f32_16x16x32_bf16 v[24:27], v[158:161], v[198:201], v[24:27]
	v_mfma_f32_16x16x32_bf16 v[16:19], v[144:147], v[214:217], v[16:19]
	v_mfma_f32_16x16x32_bf16 v[8:11], v[158:161], v[214:217], v[8:11]
	v_mfma_f32_16x16x32_bf16 v[60:63], v[148:151], v[186:189], v[60:63]
	v_mfma_f32_16x16x32_bf16 v[56:59], v[162:165], v[186:189], v[56:59]
	v_mfma_f32_16x16x32_bf16 v[48:51], v[148:151], v[194:197], v[48:51]
	v_mfma_f32_16x16x32_bf16 v[40:43], v[162:165], v[194:197], v[40:43]
	v_mfma_f32_16x16x32_bf16 v[28:31], v[148:151], v[210:213], v[28:31]
	v_mfma_f32_16x16x32_bf16 v[24:27], v[162:165], v[210:213], v[24:27]
	v_mfma_f32_16x16x32_bf16 v[16:19], v[148:151], v[218:221], v[16:19]
	v_mfma_f32_16x16x32_bf16 v[8:11], v[162:165], v[218:221], v[8:11]
	v_mfma_f32_16x16x32_bf16 v[52:55], v[166:169], v[182:185], v[52:55]
	v_mfma_f32_16x16x32_bf16 v[44:47], v[174:177], v[182:185], v[44:47]
	v_mfma_f32_16x16x32_bf16 v[36:39], v[166:169], v[190:193], v[36:39]
	v_mfma_f32_16x16x32_bf16 v[32:35], v[174:177], v[190:193], v[32:35]
	v_mfma_f32_16x16x32_bf16 v[20:23], v[166:169], v[198:201], v[20:23]
	v_mfma_f32_16x16x32_bf16 v[12:15], v[174:177], v[198:201], v[12:15]
	v_mfma_f32_16x16x32_bf16 v[4:7], v[166:169], v[214:217], v[4:7]
	v_mfma_f32_16x16x32_bf16 v[0:3], v[174:177], v[214:217], v[0:3]
	v_mfma_f32_16x16x32_bf16 v[52:55], v[170:173], v[186:189], v[52:55]
	v_mfma_f32_16x16x32_bf16 v[44:47], v[178:181], v[186:189], v[44:47]
	v_mfma_f32_16x16x32_bf16 v[36:39], v[170:173], v[194:197], v[36:39]
	v_mfma_f32_16x16x32_bf16 v[32:35], v[178:181], v[194:197], v[32:35]
	v_mfma_f32_16x16x32_bf16 v[20:23], v[170:173], v[210:213], v[20:23]
	v_mfma_f32_16x16x32_bf16 v[12:15], v[178:181], v[210:213], v[12:15]
	v_mfma_f32_16x16x32_bf16 v[4:7], v[170:173], v[218:221], v[4:7]
	v_mfma_f32_16x16x32_bf16 v[0:3], v[178:181], v[218:221], v[0:3]
	s_setprio 0
	s_barrier
	s_add_i32 s54, s54, 2
	s_add_u32 s52, s52, 0x10000
	s_addc_u32 s53, s53, 0
	s_add_u32 s26, s26, 0x100
	s_addc_u32 s27, s27, 0
	s_cmp_gt_u32 s54, 5
	s_cbranch_scc0 .LBB0_1095
	s_and_b64 vcc, exec, s[10:11]
	s_cbranch_vccz .LBB0_1098
	s_barrier

.LBB0_1171:
	v_add_u32_e32 v168, s77, v182
	v_add_u32_e32 v204, s78, v182
	ds_read_b128 v[156:159], v168
	ds_read_b128 v[160:163], v168 offset:1024
	ds_read_b128 v[164:167], v168 offset:2048
	ds_read_b128 v[168:171], v168 offset:3072
	ds_read_b128 v[172:175], v204
	ds_read_b128 v[176:179], v204 offset:1024
	ds_read_b128 v[212:215], v204 offset:2048
	ds_read_b128 v[216:219], v204 offset:3072
	s_add_u32 s48, s46, 0xfffc0080
	s_addc_u32 s49, s47, -1
	s_cmp_eq_u32 s54, 12
	s_cselect_b32 s51, s35, s49
	s_cselect_b32 s50, s43, s48
	s_cselect_b32 s49, s37, s53
	s_cselect_b32 s48, s45, s52
	v_lshl_add_u64 v[252:253], s[46:47], 0, v[154:155]
	s_add_i32 m0, s65, 0xc000
	ds_read_b128 v[220:223], v199
	ds_read_b128 v[224:227], v199 offset:1024
	ds_read_b128 v[228:231], v199 offset:2048
	ds_read_b128 v[232:235], v199 offset:3072
	ds_read_b128 v[236:239], v199 offset:4096
	ds_read_b128 v[240:243], v199 offset:5120
	ds_read_b128 v[244:247], v199 offset:6144
	ds_read_b128 v[248:251], v199 offset:7168
	global_load_lds_dwordx4 v[252:253], off
	v_lshl_add_u64 v[252:253], s[46:47], 0, v[152:153]
	s_add_i32 m0, s65, 0xe000
	s_nop 0
	global_load_lds_dwordx4 v[252:253], off
	s_waitcnt vmcnt(8)
	s_waitcnt lgkmcnt(0)
	s_barrier
	s_setprio 1
	s_waitcnt lgkmcnt(0)
	v_mfma_f32_16x16x32_bf16 v[124:127], v[156:159], v[220:223], v[124:127]
	v_mfma_f32_16x16x32_bf16 v[120:123], v[164:167], v[220:223], v[120:123]
	v_mfma_f32_16x16x32_bf16 v[116:119], v[156:159], v[228:231], v[116:119]
	v_mfma_f32_16x16x32_bf16 v[112:115], v[164:167], v[228:231], v[112:115]
	v_mfma_f32_16x16x32_bf16 v[92:95], v[156:159], v[236:239], v[92:95]
	v_mfma_f32_16x16x32_bf16 v[88:91], v[164:167], v[236:239], v[88:91]
	v_mfma_f32_16x16x32_bf16 v[84:87], v[156:159], v[244:247], v[84:87]
	v_mfma_f32_16x16x32_bf16 v[80:83], v[164:167], v[244:247], v[80:83]
	v_mfma_f32_16x16x32_bf16 v[124:127], v[160:163], v[224:227], v[124:127]
	v_mfma_f32_16x16x32_bf16 v[120:123], v[168:171], v[224:227], v[120:123]
	v_mfma_f32_16x16x32_bf16 v[116:119], v[160:163], v[232:235], v[116:119]
	v_mfma_f32_16x16x32_bf16 v[112:115], v[168:171], v[232:235], v[112:115]
	v_mfma_f32_16x16x32_bf16 v[92:95], v[160:163], v[240:243], v[92:95]
	v_mfma_f32_16x16x32_bf16 v[88:91], v[168:171], v[240:243], v[88:91]
	v_mfma_f32_16x16x32_bf16 v[84:87], v[160:163], v[248:251], v[84:87]
	v_mfma_f32_16x16x32_bf16 v[80:83], v[168:171], v[248:251], v[80:83]
	v_mfma_f32_16x16x32_bf16 v[108:111], v[172:175], v[220:223], v[108:111]
	v_mfma_f32_16x16x32_bf16 v[104:107], v[212:215], v[220:223], v[104:107]
	v_mfma_f32_16x16x32_bf16 v[100:103], v[172:175], v[228:231], v[100:103]
	v_mfma_f32_16x16x32_bf16 v[96:99], v[212:215], v[228:231], v[96:99]
	v_mfma_f32_16x16x32_bf16 v[76:79], v[172:175], v[236:239], v[76:79]
	v_mfma_f32_16x16x32_bf16 v[72:75], v[212:215], v[236:239], v[72:75]
	v_mfma_f32_16x16x32_bf16 v[68:71], v[172:175], v[244:247], v[68:71]
	v_mfma_f32_16x16x32_bf16 v[64:67], v[212:215], v[244:247], v[64:67]
	v_mfma_f32_16x16x32_bf16 v[108:111], v[176:179], v[224:227], v[108:111]
	v_mfma_f32_16x16x32_bf16 v[104:107], v[216:219], v[224:227], v[104:107]
	v_mfma_f32_16x16x32_bf16 v[100:103], v[176:179], v[232:235], v[100:103]
	v_mfma_f32_16x16x32_bf16 v[96:99], v[216:219], v[232:235], v[96:99]
	v_mfma_f32_16x16x32_bf16 v[76:79], v[176:179], v[240:243], v[76:79]
	v_mfma_f32_16x16x32_bf16 v[72:75], v[216:219], v[240:243], v[72:75]
	v_mfma_f32_16x16x32_bf16 v[68:71], v[176:179], v[248:251], v[68:71]
	v_mfma_f32_16x16x32_bf16 v[64:67], v[216:219], v[248:251], v[64:67]
	s_setprio 0
	s_barrier
	s_add_i32 s55, s77, s64
	v_lshl_add_u64 v[252:253], s[48:49], 0, v[130:131]
	s_mov_b32 m0, s55
	ds_read_b128 v[220:223], v199 offset:16384
	ds_read_b128 v[224:227], v199 offset:17408
	ds_read_b128 v[228:231], v199 offset:18432
	ds_read_b128 v[232:235], v199 offset:19456
	ds_read_b128 v[236:239], v199 offset:20480
	ds_read_b128 v[240:243], v199 offset:21504
	ds_read_b128 v[244:247], v199 offset:22528
	ds_read_b128 v[248:251], v199 offset:23552
	global_load_lds_dwordx4 v[252:253], off
	s_add_i32 m0, s55, 0x2000
	s_add_u32 s56, s48, 0x4000
	v_lshl_add_u64 v[252:253], s[48:49], 0, v[134:135]
	s_addc_u32 s57, s49, 0
	s_add_i32 s55, s78, s64
	global_load_lds_dwordx4 v[252:253], off
	v_lshl_add_u64 v[252:253], s[56:57], 0, v[130:131]
	s_mov_b32 m0, s55
	v_lshl_add_u64 v[204:205], s[50:51], 0, v[132:133]
	global_load_lds_dwordx4 v[252:253], off
	v_lshl_add_u64 v[252:253], s[56:57], 0, v[134:135]
	s_add_i32 m0, s55, 0x2000
	s_nop 0
	global_load_lds_dwordx4 v[252:253], off
	v_lshl_add_u64 v[252:253], s[50:51], 0, v[128:129]
	s_mov_b32 m0, s65
	s_nop 0
	global_load_lds_dwordx4 v[252:253], off
	s_mov_b32 m0, s66
	s_nop 0
	global_load_lds_dwordx4 v[204:205], off
	s_waitcnt vmcnt(8)
	s_waitcnt lgkmcnt(0)
	s_barrier
	s_setprio 1
	s_waitcnt lgkmcnt(0)
	v_mfma_f32_16x16x32_bf16 v[60:63], v[156:159], v[220:223], v[60:63]
	v_mfma_f32_16x16x32_bf16 v[56:59], v[164:167], v[220:223], v[56:59]
	v_mfma_f32_16x16x32_bf16 v[52:55], v[156:159], v[228:231], v[52:55]
	v_mfma_f32_16x16x32_bf16 v[48:51], v[164:167], v[228:231], v[48:51]
	v_mfma_f32_16x16x32_bf16 v[28:31], v[156:159], v[236:239], v[28:31]
	v_mfma_f32_16x16x32_bf16 v[24:27], v[164:167], v[236:239], v[24:27]
	v_mfma_f32_16x16x32_bf16 v[20:23], v[156:159], v[244:247], v[20:23]
	v_mfma_f32_16x16x32_bf16 v[12:15], v[164:167], v[244:247], v[12:15]
	v_mfma_f32_16x16x32_bf16 v[60:63], v[160:163], v[224:227], v[60:63]
	v_mfma_f32_16x16x32_bf16 v[56:59], v[168:171], v[224:227], v[56:59]
	v_mfma_f32_16x16x32_bf16 v[52:55], v[160:163], v[232:235], v[52:55]
	v_mfma_f32_16x16x32_bf16 v[48:51], v[168:171], v[232:235], v[48:51]
	v_mfma_f32_16x16x32_bf16 v[28:31], v[160:163], v[240:243], v[28:31]
	v_mfma_f32_16x16x32_bf16 v[24:27], v[168:171], v[240:243], v[24:27]
	v_mfma_f32_16x16x32_bf16 v[20:23], v[160:163], v[248:251], v[20:23]
	v_mfma_f32_16x16x32_bf16 v[12:15], v[168:171], v[248:251], v[12:15]
	v_mfma_f32_16x16x32_bf16 v[44:47], v[172:175], v[220:223], v[44:47]
	v_mfma_f32_16x16x32_bf16 v[40:43], v[212:215], v[220:223], v[40:43]
	v_mfma_f32_16x16x32_bf16 v[36:39], v[172:175], v[228:231], v[36:39]
	v_mfma_f32_16x16x32_bf16 v[32:35], v[212:215], v[228:231], v[32:35]
	v_mfma_f32_16x16x32_bf16 v[16:19], v[172:175], v[236:239], v[16:19]
	v_mfma_f32_16x16x32_bf16 v[8:11], v[212:215], v[236:239], v[8:11]
	v_mfma_f32_16x16x32_bf16 v[4:7], v[172:175], v[244:247], v[4:7]
	v_mfma_f32_16x16x32_bf16 v[0:3], v[212:215], v[244:247], v[0:3]
	v_mfma_f32_16x16x32_bf16 v[44:47], v[176:179], v[224:227], v[44:47]
	v_mfma_f32_16x16x32_bf16 v[40:43], v[216:219], v[224:227], v[40:43]
	v_mfma_f32_16x16x32_bf16 v[36:39], v[176:179], v[232:235], v[36:39]
	v_mfma_f32_16x16x32_bf16 v[32:35], v[216:219], v[232:235], v[32:35]
	v_mfma_f32_16x16x32_bf16 v[16:19], v[176:179], v[240:243], v[16:19]
	v_mfma_f32_16x16x32_bf16 v[8:11], v[216:219], v[240:243], v[8:11]
	v_mfma_f32_16x16x32_bf16 v[4:7], v[176:179], v[248:251], v[4:7]
	v_mfma_f32_16x16x32_bf16 v[0:3], v[216:219], v[248:251], v[0:3]
	s_setprio 0
	s_barrier
	s_add_i32 s55, 0, 0x18000
	s_add_i32 s56, 0, 0x1c000
	v_add_u32_e32 v168, s55, v182
	v_add_u32_e32 v206, s56, v182
	ds_read_b128 v[156:159], v168
	ds_read_b128 v[160:163], v168 offset:1024
	ds_read_b128 v[164:167], v168 offset:2048
	ds_read_b128 v[168:171], v168 offset:3072
	ds_read_b128 v[172:175], v206
	ds_read_b128 v[176:179], v206 offset:1024
	ds_read_b128 v[212:215], v206 offset:2048
	ds_read_b128 v[216:219], v206 offset:3072
	s_add_u32 s50, s50, 0x40000
	s_addc_u32 s51, s51, 0
	s_mov_b32 m0, s67
	v_lshl_add_u64 v[206:207], s[50:51], 0, v[128:129]
	ds_read_b128 v[220:223], v199 offset:32768
	ds_read_b128 v[224:227], v199 offset:33792
	ds_read_b128 v[228:231], v199 offset:34816
	ds_read_b128 v[232:235], v199 offset:35840
	ds_read_b128 v[236:239], v199 offset:36864
	ds_read_b128 v[240:243], v199 offset:37888
	ds_read_b128 v[244:247], v199 offset:38912
	ds_read_b128 v[248:251], v199 offset:39936
	global_load_lds_dwordx4 v[206:207], off
	v_lshl_add_u64 v[206:207], s[50:51], 0, v[132:133]
	s_mov_b32 m0, s68
	s_nop 0
	global_load_lds_dwordx4 v[206:207], off
	s_waitcnt vmcnt(8)
	s_waitcnt lgkmcnt(0)
	s_barrier
	s_setprio 1
	s_waitcnt lgkmcnt(0)
	v_mfma_f32_16x16x32_bf16 v[124:127], v[156:159], v[220:223], v[124:127]
	v_mfma_f32_16x16x32_bf16 v[120:123], v[164:167], v[220:223], v[120:123]
	v_mfma_f32_16x16x32_bf16 v[116:119], v[156:159], v[228:231], v[116:119]
	v_mfma_f32_16x16x32_bf16 v[112:115], v[164:167], v[228:231], v[112:115]
	v_mfma_f32_16x16x32_bf16 v[92:95], v[156:159], v[236:239], v[92:95]
	v_mfma_f32_16x16x32_bf16 v[88:91], v[164:167], v[236:239], v[88:91]
	v_mfma_f32_16x16x32_bf16 v[84:87], v[156:159], v[244:247], v[84:87]
	v_mfma_f32_16x16x32_bf16 v[80:83], v[164:167], v[244:247], v[80:83]
	v_mfma_f32_16x16x32_bf16 v[124:127], v[160:163], v[224:227], v[124:127]
	v_mfma_f32_16x16x32_bf16 v[120:123], v[168:171], v[224:227], v[120:123]
	v_mfma_f32_16x16x32_bf16 v[116:119], v[160:163], v[232:235], v[116:119]
	v_mfma_f32_16x16x32_bf16 v[112:115], v[168:171], v[232:235], v[112:115]
	v_mfma_f32_16x16x32_bf16 v[92:95], v[160:163], v[240:243], v[92:95]
	v_mfma_f32_16x16x32_bf16 v[88:91], v[168:171], v[240:243], v[88:91]
	v_mfma_f32_16x16x32_bf16 v[84:87], v[160:163], v[248:251], v[84:87]
	v_mfma_f32_16x16x32_bf16 v[80:83], v[168:171], v[248:251], v[80:83]
	v_mfma_f32_16x16x32_bf16 v[108:111], v[172:175], v[220:223], v[108:111]
	v_mfma_f32_16x16x32_bf16 v[104:107], v[212:215], v[220:223], v[104:107]
	v_mfma_f32_16x16x32_bf16 v[100:103], v[172:175], v[228:231], v[100:103]
	v_mfma_f32_16x16x32_bf16 v[96:99], v[212:215], v[228:231], v[96:99]
	v_mfma_f32_16x16x32_bf16 v[76:79], v[172:175], v[236:239], v[76:79]
	v_mfma_f32_16x16x32_bf16 v[72:75], v[212:215], v[236:239], v[72:75]
	v_mfma_f32_16x16x32_bf16 v[68:71], v[172:175], v[244:247], v[68:71]
	v_mfma_f32_16x16x32_bf16 v[64:67], v[212:215], v[244:247], v[64:67]
	v_mfma_f32_16x16x32_bf16 v[108:111], v[176:179], v[224:227], v[108:111]
	v_mfma_f32_16x16x32_bf16 v[104:107], v[216:219], v[224:227], v[104:107]
	v_mfma_f32_16x16x32_bf16 v[100:103], v[176:179], v[232:235], v[100:103]
	v_mfma_f32_16x16x32_bf16 v[96:99], v[216:219], v[232:235], v[96:99]
	v_mfma_f32_16x16x32_bf16 v[76:79], v[176:179], v[240:243], v[76:79]
	v_mfma_f32_16x16x32_bf16 v[72:75], v[216:219], v[240:243], v[72:75]
	v_mfma_f32_16x16x32_bf16 v[68:71], v[176:179], v[248:251], v[68:71]
	v_mfma_f32_16x16x32_bf16 v[64:67], v[216:219], v[248:251], v[64:67]
	s_setprio 0
	s_barrier
	s_add_u32 s50, s48, 0x8000
	s_addc_u32 s51, s49, 0
	s_add_i32 s55, s55, s64
	v_lshl_add_u64 v[206:207], s[50:51], 0, v[130:131]
	s_mov_b32 m0, s55
	ds_read_b128 v[220:223], v199 offset:49152
	ds_read_b128 v[224:227], v199 offset:50176
	ds_read_b128 v[228:231], v199 offset:51200
	ds_read_b128 v[232:235], v199 offset:52224
	ds_read_b128 v[236:239], v199 offset:53248
	ds_read_b128 v[240:243], v199 offset:54272
	ds_read_b128 v[244:247], v199 offset:55296
	ds_read_b128 v[248:251], v199 offset:56320
	global_load_lds_dwordx4 v[206:207], off
	s_add_i32 m0, s55, 0x2000
	s_add_u32 s48, s48, 0xc000
	v_lshl_add_u64 v[206:207], s[50:51], 0, v[134:135]
	s_addc_u32 s49, s49, 0
	s_add_i32 s50, s56, s64
	global_load_lds_dwordx4 v[206:207], off
	v_lshl_add_u64 v[206:207], s[48:49], 0, v[130:131]
	s_mov_b32 m0, s50
	v_lshl_add_u64 v[204:205], v[204:205], 0, s[14:15]
	global_load_lds_dwordx4 v[206:207], off
	v_lshl_add_u64 v[206:207], s[48:49], 0, v[134:135]
	s_add_i32 m0, s50, 0x2000
	s_nop 0
	global_load_lds_dwordx4 v[206:207], off
	v_lshl_add_u64 v[206:207], v[252:253], 0, s[14:15]
	s_mov_b32 m0, s74
	s_nop 0
	global_load_lds_dwordx4 v[206:207], off
	s_mov_b32 m0, s75
	s_nop 0
	global_load_lds_dwordx4 v[204:205], off
	s_waitcnt vmcnt(8)
	s_waitcnt lgkmcnt(0)
	s_barrier
	s_setprio 1
	s_waitcnt lgkmcnt(0)
	v_mfma_f32_16x16x32_bf16 v[60:63], v[156:159], v[220:223], v[60:63]
	v_mfma_f32_16x16x32_bf16 v[56:59], v[164:167], v[220:223], v[56:59]
	v_mfma_f32_16x16x32_bf16 v[52:55], v[156:159], v[228:231], v[52:55]
	v_mfma_f32_16x16x32_bf16 v[48:51], v[164:167], v[228:231], v[48:51]
	v_mfma_f32_16x16x32_bf16 v[28:31], v[156:159], v[236:239], v[28:31]
	v_mfma_f32_16x16x32_bf16 v[24:27], v[164:167], v[236:239], v[24:27]
	v_mfma_f32_16x16x32_bf16 v[20:23], v[156:159], v[244:247], v[20:23]
	v_mfma_f32_16x16x32_bf16 v[12:15], v[164:167], v[244:247], v[12:15]
	v_mfma_f32_16x16x32_bf16 v[60:63], v[160:163], v[224:227], v[60:63]
	v_mfma_f32_16x16x32_bf16 v[56:59], v[168:171], v[224:227], v[56:59]
	v_mfma_f32_16x16x32_bf16 v[52:55], v[160:163], v[232:235], v[52:55]
	v_mfma_f32_16x16x32_bf16 v[48:51], v[168:171], v[232:235], v[48:51]
	v_mfma_f32_16x16x32_bf16 v[28:31], v[160:163], v[240:243], v[28:31]
	v_mfma_f32_16x16x32_bf16 v[24:27], v[168:171], v[240:243], v[24:27]
	v_mfma_f32_16x16x32_bf16 v[20:23], v[160:163], v[248:251], v[20:23]
	v_mfma_f32_16x16x32_bf16 v[12:15], v[168:171], v[248:251], v[12:15]
	v_mfma_f32_16x16x32_bf16 v[44:47], v[172:175], v[220:223], v[44:47]
	v_mfma_f32_16x16x32_bf16 v[40:43], v[212:215], v[220:223], v[40:43]
	v_mfma_f32_16x16x32_bf16 v[36:39], v[172:175], v[228:231], v[36:39]
	v_mfma_f32_16x16x32_bf16 v[32:35], v[212:215], v[228:231], v[32:35]
	v_mfma_f32_16x16x32_bf16 v[16:19], v[172:175], v[236:239], v[16:19]
	v_mfma_f32_16x16x32_bf16 v[8:11], v[212:215], v[236:239], v[8:11]
	v_mfma_f32_16x16x32_bf16 v[4:7], v[172:175], v[244:247], v[4:7]
	v_mfma_f32_16x16x32_bf16 v[0:3], v[212:215], v[244:247], v[0:3]
	v_mfma_f32_16x16x32_bf16 v[44:47], v[176:179], v[224:227], v[44:47]
	v_mfma_f32_16x16x32_bf16 v[40:43], v[216:219], v[224:227], v[40:43]
	v_mfma_f32_16x16x32_bf16 v[36:39], v[176:179], v[232:235], v[36:39]
	v_mfma_f32_16x16x32_bf16 v[32:35], v[216:219], v[232:235], v[32:35]
	v_mfma_f32_16x16x32_bf16 v[16:19], v[176:179], v[240:243], v[16:19]
	v_mfma_f32_16x16x32_bf16 v[8:11], v[216:219], v[240:243], v[8:11]
	v_mfma_f32_16x16x32_bf16 v[4:7], v[176:179], v[248:251], v[4:7]
	v_mfma_f32_16x16x32_bf16 v[0:3], v[216:219], v[248:251], v[0:3]
	s_setprio 0
	s_barrier
	s_add_i32 s54, s54, 2
	s_add_u32 s52, s52, 0x10000
	s_addc_u32 s53, s53, 0
	s_add_u32 s46, s46, 0x100
	s_addc_u32 s47, s47, 0
	s_cmp_gt_u32 s54, 13
	s_cbranch_scc0 .LBB0_1171
	s_and_b64 vcc, exec, s[18:19]
	s_cbranch_vccz .LBB0_1174
	s_barrier

.LBB0_1253:
	ds_read_b128 v[170:173], v167
	ds_read_b128 v[174:177], v167 offset:1024
	ds_read_b128 v[178:181], v167 offset:2048
	ds_read_b128 v[182:185], v167 offset:3072
	ds_read_b128 v[186:189], v168
	ds_read_b128 v[190:193], v168 offset:1024
	ds_read_b128 v[194:197], v168 offset:2048
	ds_read_b128 v[198:201], v168 offset:3072
	s_add_u32 s26, s24, 0xfffc0080
	s_addc_u32 s27, s25, -1
	s_cmp_eq_u32 s54, 12
	s_cselect_b32 s29, s11, s27
	s_cselect_b32 s28, s50, s26
	s_cselect_b32 s27, s13, s53
	s_cselect_b32 s26, s51, s52
	v_lshl_add_u64 v[164:165], s[24:25], 0, v[158:159]
	s_add_i32 m0, s21, 0xc000
	ds_read_b128 v[210:213], v169
	ds_read_b128 v[214:217], v169 offset:1024
	ds_read_b128 v[218:221], v169 offset:2048
	ds_read_b128 v[222:225], v169 offset:3072
	ds_read_b128 v[226:229], v169 offset:4096
	ds_read_b128 v[230:233], v169 offset:5120
	ds_read_b128 v[234:237], v169 offset:6144
	ds_read_b128 v[238:241], v169 offset:7168
	global_load_lds_dwordx4 v[164:165], off
	v_lshl_add_u64 v[164:165], s[24:25], 0, v[156:157]
	s_add_i32 m0, s21, 0xe000
	s_nop 0
	global_load_lds_dwordx4 v[164:165], off
	s_waitcnt vmcnt(8)
	s_waitcnt lgkmcnt(0)
	s_barrier
	s_setprio 1
	s_waitcnt lgkmcnt(0)
	v_mfma_f32_16x16x32_bf16 v[124:127], v[170:173], v[210:213], v[124:127]
	v_mfma_f32_16x16x32_bf16 v[116:119], v[178:181], v[210:213], v[116:119]
	v_mfma_f32_16x16x32_bf16 v[108:111], v[170:173], v[218:221], v[108:111]
	v_mfma_f32_16x16x32_bf16 v[100:103], v[178:181], v[218:221], v[100:103]
	v_mfma_f32_16x16x32_bf16 v[92:95], v[170:173], v[226:229], v[92:95]
	v_mfma_f32_16x16x32_bf16 v[84:87], v[178:181], v[226:229], v[84:87]
	v_mfma_f32_16x16x32_bf16 v[76:79], v[170:173], v[234:237], v[76:79]
	v_mfma_f32_16x16x32_bf16 v[68:71], v[178:181], v[234:237], v[68:71]
	v_mfma_f32_16x16x32_bf16 v[124:127], v[174:177], v[214:217], v[124:127]
	v_mfma_f32_16x16x32_bf16 v[116:119], v[182:185], v[214:217], v[116:119]
	v_mfma_f32_16x16x32_bf16 v[108:111], v[174:177], v[222:225], v[108:111]
	v_mfma_f32_16x16x32_bf16 v[100:103], v[182:185], v[222:225], v[100:103]
	v_mfma_f32_16x16x32_bf16 v[92:95], v[174:177], v[230:233], v[92:95]
	v_mfma_f32_16x16x32_bf16 v[84:87], v[182:185], v[230:233], v[84:87]
	v_mfma_f32_16x16x32_bf16 v[76:79], v[174:177], v[238:241], v[76:79]
	v_mfma_f32_16x16x32_bf16 v[68:71], v[182:185], v[238:241], v[68:71]
	v_mfma_f32_16x16x32_bf16 v[120:123], v[186:189], v[210:213], v[120:123]
	v_mfma_f32_16x16x32_bf16 v[112:115], v[194:197], v[210:213], v[112:115]
	v_mfma_f32_16x16x32_bf16 v[104:107], v[186:189], v[218:221], v[104:107]
	v_mfma_f32_16x16x32_bf16 v[96:99], v[194:197], v[218:221], v[96:99]
	v_mfma_f32_16x16x32_bf16 v[88:91], v[186:189], v[226:229], v[88:91]
	v_mfma_f32_16x16x32_bf16 v[80:83], v[194:197], v[226:229], v[80:83]
	v_mfma_f32_16x16x32_bf16 v[72:75], v[186:189], v[234:237], v[72:75]
	v_mfma_f32_16x16x32_bf16 v[64:67], v[194:197], v[234:237], v[64:67]
	v_mfma_f32_16x16x32_bf16 v[120:123], v[190:193], v[214:217], v[120:123]
	v_mfma_f32_16x16x32_bf16 v[112:115], v[198:201], v[214:217], v[112:115]
	v_mfma_f32_16x16x32_bf16 v[104:107], v[190:193], v[222:225], v[104:107]
	v_mfma_f32_16x16x32_bf16 v[96:99], v[198:201], v[222:225], v[96:99]
	v_mfma_f32_16x16x32_bf16 v[88:91], v[190:193], v[230:233], v[88:91]
	v_mfma_f32_16x16x32_bf16 v[80:83], v[198:201], v[230:233], v[80:83]
	v_mfma_f32_16x16x32_bf16 v[72:75], v[190:193], v[238:241], v[72:75]
	v_mfma_f32_16x16x32_bf16 v[64:67], v[198:201], v[238:241], v[64:67]
	s_setprio 0
	s_barrier
	s_add_i32 s55, s48, s35
	v_lshl_add_u64 v[164:165], s[26:27], 0, v[134:135]
	s_mov_b32 m0, s55
	ds_read_b128 v[210:213], v169 offset:16384
	ds_read_b128 v[214:217], v169 offset:17408
	ds_read_b128 v[218:221], v169 offset:18432
	ds_read_b128 v[222:225], v169 offset:19456
	ds_read_b128 v[226:229], v169 offset:20480
	ds_read_b128 v[230:233], v169 offset:21504
	ds_read_b128 v[234:237], v169 offset:22528
	ds_read_b128 v[238:241], v169 offset:23552
	global_load_lds_dwordx4 v[164:165], off
	s_add_i32 m0, s55, 0x2000
	s_add_u32 s56, s26, 0x4000
	v_lshl_add_u64 v[164:165], s[26:27], 0, v[130:131]
	s_addc_u32 s57, s27, 0
	s_add_i32 s55, s49, s35
	global_load_lds_dwordx4 v[164:165], off
	v_lshl_add_u64 v[164:165], s[56:57], 0, v[134:135]
	s_mov_b32 m0, s55
	v_lshl_add_u64 v[204:205], s[28:29], 0, v[132:133]
	global_load_lds_dwordx4 v[164:165], off
	v_lshl_add_u64 v[164:165], s[56:57], 0, v[130:131]
	s_add_i32 m0, s55, 0x2000
	s_nop 0
	global_load_lds_dwordx4 v[164:165], off
	v_lshl_add_u64 v[164:165], s[28:29], 0, v[136:137]
	s_mov_b32 m0, s21
	s_nop 0
	global_load_lds_dwordx4 v[164:165], off
	s_mov_b32 m0, s23
	s_nop 0
	global_load_lds_dwordx4 v[204:205], off
	s_waitcnt vmcnt(8)
	s_waitcnt lgkmcnt(0)
	s_barrier
	s_setprio 1
	s_waitcnt lgkmcnt(0)
	v_mfma_f32_16x16x32_bf16 v[60:63], v[170:173], v[210:213], v[60:63]
	v_mfma_f32_16x16x32_bf16 v[52:55], v[178:181], v[210:213], v[52:55]
	v_mfma_f32_16x16x32_bf16 v[44:47], v[170:173], v[218:221], v[44:47]
	v_mfma_f32_16x16x32_bf16 v[36:39], v[178:181], v[218:221], v[36:39]
	v_mfma_f32_16x16x32_bf16 v[28:31], v[170:173], v[226:229], v[28:31]
	v_mfma_f32_16x16x32_bf16 v[20:23], v[178:181], v[226:229], v[20:23]
	v_mfma_f32_16x16x32_bf16 v[12:15], v[170:173], v[234:237], v[12:15]
	v_mfma_f32_16x16x32_bf16 v[4:7], v[178:181], v[234:237], v[4:7]
	v_mfma_f32_16x16x32_bf16 v[60:63], v[174:177], v[214:217], v[60:63]
	v_mfma_f32_16x16x32_bf16 v[52:55], v[182:185], v[214:217], v[52:55]
	v_mfma_f32_16x16x32_bf16 v[44:47], v[174:177], v[222:225], v[44:47]
	v_mfma_f32_16x16x32_bf16 v[36:39], v[182:185], v[222:225], v[36:39]
	v_mfma_f32_16x16x32_bf16 v[28:31], v[174:177], v[230:233], v[28:31]
	v_mfma_f32_16x16x32_bf16 v[20:23], v[182:185], v[230:233], v[20:23]
	v_mfma_f32_16x16x32_bf16 v[12:15], v[174:177], v[238:241], v[12:15]
	v_mfma_f32_16x16x32_bf16 v[4:7], v[182:185], v[238:241], v[4:7]
	v_mfma_f32_16x16x32_bf16 v[56:59], v[186:189], v[210:213], v[56:59]
	v_mfma_f32_16x16x32_bf16 v[48:51], v[194:197], v[210:213], v[48:51]
	v_mfma_f32_16x16x32_bf16 v[40:43], v[186:189], v[218:221], v[40:43]
	v_mfma_f32_16x16x32_bf16 v[32:35], v[194:197], v[218:221], v[32:35]
	v_mfma_f32_16x16x32_bf16 v[24:27], v[186:189], v[226:229], v[24:27]
	v_mfma_f32_16x16x32_bf16 v[16:19], v[194:197], v[226:229], v[16:19]
	v_mfma_f32_16x16x32_bf16 v[8:11], v[186:189], v[234:237], v[8:11]
	v_mfma_f32_16x16x32_bf16 v[0:3], v[194:197], v[234:237], v[0:3]
	v_mfma_f32_16x16x32_bf16 v[56:59], v[190:193], v[214:217], v[56:59]
	v_mfma_f32_16x16x32_bf16 v[48:51], v[198:201], v[214:217], v[48:51]
	v_mfma_f32_16x16x32_bf16 v[40:43], v[190:193], v[222:225], v[40:43]
	v_mfma_f32_16x16x32_bf16 v[32:35], v[198:201], v[222:225], v[32:35]
	v_mfma_f32_16x16x32_bf16 v[24:27], v[190:193], v[230:233], v[24:27]
	v_mfma_f32_16x16x32_bf16 v[16:19], v[198:201], v[230:233], v[16:19]
	v_mfma_f32_16x16x32_bf16 v[8:11], v[190:193], v[238:241], v[8:11]
	v_mfma_f32_16x16x32_bf16 v[0:3], v[198:201], v[238:241], v[0:3]
	s_setprio 0
	s_barrier
	s_add_i32 s55, 0, 0x18000
	s_add_i32 s56, 0, 0x1c000
	v_add_u32_e32 v182, s55, v129
	v_add_u32_e32 v198, s56, v129
	ds_read_b128 v[170:173], v182
	ds_read_b128 v[174:177], v182 offset:1024
	ds_read_b128 v[178:181], v182 offset:2048
	ds_read_b128 v[182:185], v182 offset:3072
	ds_read_b128 v[186:189], v198
	ds_read_b128 v[190:193], v198 offset:1024
	ds_read_b128 v[194:197], v198 offset:2048
	ds_read_b128 v[198:201], v198 offset:3072
	s_add_u32 s28, s28, 0x40000
	s_addc_u32 s29, s29, 0
	s_mov_b32 m0, s39
	v_lshl_add_u64 v[206:207], s[28:29], 0, v[136:137]
	ds_read_b128 v[210:213], v169 offset:32768
	ds_read_b128 v[214:217], v169 offset:33792
	ds_read_b128 v[218:221], v169 offset:34816
	ds_read_b128 v[222:225], v169 offset:35840
	ds_read_b128 v[226:229], v169 offset:36864
	ds_read_b128 v[230:233], v169 offset:37888
	ds_read_b128 v[234:237], v169 offset:38912
	ds_read_b128 v[238:241], v169 offset:39936
	global_load_lds_dwordx4 v[206:207], off
	v_lshl_add_u64 v[206:207], s[28:29], 0, v[132:133]
	s_mov_b32 m0, s40
	s_nop 0
	global_load_lds_dwordx4 v[206:207], off
	s_waitcnt vmcnt(8)
	s_waitcnt lgkmcnt(0)
	s_barrier
	s_setprio 1
	s_waitcnt lgkmcnt(0)
	v_mfma_f32_16x16x32_bf16 v[124:127], v[170:173], v[210:213], v[124:127]
	v_mfma_f32_16x16x32_bf16 v[116:119], v[178:181], v[210:213], v[116:119]
	v_mfma_f32_16x16x32_bf16 v[108:111], v[170:173], v[218:221], v[108:111]
	v_mfma_f32_16x16x32_bf16 v[100:103], v[178:181], v[218:221], v[100:103]
	v_mfma_f32_16x16x32_bf16 v[92:95], v[170:173], v[226:229], v[92:95]
	v_mfma_f32_16x16x32_bf16 v[84:87], v[178:181], v[226:229], v[84:87]
	v_mfma_f32_16x16x32_bf16 v[76:79], v[170:173], v[234:237], v[76:79]
	v_mfma_f32_16x16x32_bf16 v[68:71], v[178:181], v[234:237], v[68:71]
	v_mfma_f32_16x16x32_bf16 v[124:127], v[174:177], v[214:217], v[124:127]
	v_mfma_f32_16x16x32_bf16 v[116:119], v[182:185], v[214:217], v[116:119]
	v_mfma_f32_16x16x32_bf16 v[108:111], v[174:177], v[222:225], v[108:111]
	v_mfma_f32_16x16x32_bf16 v[100:103], v[182:185], v[222:225], v[100:103]
	v_mfma_f32_16x16x32_bf16 v[92:95], v[174:177], v[230:233], v[92:95]
	v_mfma_f32_16x16x32_bf16 v[84:87], v[182:185], v[230:233], v[84:87]
	v_mfma_f32_16x16x32_bf16 v[76:79], v[174:177], v[238:241], v[76:79]
	v_mfma_f32_16x16x32_bf16 v[68:71], v[182:185], v[238:241], v[68:71]
	v_mfma_f32_16x16x32_bf16 v[120:123], v[186:189], v[210:213], v[120:123]
	v_mfma_f32_16x16x32_bf16 v[112:115], v[194:197], v[210:213], v[112:115]
	v_mfma_f32_16x16x32_bf16 v[104:107], v[186:189], v[218:221], v[104:107]
	v_mfma_f32_16x16x32_bf16 v[96:99], v[194:197], v[218:221], v[96:99]
	v_mfma_f32_16x16x32_bf16 v[88:91], v[186:189], v[226:229], v[88:91]
	v_mfma_f32_16x16x32_bf16 v[80:83], v[194:197], v[226:229], v[80:83]
	v_mfma_f32_16x16x32_bf16 v[72:75], v[186:189], v[234:237], v[72:75]
	v_mfma_f32_16x16x32_bf16 v[64:67], v[194:197], v[234:237], v[64:67]
	v_mfma_f32_16x16x32_bf16 v[120:123], v[190:193], v[214:217], v[120:123]
	v_mfma_f32_16x16x32_bf16 v[112:115], v[198:201], v[214:217], v[112:115]
	v_mfma_f32_16x16x32_bf16 v[104:107], v[190:193], v[222:225], v[104:107]
	v_mfma_f32_16x16x32_bf16 v[96:99], v[198:201], v[222:225], v[96:99]
	v_mfma_f32_16x16x32_bf16 v[88:91], v[190:193], v[230:233], v[88:91]
	v_mfma_f32_16x16x32_bf16 v[80:83], v[198:201], v[230:233], v[80:83]
	v_mfma_f32_16x16x32_bf16 v[72:75], v[190:193], v[238:241], v[72:75]
	v_mfma_f32_16x16x32_bf16 v[64:67], v[198:201], v[238:241], v[64:67]
	s_setprio 0
	s_barrier
	s_add_u32 s28, s26, 0x8000
	s_addc_u32 s29, s27, 0
	s_add_i32 s55, s55, s35
	v_lshl_add_u64 v[206:207], s[28:29], 0, v[134:135]
	s_mov_b32 m0, s55
	ds_read_b128 v[210:213], v169 offset:49152
	ds_read_b128 v[214:217], v169 offset:50176
	ds_read_b128 v[218:221], v169 offset:51200
	ds_read_b128 v[222:225], v169 offset:52224
	ds_read_b128 v[226:229], v169 offset:53248
	ds_read_b128 v[230:233], v169 offset:54272
	ds_read_b128 v[234:237], v169 offset:55296
	ds_read_b128 v[238:241], v169 offset:56320
	global_load_lds_dwordx4 v[206:207], off
	s_add_i32 m0, s55, 0x2000
	s_add_u32 s26, s26, 0xc000
	v_lshl_add_u64 v[206:207], s[28:29], 0, v[130:131]
	s_addc_u32 s27, s27, 0
	s_add_i32 s28, s56, s35
	global_load_lds_dwordx4 v[206:207], off
	v_lshl_add_u64 v[206:207], s[26:27], 0, v[134:135]
	s_mov_b32 m0, s28
	v_lshl_add_u64 v[164:165], v[164:165], 0, s[6:7]
	global_load_lds_dwordx4 v[206:207], off
	v_lshl_add_u64 v[206:207], s[26:27], 0, v[130:131]
	s_add_i32 m0, s28, 0x2000
	s_nop 0
	global_load_lds_dwordx4 v[206:207], off
	s_mov_b32 m0, s45
	s_nop 0
	global_load_lds_dwordx4 v[164:165], off
	v_lshl_add_u64 v[164:165], v[204:205], 0, s[6:7]
	s_mov_b32 m0, s46
	s_nop 0
	global_load_lds_dwordx4 v[164:165], off
	s_waitcnt vmcnt(8)
	s_waitcnt lgkmcnt(0)
	s_barrier
	s_setprio 1
	s_waitcnt lgkmcnt(0)
	v_mfma_f32_16x16x32_bf16 v[60:63], v[170:173], v[210:213], v[60:63]
	v_mfma_f32_16x16x32_bf16 v[52:55], v[178:181], v[210:213], v[52:55]
	v_mfma_f32_16x16x32_bf16 v[44:47], v[170:173], v[218:221], v[44:47]
	v_mfma_f32_16x16x32_bf16 v[36:39], v[178:181], v[218:221], v[36:39]
	v_mfma_f32_16x16x32_bf16 v[28:31], v[170:173], v[226:229], v[28:31]
	v_mfma_f32_16x16x32_bf16 v[20:23], v[178:181], v[226:229], v[20:23]
	v_mfma_f32_16x16x32_bf16 v[12:15], v[170:173], v[234:237], v[12:15]
	v_mfma_f32_16x16x32_bf16 v[4:7], v[178:181], v[234:237], v[4:7]
	v_mfma_f32_16x16x32_bf16 v[60:63], v[174:177], v[214:217], v[60:63]
	v_mfma_f32_16x16x32_bf16 v[52:55], v[182:185], v[214:217], v[52:55]
	v_mfma_f32_16x16x32_bf16 v[44:47], v[174:177], v[222:225], v[44:47]
	v_mfma_f32_16x16x32_bf16 v[36:39], v[182:185], v[222:225], v[36:39]
	v_mfma_f32_16x16x32_bf16 v[28:31], v[174:177], v[230:233], v[28:31]
	v_mfma_f32_16x16x32_bf16 v[20:23], v[182:185], v[230:233], v[20:23]
	v_mfma_f32_16x16x32_bf16 v[12:15], v[174:177], v[238:241], v[12:15]
	v_mfma_f32_16x16x32_bf16 v[4:7], v[182:185], v[238:241], v[4:7]
	v_mfma_f32_16x16x32_bf16 v[56:59], v[186:189], v[210:213], v[56:59]
	v_mfma_f32_16x16x32_bf16 v[48:51], v[194:197], v[210:213], v[48:51]
	v_mfma_f32_16x16x32_bf16 v[40:43], v[186:189], v[218:221], v[40:43]
	v_mfma_f32_16x16x32_bf16 v[32:35], v[194:197], v[218:221], v[32:35]
	v_mfma_f32_16x16x32_bf16 v[24:27], v[186:189], v[226:229], v[24:27]
	v_mfma_f32_16x16x32_bf16 v[16:19], v[194:197], v[226:229], v[16:19]
	v_mfma_f32_16x16x32_bf16 v[8:11], v[186:189], v[234:237], v[8:11]
	v_mfma_f32_16x16x32_bf16 v[0:3], v[194:197], v[234:237], v[0:3]
	v_mfma_f32_16x16x32_bf16 v[56:59], v[190:193], v[214:217], v[56:59]
	v_mfma_f32_16x16x32_bf16 v[48:51], v[198:201], v[214:217], v[48:51]
	v_mfma_f32_16x16x32_bf16 v[40:43], v[190:193], v[222:225], v[40:43]
	v_mfma_f32_16x16x32_bf16 v[32:35], v[198:201], v[222:225], v[32:35]
	v_mfma_f32_16x16x32_bf16 v[24:27], v[190:193], v[230:233], v[24:27]
	v_mfma_f32_16x16x32_bf16 v[16:19], v[198:201], v[230:233], v[16:19]
	v_mfma_f32_16x16x32_bf16 v[8:11], v[190:193], v[238:241], v[8:11]
	v_mfma_f32_16x16x32_bf16 v[0:3], v[198:201], v[238:241], v[0:3]
	s_setprio 0
	s_barrier
	s_add_i32 s54, s54, 2
	s_add_u32 s52, s52, 0x10000
	s_addc_u32 s53, s53, 0
	s_add_u32 s24, s24, 0x100
	s_addc_u32 s25, s25, 0
	s_cmp_gt_u32 s54, 13
	s_cbranch_scc0 .LBB0_1253
	s_and_b64 vcc, exec, s[8:9]
	s_cbranch_vccz .LBB0_1256
	s_barrier

.LBB0_1481:
	v_add_u32_e32 v168, s61, v182
	v_add_u32_e32 v204, s62, v182
	ds_read_b128 v[156:159], v168
	ds_read_b128 v[160:163], v168 offset:1024
	ds_read_b128 v[164:167], v168 offset:2048
	ds_read_b128 v[168:171], v168 offset:3072
	ds_read_b128 v[172:175], v204
	ds_read_b128 v[176:179], v204 offset:1024
	ds_read_b128 v[212:215], v204 offset:2048
	ds_read_b128 v[216:219], v204 offset:3072
	s_add_u32 s38, s36, 0x4000
	s_addc_u32 s39, s37, 0
	s_cmp_eq_u32 s70, 40
	s_cselect_b32 s42, s0, s38
	s_cselect_b32 s43, s1, s39
	s_cselect_b32 s40, s34, s68
	s_cselect_b32 s41, s35, s69
	s_add_u32 s38, s42, 0x8000
	s_addc_u32 s39, s43, 0
	v_lshl_add_u64 v[204:205], s[36:37], 0, v[150:151]
	s_add_i32 m0, s48, 0xc000
	ds_read_b128 v[220:223], v199
	ds_read_b128 v[224:227], v199 offset:1024
	ds_read_b128 v[228:231], v199 offset:2048
	ds_read_b128 v[232:235], v199 offset:3072
	ds_read_b128 v[236:239], v199 offset:4096
	ds_read_b128 v[240:243], v199 offset:5120
	ds_read_b128 v[244:247], v199 offset:6144
	ds_read_b128 v[248:251], v199 offset:7168
	global_load_lds_dwordx4 v[204:205], off
	v_lshl_add_u64 v[204:205], s[36:37], 0, v[148:149]
	s_add_i32 m0, s48, 0xe000
	s_nop 0
	global_load_lds_dwordx4 v[204:205], off
	s_waitcnt vmcnt(8)
	s_waitcnt lgkmcnt(0)
	s_barrier
	s_setprio 1
	s_waitcnt lgkmcnt(0)
	v_mfma_f32_16x16x32_bf16 v[124:127], v[156:159], v[220:223], v[124:127]
	v_mfma_f32_16x16x32_bf16 v[120:123], v[164:167], v[220:223], v[120:123]
	v_mfma_f32_16x16x32_bf16 v[116:119], v[156:159], v[228:231], v[116:119]
	v_mfma_f32_16x16x32_bf16 v[112:115], v[164:167], v[228:231], v[112:115]
	v_mfma_f32_16x16x32_bf16 v[92:95], v[156:159], v[236:239], v[92:95]
	v_mfma_f32_16x16x32_bf16 v[88:91], v[164:167], v[236:239], v[88:91]
	v_mfma_f32_16x16x32_bf16 v[84:87], v[156:159], v[244:247], v[84:87]
	v_mfma_f32_16x16x32_bf16 v[80:83], v[164:167], v[244:247], v[80:83]
	v_mfma_f32_16x16x32_bf16 v[124:127], v[160:163], v[224:227], v[124:127]
	v_mfma_f32_16x16x32_bf16 v[120:123], v[168:171], v[224:227], v[120:123]
	v_mfma_f32_16x16x32_bf16 v[116:119], v[160:163], v[232:235], v[116:119]
	v_mfma_f32_16x16x32_bf16 v[112:115], v[168:171], v[232:235], v[112:115]
	v_mfma_f32_16x16x32_bf16 v[92:95], v[160:163], v[240:243], v[92:95]
	v_mfma_f32_16x16x32_bf16 v[88:91], v[168:171], v[240:243], v[88:91]
	v_mfma_f32_16x16x32_bf16 v[84:87], v[160:163], v[248:251], v[84:87]
	v_mfma_f32_16x16x32_bf16 v[80:83], v[168:171], v[248:251], v[80:83]
	v_mfma_f32_16x16x32_bf16 v[108:111], v[172:175], v[220:223], v[108:111]
	v_mfma_f32_16x16x32_bf16 v[104:107], v[212:215], v[220:223], v[104:107]
	v_mfma_f32_16x16x32_bf16 v[100:103], v[172:175], v[228:231], v[100:103]
	v_mfma_f32_16x16x32_bf16 v[96:99], v[212:215], v[228:231], v[96:99]
	v_mfma_f32_16x16x32_bf16 v[76:79], v[172:175], v[236:239], v[76:79]
	v_mfma_f32_16x16x32_bf16 v[72:75], v[212:215], v[236:239], v[72:75]
	v_mfma_f32_16x16x32_bf16 v[68:71], v[172:175], v[244:247], v[68:71]
	v_mfma_f32_16x16x32_bf16 v[64:67], v[212:215], v[244:247], v[64:67]
	v_mfma_f32_16x16x32_bf16 v[108:111], v[176:179], v[224:227], v[108:111]
	v_mfma_f32_16x16x32_bf16 v[104:107], v[216:219], v[224:227], v[104:107]
	v_mfma_f32_16x16x32_bf16 v[100:103], v[176:179], v[232:235], v[100:103]
	v_mfma_f32_16x16x32_bf16 v[96:99], v[216:219], v[232:235], v[96:99]
	v_mfma_f32_16x16x32_bf16 v[76:79], v[176:179], v[240:243], v[76:79]
	v_mfma_f32_16x16x32_bf16 v[72:75], v[216:219], v[240:243], v[72:75]
	v_mfma_f32_16x16x32_bf16 v[68:71], v[176:179], v[248:251], v[68:71]
	v_mfma_f32_16x16x32_bf16 v[64:67], v[216:219], v[248:251], v[64:67]
	s_setprio 0
	s_barrier
	s_add_i32 s71, s61, s47
	v_lshl_add_u64 v[204:205], s[40:41], 0, v[128:129]
	s_mov_b32 m0, s71
	ds_read_b128 v[220:223], v199 offset:16384
	ds_read_b128 v[224:227], v199 offset:17408
	ds_read_b128 v[228:231], v199 offset:18432
	ds_read_b128 v[232:235], v199 offset:19456
	ds_read_b128 v[236:239], v199 offset:20480
	ds_read_b128 v[240:243], v199 offset:21504
	ds_read_b128 v[244:247], v199 offset:22528
	ds_read_b128 v[248:251], v199 offset:23552
	global_load_lds_dwordx4 v[204:205], off
	s_add_i32 m0, s71, 0x2000
	s_add_u32 s72, s40, 0x4000
	v_lshl_add_u64 v[204:205], s[40:41], 0, v[130:131]
	s_addc_u32 s73, s41, 0
	s_add_i32 s71, s62, s47
	global_load_lds_dwordx4 v[204:205], off
	v_lshl_add_u64 v[204:205], s[72:73], 0, v[128:129]
	s_mov_b32 m0, s71
	s_nop 0
	global_load_lds_dwordx4 v[204:205], off
	v_lshl_add_u64 v[204:205], s[72:73], 0, v[130:131]
	s_add_i32 m0, s71, 0x2000
	s_nop 0
	global_load_lds_dwordx4 v[204:205], off
	v_lshl_add_u64 v[204:205], s[42:43], 0, v[128:129]
	s_mov_b32 m0, s48
	s_nop 0
	global_load_lds_dwordx4 v[204:205], off
	v_lshl_add_u64 v[204:205], s[42:43], 0, v[130:131]
	s_mov_b32 m0, s49
	s_nop 0
	global_load_lds_dwordx4 v[204:205], off
	s_waitcnt vmcnt(8)
	s_waitcnt lgkmcnt(0)
	s_barrier
	s_setprio 1
	s_waitcnt lgkmcnt(0)
	v_mfma_f32_16x16x32_bf16 v[60:63], v[156:159], v[220:223], v[60:63]
	v_mfma_f32_16x16x32_bf16 v[56:59], v[164:167], v[220:223], v[56:59]
	v_mfma_f32_16x16x32_bf16 v[52:55], v[156:159], v[228:231], v[52:55]
	v_mfma_f32_16x16x32_bf16 v[48:51], v[164:167], v[228:231], v[48:51]
	v_mfma_f32_16x16x32_bf16 v[28:31], v[156:159], v[236:239], v[28:31]
	v_mfma_f32_16x16x32_bf16 v[24:27], v[164:167], v[236:239], v[24:27]
	v_mfma_f32_16x16x32_bf16 v[20:23], v[156:159], v[244:247], v[20:23]
	v_mfma_f32_16x16x32_bf16 v[12:15], v[164:167], v[244:247], v[12:15]
	v_mfma_f32_16x16x32_bf16 v[60:63], v[160:163], v[224:227], v[60:63]
	v_mfma_f32_16x16x32_bf16 v[56:59], v[168:171], v[224:227], v[56:59]
	v_mfma_f32_16x16x32_bf16 v[52:55], v[160:163], v[232:235], v[52:55]
	v_mfma_f32_16x16x32_bf16 v[48:51], v[168:171], v[232:235], v[48:51]
	v_mfma_f32_16x16x32_bf16 v[28:31], v[160:163], v[240:243], v[28:31]
	v_mfma_f32_16x16x32_bf16 v[24:27], v[168:171], v[240:243], v[24:27]
	v_mfma_f32_16x16x32_bf16 v[20:23], v[160:163], v[248:251], v[20:23]
	v_mfma_f32_16x16x32_bf16 v[12:15], v[168:171], v[248:251], v[12:15]
	v_mfma_f32_16x16x32_bf16 v[44:47], v[172:175], v[220:223], v[44:47]
	v_mfma_f32_16x16x32_bf16 v[40:43], v[212:215], v[220:223], v[40:43]
	v_mfma_f32_16x16x32_bf16 v[36:39], v[172:175], v[228:231], v[36:39]
	v_mfma_f32_16x16x32_bf16 v[32:35], v[212:215], v[228:231], v[32:35]
	v_mfma_f32_16x16x32_bf16 v[16:19], v[172:175], v[236:239], v[16:19]
	v_mfma_f32_16x16x32_bf16 v[8:11], v[212:215], v[236:239], v[8:11]
	v_mfma_f32_16x16x32_bf16 v[4:7], v[172:175], v[244:247], v[4:7]
	v_mfma_f32_16x16x32_bf16 v[0:3], v[212:215], v[244:247], v[0:3]
	v_mfma_f32_16x16x32_bf16 v[44:47], v[176:179], v[224:227], v[44:47]
	v_mfma_f32_16x16x32_bf16 v[40:43], v[216:219], v[224:227], v[40:43]
	v_mfma_f32_16x16x32_bf16 v[36:39], v[176:179], v[232:235], v[36:39]
	v_mfma_f32_16x16x32_bf16 v[32:35], v[216:219], v[232:235], v[32:35]
	v_mfma_f32_16x16x32_bf16 v[16:19], v[176:179], v[240:243], v[16:19]
	v_mfma_f32_16x16x32_bf16 v[8:11], v[216:219], v[240:243], v[8:11]
	v_mfma_f32_16x16x32_bf16 v[4:7], v[176:179], v[248:251], v[4:7]
	v_mfma_f32_16x16x32_bf16 v[0:3], v[216:219], v[248:251], v[0:3]
	s_setprio 0
	s_barrier
	s_add_i32 s71, 0, 0x18000
	s_add_i32 s72, 0, 0x1c000
	v_add_u32_e32 v168, s71, v182
	v_add_u32_e32 v204, s72, v182
	ds_read_b128 v[156:159], v168
	ds_read_b128 v[160:163], v168 offset:1024
	ds_read_b128 v[164:167], v168 offset:2048
	ds_read_b128 v[168:171], v168 offset:3072
	ds_read_b128 v[172:175], v204
	ds_read_b128 v[176:179], v204 offset:1024
	ds_read_b128 v[212:215], v204 offset:2048
	ds_read_b128 v[216:219], v204 offset:3072
	s_add_u32 s42, s42, 0x4000
	s_addc_u32 s43, s43, 0
	s_mov_b32 m0, s50
	v_lshl_add_u64 v[204:205], s[42:43], 0, v[128:129]
	ds_read_b128 v[220:223], v199 offset:32768
	ds_read_b128 v[224:227], v199 offset:33792
	ds_read_b128 v[228:231], v199 offset:34816
	ds_read_b128 v[232:235], v199 offset:35840
	ds_read_b128 v[236:239], v199 offset:36864
	ds_read_b128 v[240:243], v199 offset:37888
	ds_read_b128 v[244:247], v199 offset:38912
	ds_read_b128 v[248:251], v199 offset:39936
	global_load_lds_dwordx4 v[204:205], off
	v_lshl_add_u64 v[204:205], s[42:43], 0, v[130:131]
	s_mov_b32 m0, s51
	s_nop 0
	global_load_lds_dwordx4 v[204:205], off
	s_waitcnt vmcnt(8)
	s_waitcnt lgkmcnt(0)
	s_barrier
	s_setprio 1
	s_waitcnt lgkmcnt(0)
	v_mfma_f32_16x16x32_bf16 v[124:127], v[156:159], v[220:223], v[124:127]
	v_mfma_f32_16x16x32_bf16 v[120:123], v[164:167], v[220:223], v[120:123]
	v_mfma_f32_16x16x32_bf16 v[116:119], v[156:159], v[228:231], v[116:119]
	v_mfma_f32_16x16x32_bf16 v[112:115], v[164:167], v[228:231], v[112:115]
	v_mfma_f32_16x16x32_bf16 v[92:95], v[156:159], v[236:239], v[92:95]
	v_mfma_f32_16x16x32_bf16 v[88:91], v[164:167], v[236:239], v[88:91]
	v_mfma_f32_16x16x32_bf16 v[84:87], v[156:159], v[244:247], v[84:87]
	v_mfma_f32_16x16x32_bf16 v[80:83], v[164:167], v[244:247], v[80:83]
	v_mfma_f32_16x16x32_bf16 v[124:127], v[160:163], v[224:227], v[124:127]
	v_mfma_f32_16x16x32_bf16 v[120:123], v[168:171], v[224:227], v[120:123]
	v_mfma_f32_16x16x32_bf16 v[116:119], v[160:163], v[232:235], v[116:119]
	v_mfma_f32_16x16x32_bf16 v[112:115], v[168:171], v[232:235], v[112:115]
	v_mfma_f32_16x16x32_bf16 v[92:95], v[160:163], v[240:243], v[92:95]
	v_mfma_f32_16x16x32_bf16 v[88:91], v[168:171], v[240:243], v[88:91]
	v_mfma_f32_16x16x32_bf16 v[84:87], v[160:163], v[248:251], v[84:87]
	v_mfma_f32_16x16x32_bf16 v[80:83], v[168:171], v[248:251], v[80:83]
	v_mfma_f32_16x16x32_bf16 v[108:111], v[172:175], v[220:223], v[108:111]
	v_mfma_f32_16x16x32_bf16 v[104:107], v[212:215], v[220:223], v[104:107]
	v_mfma_f32_16x16x32_bf16 v[100:103], v[172:175], v[228:231], v[100:103]
	v_mfma_f32_16x16x32_bf16 v[96:99], v[212:215], v[228:231], v[96:99]
	v_mfma_f32_16x16x32_bf16 v[76:79], v[172:175], v[236:239], v[76:79]
	v_mfma_f32_16x16x32_bf16 v[72:75], v[212:215], v[236:239], v[72:75]
	v_mfma_f32_16x16x32_bf16 v[68:71], v[172:175], v[244:247], v[68:71]
	v_mfma_f32_16x16x32_bf16 v[64:67], v[212:215], v[244:247], v[64:67]
	v_mfma_f32_16x16x32_bf16 v[108:111], v[176:179], v[224:227], v[108:111]
	v_mfma_f32_16x16x32_bf16 v[104:107], v[216:219], v[224:227], v[104:107]
	v_mfma_f32_16x16x32_bf16 v[100:103], v[176:179], v[232:235], v[100:103]
	v_mfma_f32_16x16x32_bf16 v[96:99], v[216:219], v[232:235], v[96:99]
	v_mfma_f32_16x16x32_bf16 v[76:79], v[176:179], v[240:243], v[76:79]
	v_mfma_f32_16x16x32_bf16 v[72:75], v[216:219], v[240:243], v[72:75]
	v_mfma_f32_16x16x32_bf16 v[68:71], v[176:179], v[248:251], v[68:71]
	v_mfma_f32_16x16x32_bf16 v[64:67], v[216:219], v[248:251], v[64:67]
	s_setprio 0
	s_barrier
	s_add_u32 s42, s40, 0x8000
	s_addc_u32 s43, s41, 0
	s_add_i32 s71, s71, s47
	v_lshl_add_u64 v[204:205], s[42:43], 0, v[128:129]
	s_mov_b32 m0, s71
	ds_read_b128 v[220:223], v199 offset:49152
	ds_read_b128 v[224:227], v199 offset:50176
	ds_read_b128 v[228:231], v199 offset:51200
	ds_read_b128 v[232:235], v199 offset:52224
	ds_read_b128 v[236:239], v199 offset:53248
	ds_read_b128 v[240:243], v199 offset:54272
	ds_read_b128 v[244:247], v199 offset:55296
	ds_read_b128 v[248:251], v199 offset:56320
	global_load_lds_dwordx4 v[204:205], off
	s_add_i32 m0, s71, 0x2000
	s_add_u32 s40, s40, 0xc000
	v_lshl_add_u64 v[204:205], s[42:43], 0, v[130:131]
	s_addc_u32 s41, s41, 0
	s_add_i32 s42, s72, s47
	global_load_lds_dwordx4 v[204:205], off
	v_lshl_add_u64 v[204:205], s[40:41], 0, v[128:129]
	s_mov_b32 m0, s42
	s_nop 0
	global_load_lds_dwordx4 v[204:205], off
	v_lshl_add_u64 v[204:205], s[40:41], 0, v[130:131]
	s_add_i32 m0, s42, 0x2000
	s_nop 0
	global_load_lds_dwordx4 v[204:205], off
	v_lshl_add_u64 v[204:205], s[38:39], 0, v[128:129]
	s_mov_b32 m0, s57
	s_nop 0
	global_load_lds_dwordx4 v[204:205], off
	v_lshl_add_u64 v[204:205], s[38:39], 0, v[130:131]
	s_mov_b32 m0, s58
	s_nop 0
	global_load_lds_dwordx4 v[204:205], off
	s_waitcnt vmcnt(8)
	s_waitcnt lgkmcnt(0)
	s_barrier
	s_setprio 1
	s_waitcnt lgkmcnt(0)
	v_mfma_f32_16x16x32_bf16 v[60:63], v[156:159], v[220:223], v[60:63]
	v_mfma_f32_16x16x32_bf16 v[56:59], v[164:167], v[220:223], v[56:59]
	v_mfma_f32_16x16x32_bf16 v[52:55], v[156:159], v[228:231], v[52:55]
	v_mfma_f32_16x16x32_bf16 v[48:51], v[164:167], v[228:231], v[48:51]
	v_mfma_f32_16x16x32_bf16 v[28:31], v[156:159], v[236:239], v[28:31]
	v_mfma_f32_16x16x32_bf16 v[24:27], v[164:167], v[236:239], v[24:27]
	v_mfma_f32_16x16x32_bf16 v[20:23], v[156:159], v[244:247], v[20:23]
	v_mfma_f32_16x16x32_bf16 v[12:15], v[164:167], v[244:247], v[12:15]
	v_mfma_f32_16x16x32_bf16 v[60:63], v[160:163], v[224:227], v[60:63]
	v_mfma_f32_16x16x32_bf16 v[56:59], v[168:171], v[224:227], v[56:59]
	v_mfma_f32_16x16x32_bf16 v[52:55], v[160:163], v[232:235], v[52:55]
	v_mfma_f32_16x16x32_bf16 v[48:51], v[168:171], v[232:235], v[48:51]
	v_mfma_f32_16x16x32_bf16 v[28:31], v[160:163], v[240:243], v[28:31]
	v_mfma_f32_16x16x32_bf16 v[24:27], v[168:171], v[240:243], v[24:27]
	v_mfma_f32_16x16x32_bf16 v[20:23], v[160:163], v[248:251], v[20:23]
	v_mfma_f32_16x16x32_bf16 v[12:15], v[168:171], v[248:251], v[12:15]
	v_mfma_f32_16x16x32_bf16 v[44:47], v[172:175], v[220:223], v[44:47]
	v_mfma_f32_16x16x32_bf16 v[40:43], v[212:215], v[220:223], v[40:43]
	v_mfma_f32_16x16x32_bf16 v[36:39], v[172:175], v[228:231], v[36:39]
	v_mfma_f32_16x16x32_bf16 v[32:35], v[212:215], v[228:231], v[32:35]
	v_mfma_f32_16x16x32_bf16 v[16:19], v[172:175], v[236:239], v[16:19]
	v_mfma_f32_16x16x32_bf16 v[8:11], v[212:215], v[236:239], v[8:11]
	v_mfma_f32_16x16x32_bf16 v[4:7], v[172:175], v[244:247], v[4:7]
	v_mfma_f32_16x16x32_bf16 v[0:3], v[212:215], v[244:247], v[0:3]
	v_mfma_f32_16x16x32_bf16 v[44:47], v[176:179], v[224:227], v[44:47]
	v_mfma_f32_16x16x32_bf16 v[40:43], v[216:219], v[224:227], v[40:43]
	v_mfma_f32_16x16x32_bf16 v[36:39], v[176:179], v[232:235], v[36:39]
	v_mfma_f32_16x16x32_bf16 v[32:35], v[216:219], v[232:235], v[32:35]
	v_mfma_f32_16x16x32_bf16 v[16:19], v[176:179], v[240:243], v[16:19]
	v_mfma_f32_16x16x32_bf16 v[8:11], v[216:219], v[240:243], v[8:11]
	v_mfma_f32_16x16x32_bf16 v[4:7], v[176:179], v[248:251], v[4:7]
	v_mfma_f32_16x16x32_bf16 v[0:3], v[216:219], v[248:251], v[0:3]
	s_setprio 0
	s_barrier
	s_add_i32 s70, s70, 2
	s_add_u32 s68, s68, 0x10000
	s_addc_u32 s69, s69, 0
	s_add_u32 s36, s36, 0x10000
	s_addc_u32 s37, s37, 0
	s_cmp_gt_u32 s70, 41
	s_cbranch_scc0 .LBB0_1481
	s_and_b64 vcc, exec, s[18:19]
	s_cbranch_vccz .LBB0_1484
	s_barrier

.LBB0_1563:
	ds_read_b128 v[168:171], v165
	ds_read_b128 v[172:175], v165 offset:1024
	ds_read_b128 v[176:179], v165 offset:2048
	ds_read_b128 v[180:183], v165 offset:3072
	ds_read_b128 v[184:187], v166
	ds_read_b128 v[188:191], v166 offset:1024
	ds_read_b128 v[192:195], v166 offset:2048
	ds_read_b128 v[196:199], v166 offset:3072
	s_add_u32 s22, s20, 0xfffc0080
	s_addc_u32 s23, s21, -1
	s_cmp_eq_u32 s49, 12
	s_cselect_b32 s25, s9, s23
	s_cselect_b32 s24, s45, s22
	s_cselect_b32 s23, s11, s48
	s_cselect_b32 s22, s46, s47
	v_lshl_add_u64 v[162:163], s[20:21], 0, v[156:157]
	s_add_i32 m0, s17, 0xc000
	ds_read_b128 v[210:213], v167
	ds_read_b128 v[214:217], v167 offset:1024
	ds_read_b128 v[218:221], v167 offset:2048
	ds_read_b128 v[222:225], v167 offset:3072
	ds_read_b128 v[226:229], v167 offset:4096
	ds_read_b128 v[230:233], v167 offset:5120
	ds_read_b128 v[234:237], v167 offset:6144
	ds_read_b128 v[238:241], v167 offset:7168
	global_load_lds_dwordx4 v[162:163], off
	v_lshl_add_u64 v[162:163], s[20:21], 0, v[154:155]
	s_add_i32 m0, s17, 0xe000
	s_nop 0
	global_load_lds_dwordx4 v[162:163], off
	s_waitcnt vmcnt(8)
	s_waitcnt lgkmcnt(0)
	s_barrier
	s_setprio 1
	s_waitcnt lgkmcnt(0)
	v_mfma_f32_16x16x32_bf16 v[124:127], v[168:171], v[210:213], v[124:127]
	v_mfma_f32_16x16x32_bf16 v[116:119], v[176:179], v[210:213], v[116:119]
	v_mfma_f32_16x16x32_bf16 v[108:111], v[168:171], v[218:221], v[108:111]
	v_mfma_f32_16x16x32_bf16 v[100:103], v[176:179], v[218:221], v[100:103]
	v_mfma_f32_16x16x32_bf16 v[92:95], v[168:171], v[226:229], v[92:95]
	v_mfma_f32_16x16x32_bf16 v[84:87], v[176:179], v[226:229], v[84:87]
	v_mfma_f32_16x16x32_bf16 v[76:79], v[168:171], v[234:237], v[76:79]
	v_mfma_f32_16x16x32_bf16 v[68:71], v[176:179], v[234:237], v[68:71]
	v_mfma_f32_16x16x32_bf16 v[124:127], v[172:175], v[214:217], v[124:127]
	v_mfma_f32_16x16x32_bf16 v[116:119], v[180:183], v[214:217], v[116:119]
	v_mfma_f32_16x16x32_bf16 v[108:111], v[172:175], v[222:225], v[108:111]
	v_mfma_f32_16x16x32_bf16 v[100:103], v[180:183], v[222:225], v[100:103]
	v_mfma_f32_16x16x32_bf16 v[92:95], v[172:175], v[230:233], v[92:95]
	v_mfma_f32_16x16x32_bf16 v[84:87], v[180:183], v[230:233], v[84:87]
	v_mfma_f32_16x16x32_bf16 v[76:79], v[172:175], v[238:241], v[76:79]
	v_mfma_f32_16x16x32_bf16 v[68:71], v[180:183], v[238:241], v[68:71]
	v_mfma_f32_16x16x32_bf16 v[120:123], v[184:187], v[210:213], v[120:123]
	v_mfma_f32_16x16x32_bf16 v[112:115], v[192:195], v[210:213], v[112:115]
	v_mfma_f32_16x16x32_bf16 v[104:107], v[184:187], v[218:221], v[104:107]
	v_mfma_f32_16x16x32_bf16 v[96:99], v[192:195], v[218:221], v[96:99]
	v_mfma_f32_16x16x32_bf16 v[88:91], v[184:187], v[226:229], v[88:91]
	v_mfma_f32_16x16x32_bf16 v[80:83], v[192:195], v[226:229], v[80:83]
	v_mfma_f32_16x16x32_bf16 v[72:75], v[184:187], v[234:237], v[72:75]
	v_mfma_f32_16x16x32_bf16 v[64:67], v[192:195], v[234:237], v[64:67]
	v_mfma_f32_16x16x32_bf16 v[120:123], v[188:191], v[214:217], v[120:123]
	v_mfma_f32_16x16x32_bf16 v[112:115], v[196:199], v[214:217], v[112:115]
	v_mfma_f32_16x16x32_bf16 v[104:107], v[188:191], v[222:225], v[104:107]
	v_mfma_f32_16x16x32_bf16 v[96:99], v[196:199], v[222:225], v[96:99]
	v_mfma_f32_16x16x32_bf16 v[88:91], v[188:191], v[230:233], v[88:91]
	v_mfma_f32_16x16x32_bf16 v[80:83], v[196:199], v[230:233], v[80:83]
	v_mfma_f32_16x16x32_bf16 v[72:75], v[188:191], v[238:241], v[72:75]
	v_mfma_f32_16x16x32_bf16 v[64:67], v[196:199], v[238:241], v[64:67]
	s_setprio 0
	s_barrier
	s_add_i32 s50, s43, s33
	v_lshl_add_u64 v[162:163], s[22:23], 0, v[132:133]
	s_mov_b32 m0, s50
	s_cmp_lg_u32 s54, 0
	s_cbranch_scc1 .Lts0_skip1
	ds_read_b128 v[210:213], v167 offset:16384
	ds_read_b128 v[214:217], v167 offset:17408
	ds_read_b128 v[218:221], v167 offset:18432
	ds_read_b128 v[222:225], v167 offset:19456
	ds_read_b128 v[226:229], v167 offset:20480
	ds_read_b128 v[230:233], v167 offset:21504
	ds_read_b128 v[234:237], v167 offset:22528
	ds_read_b128 v[238:241], v167 offset:23552
.Lts0_skip1:
	global_load_lds_dwordx4 v[162:163], off
	s_add_i32 m0, s50, 0x2000
	s_add_u32 s50, s22, 0x4000
	v_lshl_add_u64 v[162:163], s[22:23], 0, v[128:129]
	s_addc_u32 s51, s23, 0
	s_add_i32 s52, s44, s33
	global_load_lds_dwordx4 v[162:163], off
	v_lshl_add_u64 v[162:163], s[50:51], 0, v[132:133]
	s_mov_b32 m0, s52
	v_lshl_add_u64 v[200:201], s[24:25], 0, v[130:131]
	global_load_lds_dwordx4 v[162:163], off
	v_lshl_add_u64 v[162:163], s[50:51], 0, v[128:129]
	s_add_i32 m0, s52, 0x2000
	s_nop 0
	global_load_lds_dwordx4 v[162:163], off
	v_lshl_add_u64 v[162:163], s[24:25], 0, v[134:135]
	s_mov_b32 m0, s17
	s_nop 0
	global_load_lds_dwordx4 v[162:163], off
	s_mov_b32 m0, s19
	s_nop 0
	global_load_lds_dwordx4 v[200:201], off
	s_waitcnt vmcnt(8)
	s_waitcnt lgkmcnt(0)
	s_barrier
	s_cmp_lg_u32 s54, 0
	s_cbranch_scc1 .Lts0_skip0
	s_setprio 1
	s_waitcnt lgkmcnt(0)
	v_mfma_f32_16x16x32_bf16 v[60:63], v[168:171], v[210:213], v[60:63]
	v_mfma_f32_16x16x32_bf16 v[52:55], v[176:179], v[210:213], v[52:55]
	v_mfma_f32_16x16x32_bf16 v[44:47], v[168:171], v[218:221], v[44:47]
	v_mfma_f32_16x16x32_bf16 v[36:39], v[176:179], v[218:221], v[36:39]
	v_mfma_f32_16x16x32_bf16 v[28:31], v[168:171], v[226:229], v[28:31]
	v_mfma_f32_16x16x32_bf16 v[20:23], v[176:179], v[226:229], v[20:23]
	v_mfma_f32_16x16x32_bf16 v[12:15], v[168:171], v[234:237], v[12:15]
	v_mfma_f32_16x16x32_bf16 v[4:7], v[176:179], v[234:237], v[4:7]
	v_mfma_f32_16x16x32_bf16 v[60:63], v[172:175], v[214:217], v[60:63]
	v_mfma_f32_16x16x32_bf16 v[52:55], v[180:183], v[214:217], v[52:55]
	v_mfma_f32_16x16x32_bf16 v[44:47], v[172:175], v[222:225], v[44:47]
	v_mfma_f32_16x16x32_bf16 v[36:39], v[180:183], v[222:225], v[36:39]
	v_mfma_f32_16x16x32_bf16 v[28:31], v[172:175], v[230:233], v[28:31]
	v_mfma_f32_16x16x32_bf16 v[20:23], v[180:183], v[230:233], v[20:23]
	v_mfma_f32_16x16x32_bf16 v[12:15], v[172:175], v[238:241], v[12:15]
	v_mfma_f32_16x16x32_bf16 v[4:7], v[180:183], v[238:241], v[4:7]
	v_mfma_f32_16x16x32_bf16 v[56:59], v[184:187], v[210:213], v[56:59]
	v_mfma_f32_16x16x32_bf16 v[48:51], v[192:195], v[210:213], v[48:51]
	v_mfma_f32_16x16x32_bf16 v[40:43], v[184:187], v[218:221], v[40:43]
	v_mfma_f32_16x16x32_bf16 v[32:35], v[192:195], v[218:221], v[32:35]
	v_mfma_f32_16x16x32_bf16 v[24:27], v[184:187], v[226:229], v[24:27]
	v_mfma_f32_16x16x32_bf16 v[16:19], v[192:195], v[226:229], v[16:19]
	v_mfma_f32_16x16x32_bf16 v[8:11], v[184:187], v[234:237], v[8:11]
	v_mfma_f32_16x16x32_bf16 v[0:3], v[192:195], v[234:237], v[0:3]
	v_mfma_f32_16x16x32_bf16 v[56:59], v[188:191], v[214:217], v[56:59]
	v_mfma_f32_16x16x32_bf16 v[48:51], v[196:199], v[214:217], v[48:51]
	v_mfma_f32_16x16x32_bf16 v[40:43], v[188:191], v[222:225], v[40:43]
	v_mfma_f32_16x16x32_bf16 v[32:35], v[196:199], v[222:225], v[32:35]
	v_mfma_f32_16x16x32_bf16 v[24:27], v[188:191], v[230:233], v[24:27]
	v_mfma_f32_16x16x32_bf16 v[16:19], v[196:199], v[230:233], v[16:19]
	v_mfma_f32_16x16x32_bf16 v[8:11], v[188:191], v[238:241], v[8:11]
	v_mfma_f32_16x16x32_bf16 v[0:3], v[196:199], v[238:241], v[0:3]
	s_setprio 0
.Lts0_skip0:
	s_barrier
	s_add_i32 s50, 0, 0x18000
	s_add_i32 s51, 0, 0x1c000
	v_add_u32_e32 v180, s50, v164
	v_add_u32_e32 v196, s51, v164
	ds_read_b128 v[168:171], v180
	ds_read_b128 v[172:175], v180 offset:1024
	ds_read_b128 v[176:179], v180 offset:2048
	ds_read_b128 v[180:183], v180 offset:3072
	ds_read_b128 v[184:187], v196
	ds_read_b128 v[188:191], v196 offset:1024
	ds_read_b128 v[192:195], v196 offset:2048
	ds_read_b128 v[196:199], v196 offset:3072
	s_add_u32 s24, s24, 0x40000
	s_addc_u32 s25, s25, 0
	s_mov_b32 m0, s36
	v_lshl_add_u64 v[204:205], s[24:25], 0, v[134:135]
	ds_read_b128 v[210:213], v167 offset:32768
	ds_read_b128 v[214:217], v167 offset:33792
	ds_read_b128 v[218:221], v167 offset:34816
	ds_read_b128 v[222:225], v167 offset:35840
	ds_read_b128 v[226:229], v167 offset:36864
	ds_read_b128 v[230:233], v167 offset:37888
	ds_read_b128 v[234:237], v167 offset:38912
	ds_read_b128 v[238:241], v167 offset:39936
	global_load_lds_dwordx4 v[204:205], off
	v_lshl_add_u64 v[204:205], s[24:25], 0, v[130:131]
	s_mov_b32 m0, s37
	s_nop 0
	global_load_lds_dwordx4 v[204:205], off
	s_waitcnt vmcnt(8)
	s_waitcnt lgkmcnt(0)
	s_barrier
	s_setprio 1
	s_waitcnt lgkmcnt(0)
	v_mfma_f32_16x16x32_bf16 v[124:127], v[168:171], v[210:213], v[124:127]
	v_mfma_f32_16x16x32_bf16 v[116:119], v[176:179], v[210:213], v[116:119]
	v_mfma_f32_16x16x32_bf16 v[108:111], v[168:171], v[218:221], v[108:111]
	v_mfma_f32_16x16x32_bf16 v[100:103], v[176:179], v[218:221], v[100:103]
	v_mfma_f32_16x16x32_bf16 v[92:95], v[168:171], v[226:229], v[92:95]
	v_mfma_f32_16x16x32_bf16 v[84:87], v[176:179], v[226:229], v[84:87]
	v_mfma_f32_16x16x32_bf16 v[76:79], v[168:171], v[234:237], v[76:79]
	v_mfma_f32_16x16x32_bf16 v[68:71], v[176:179], v[234:237], v[68:71]
	v_mfma_f32_16x16x32_bf16 v[124:127], v[172:175], v[214:217], v[124:127]
	v_mfma_f32_16x16x32_bf16 v[116:119], v[180:183], v[214:217], v[116:119]
	v_mfma_f32_16x16x32_bf16 v[108:111], v[172:175], v[222:225], v[108:111]
	v_mfma_f32_16x16x32_bf16 v[100:103], v[180:183], v[222:225], v[100:103]
	v_mfma_f32_16x16x32_bf16 v[92:95], v[172:175], v[230:233], v[92:95]
	v_mfma_f32_16x16x32_bf16 v[84:87], v[180:183], v[230:233], v[84:87]
	v_mfma_f32_16x16x32_bf16 v[76:79], v[172:175], v[238:241], v[76:79]
	v_mfma_f32_16x16x32_bf16 v[68:71], v[180:183], v[238:241], v[68:71]
	v_mfma_f32_16x16x32_bf16 v[120:123], v[184:187], v[210:213], v[120:123]
	v_mfma_f32_16x16x32_bf16 v[112:115], v[192:195], v[210:213], v[112:115]
	v_mfma_f32_16x16x32_bf16 v[104:107], v[184:187], v[218:221], v[104:107]
	v_mfma_f32_16x16x32_bf16 v[96:99], v[192:195], v[218:221], v[96:99]
	v_mfma_f32_16x16x32_bf16 v[88:91], v[184:187], v[226:229], v[88:91]
	v_mfma_f32_16x16x32_bf16 v[80:83], v[192:195], v[226:229], v[80:83]
	v_mfma_f32_16x16x32_bf16 v[72:75], v[184:187], v[234:237], v[72:75]
	v_mfma_f32_16x16x32_bf16 v[64:67], v[192:195], v[234:237], v[64:67]
	v_mfma_f32_16x16x32_bf16 v[120:123], v[188:191], v[214:217], v[120:123]
	v_mfma_f32_16x16x32_bf16 v[112:115], v[196:199], v[214:217], v[112:115]
	v_mfma_f32_16x16x32_bf16 v[104:107], v[188:191], v[222:225], v[104:107]
	v_mfma_f32_16x16x32_bf16 v[96:99], v[196:199], v[222:225], v[96:99]
	v_mfma_f32_16x16x32_bf16 v[88:91], v[188:191], v[230:233], v[88:91]
	v_mfma_f32_16x16x32_bf16 v[80:83], v[196:199], v[230:233], v[80:83]
	v_mfma_f32_16x16x32_bf16 v[72:75], v[188:191], v[238:241], v[72:75]
	v_mfma_f32_16x16x32_bf16 v[64:67], v[196:199], v[238:241], v[64:67]
	s_setprio 0
	s_barrier
	s_add_u32 s24, s22, 0x8000
	s_addc_u32 s25, s23, 0
	s_add_i32 s50, s50, s33
	v_lshl_add_u64 v[204:205], s[24:25], 0, v[132:133]
	s_mov_b32 m0, s50
	s_cmp_lg_u32 s54, 0
	s_cbranch_scc1 .Lts0_skip3
	ds_read_b128 v[210:213], v167 offset:49152
	ds_read_b128 v[214:217], v167 offset:50176
	ds_read_b128 v[218:221], v167 offset:51200
	ds_read_b128 v[222:225], v167 offset:52224
	ds_read_b128 v[226:229], v167 offset:53248
	ds_read_b128 v[230:233], v167 offset:54272
	ds_read_b128 v[234:237], v167 offset:55296
	ds_read_b128 v[238:241], v167 offset:56320
.Lts0_skip3:
	global_load_lds_dwordx4 v[204:205], off
	s_add_i32 m0, s50, 0x2000
	s_add_u32 s22, s22, 0xc000
	v_lshl_add_u64 v[204:205], s[24:25], 0, v[128:129]
	s_addc_u32 s23, s23, 0
	s_add_i32 s24, s51, s33
	global_load_lds_dwordx4 v[204:205], off
	v_lshl_add_u64 v[204:205], s[22:23], 0, v[132:133]
	s_mov_b32 m0, s24
	v_lshl_add_u64 v[162:163], v[162:163], 0, s[4:5]
	global_load_lds_dwordx4 v[204:205], off
	v_lshl_add_u64 v[204:205], s[22:23], 0, v[128:129]
	s_add_i32 m0, s24, 0x2000
	s_nop 0
	global_load_lds_dwordx4 v[204:205], off
	s_mov_b32 m0, s40
	s_nop 0
	global_load_lds_dwordx4 v[162:163], off
	v_lshl_add_u64 v[162:163], v[200:201], 0, s[4:5]
	s_mov_b32 m0, s41
	s_nop 0
	global_load_lds_dwordx4 v[162:163], off
	s_waitcnt vmcnt(8)
	s_waitcnt lgkmcnt(0)
	s_barrier
	s_cmp_lg_u32 s54, 0
	s_cbranch_scc1 .Lts0_skip2
	s_setprio 1
	s_waitcnt lgkmcnt(0)
	v_mfma_f32_16x16x32_bf16 v[60:63], v[168:171], v[210:213], v[60:63]
	v_mfma_f32_16x16x32_bf16 v[52:55], v[176:179], v[210:213], v[52:55]
	v_mfma_f32_16x16x32_bf16 v[44:47], v[168:171], v[218:221], v[44:47]
	v_mfma_f32_16x16x32_bf16 v[36:39], v[176:179], v[218:221], v[36:39]
	v_mfma_f32_16x16x32_bf16 v[28:31], v[168:171], v[226:229], v[28:31]
	v_mfma_f32_16x16x32_bf16 v[20:23], v[176:179], v[226:229], v[20:23]
	v_mfma_f32_16x16x32_bf16 v[12:15], v[168:171], v[234:237], v[12:15]
	v_mfma_f32_16x16x32_bf16 v[4:7], v[176:179], v[234:237], v[4:7]
	v_mfma_f32_16x16x32_bf16 v[60:63], v[172:175], v[214:217], v[60:63]
	v_mfma_f32_16x16x32_bf16 v[52:55], v[180:183], v[214:217], v[52:55]
	v_mfma_f32_16x16x32_bf16 v[44:47], v[172:175], v[222:225], v[44:47]
	v_mfma_f32_16x16x32_bf16 v[36:39], v[180:183], v[222:225], v[36:39]
	v_mfma_f32_16x16x32_bf16 v[28:31], v[172:175], v[230:233], v[28:31]
	v_mfma_f32_16x16x32_bf16 v[20:23], v[180:183], v[230:233], v[20:23]
	v_mfma_f32_16x16x32_bf16 v[12:15], v[172:175], v[238:241], v[12:15]
	v_mfma_f32_16x16x32_bf16 v[4:7], v[180:183], v[238:241], v[4:7]
	v_mfma_f32_16x16x32_bf16 v[56:59], v[184:187], v[210:213], v[56:59]
	v_mfma_f32_16x16x32_bf16 v[48:51], v[192:195], v[210:213], v[48:51]
	v_mfma_f32_16x16x32_bf16 v[40:43], v[184:187], v[218:221], v[40:43]
	v_mfma_f32_16x16x32_bf16 v[32:35], v[192:195], v[218:221], v[32:35]
	v_mfma_f32_16x16x32_bf16 v[24:27], v[184:187], v[226:229], v[24:27]
	v_mfma_f32_16x16x32_bf16 v[16:19], v[192:195], v[226:229], v[16:19]
	v_mfma_f32_16x16x32_bf16 v[8:11], v[184:187], v[234:237], v[8:11]
	v_mfma_f32_16x16x32_bf16 v[0:3], v[192:195], v[234:237], v[0:3]
	v_mfma_f32_16x16x32_bf16 v[56:59], v[188:191], v[214:217], v[56:59]
	v_mfma_f32_16x16x32_bf16 v[48:51], v[196:199], v[214:217], v[48:51]
	v_mfma_f32_16x16x32_bf16 v[40:43], v[188:191], v[222:225], v[40:43]
	v_mfma_f32_16x16x32_bf16 v[32:35], v[196:199], v[222:225], v[32:35]
	v_mfma_f32_16x16x32_bf16 v[24:27], v[188:191], v[230:233], v[24:27]
	v_mfma_f32_16x16x32_bf16 v[16:19], v[196:199], v[230:233], v[16:19]
	v_mfma_f32_16x16x32_bf16 v[8:11], v[188:191], v[238:241], v[8:11]
	v_mfma_f32_16x16x32_bf16 v[0:3], v[196:199], v[238:241], v[0:3]
	s_setprio 0

.LBB0_1645:
	v_add_u32_e32 v168, s69, v182
	v_add_u32_e32 v204, s70, v182
	ds_read_b128 v[156:159], v168
	ds_read_b128 v[160:163], v168 offset:1024
	ds_read_b128 v[164:167], v168 offset:2048
	ds_read_b128 v[168:171], v168 offset:3072
	ds_read_b128 v[172:175], v204
	ds_read_b128 v[176:179], v204 offset:1024
	ds_read_b128 v[212:215], v204 offset:2048
	ds_read_b128 v[216:219], v204 offset:3072
	s_add_u32 s38, s36, 0x4000
	s_addc_u32 s39, s37, 0
	s_cmp_eq_u32 s47, 40
	s_cselect_b32 s42, s0, s38
	s_cselect_b32 s43, s1, s39
	s_cselect_b32 s40, s34, s45
	s_cselect_b32 s41, s35, s46
	s_add_u32 s38, s42, 0x8000
	s_addc_u32 s39, s43, 0
	v_lshl_add_u64 v[204:205], s[36:37], 0, v[150:151]
	s_add_i32 m0, s56, 0xc000
	ds_read_b128 v[220:223], v199
	ds_read_b128 v[224:227], v199 offset:1024
	ds_read_b128 v[228:231], v199 offset:2048
	ds_read_b128 v[232:235], v199 offset:3072
	ds_read_b128 v[236:239], v199 offset:4096
	ds_read_b128 v[240:243], v199 offset:5120
	ds_read_b128 v[244:247], v199 offset:6144
	ds_read_b128 v[248:251], v199 offset:7168
	global_load_lds_dwordx4 v[204:205], off
	v_lshl_add_u64 v[204:205], s[36:37], 0, v[148:149]
	s_add_i32 m0, s56, 0xe000
	s_nop 0
	global_load_lds_dwordx4 v[204:205], off
	s_waitcnt vmcnt(8)
	s_waitcnt lgkmcnt(0)
	s_barrier
	s_setprio 1
	s_waitcnt lgkmcnt(0)
	v_mfma_f32_16x16x32_bf16 v[124:127], v[156:159], v[220:223], v[124:127]
	v_mfma_f32_16x16x32_bf16 v[120:123], v[164:167], v[220:223], v[120:123]
	v_mfma_f32_16x16x32_bf16 v[116:119], v[156:159], v[228:231], v[116:119]
	v_mfma_f32_16x16x32_bf16 v[112:115], v[164:167], v[228:231], v[112:115]
	v_mfma_f32_16x16x32_bf16 v[92:95], v[156:159], v[236:239], v[92:95]
	v_mfma_f32_16x16x32_bf16 v[88:91], v[164:167], v[236:239], v[88:91]
	v_mfma_f32_16x16x32_bf16 v[84:87], v[156:159], v[244:247], v[84:87]
	v_mfma_f32_16x16x32_bf16 v[80:83], v[164:167], v[244:247], v[80:83]
	v_mfma_f32_16x16x32_bf16 v[124:127], v[160:163], v[224:227], v[124:127]
	v_mfma_f32_16x16x32_bf16 v[120:123], v[168:171], v[224:227], v[120:123]
	v_mfma_f32_16x16x32_bf16 v[116:119], v[160:163], v[232:235], v[116:119]
	v_mfma_f32_16x16x32_bf16 v[112:115], v[168:171], v[232:235], v[112:115]
	v_mfma_f32_16x16x32_bf16 v[92:95], v[160:163], v[240:243], v[92:95]
	v_mfma_f32_16x16x32_bf16 v[88:91], v[168:171], v[240:243], v[88:91]
	v_mfma_f32_16x16x32_bf16 v[84:87], v[160:163], v[248:251], v[84:87]
	v_mfma_f32_16x16x32_bf16 v[80:83], v[168:171], v[248:251], v[80:83]
	v_mfma_f32_16x16x32_bf16 v[108:111], v[172:175], v[220:223], v[108:111]
	v_mfma_f32_16x16x32_bf16 v[104:107], v[212:215], v[220:223], v[104:107]
	v_mfma_f32_16x16x32_bf16 v[100:103], v[172:175], v[228:231], v[100:103]
	v_mfma_f32_16x16x32_bf16 v[96:99], v[212:215], v[228:231], v[96:99]
	v_mfma_f32_16x16x32_bf16 v[76:79], v[172:175], v[236:239], v[76:79]
	v_mfma_f32_16x16x32_bf16 v[72:75], v[212:215], v[236:239], v[72:75]
	v_mfma_f32_16x16x32_bf16 v[68:71], v[172:175], v[244:247], v[68:71]
	v_mfma_f32_16x16x32_bf16 v[64:67], v[212:215], v[244:247], v[64:67]
	v_mfma_f32_16x16x32_bf16 v[108:111], v[176:179], v[224:227], v[108:111]
	v_mfma_f32_16x16x32_bf16 v[104:107], v[216:219], v[224:227], v[104:107]
	v_mfma_f32_16x16x32_bf16 v[100:103], v[176:179], v[232:235], v[100:103]
	v_mfma_f32_16x16x32_bf16 v[96:99], v[216:219], v[232:235], v[96:99]
	v_mfma_f32_16x16x32_bf16 v[76:79], v[176:179], v[240:243], v[76:79]
	v_mfma_f32_16x16x32_bf16 v[72:75], v[216:219], v[240:243], v[72:75]
	v_mfma_f32_16x16x32_bf16 v[68:71], v[176:179], v[248:251], v[68:71]
	v_mfma_f32_16x16x32_bf16 v[64:67], v[216:219], v[248:251], v[64:67]
	s_setprio 0
	s_barrier
	s_add_i32 s48, s69, s55
	v_lshl_add_u64 v[204:205], s[40:41], 0, v[128:129]
	s_mov_b32 m0, s48
	ds_read_b128 v[220:223], v199 offset:16384
	ds_read_b128 v[224:227], v199 offset:17408
	ds_read_b128 v[228:231], v199 offset:18432
	ds_read_b128 v[232:235], v199 offset:19456
	ds_read_b128 v[236:239], v199 offset:20480
	ds_read_b128 v[240:243], v199 offset:21504
	ds_read_b128 v[244:247], v199 offset:22528
	ds_read_b128 v[248:251], v199 offset:23552
	global_load_lds_dwordx4 v[204:205], off
	s_add_i32 m0, s48, 0x2000
	s_add_u32 s48, s40, 0x4000
	v_lshl_add_u64 v[204:205], s[40:41], 0, v[130:131]
	s_addc_u32 s49, s41, 0
	s_add_i32 s50, s70, s55
	global_load_lds_dwordx4 v[204:205], off
	v_lshl_add_u64 v[204:205], s[48:49], 0, v[128:129]
	s_mov_b32 m0, s50
	s_nop 0
	global_load_lds_dwordx4 v[204:205], off
	v_lshl_add_u64 v[204:205], s[48:49], 0, v[130:131]
	s_add_i32 m0, s50, 0x2000
	s_nop 0
	global_load_lds_dwordx4 v[204:205], off
	v_lshl_add_u64 v[204:205], s[42:43], 0, v[128:129]
	s_mov_b32 m0, s56
	s_nop 0
	global_load_lds_dwordx4 v[204:205], off
	v_lshl_add_u64 v[204:205], s[42:43], 0, v[130:131]
	s_mov_b32 m0, s57
	s_nop 0
	global_load_lds_dwordx4 v[204:205], off
	s_waitcnt vmcnt(8)
	s_waitcnt lgkmcnt(0)
	s_barrier
	s_setprio 1
	s_waitcnt lgkmcnt(0)
	v_mfma_f32_16x16x32_bf16 v[60:63], v[156:159], v[220:223], v[60:63]
	v_mfma_f32_16x16x32_bf16 v[56:59], v[164:167], v[220:223], v[56:59]
	v_mfma_f32_16x16x32_bf16 v[52:55], v[156:159], v[228:231], v[52:55]
	v_mfma_f32_16x16x32_bf16 v[48:51], v[164:167], v[228:231], v[48:51]
	v_mfma_f32_16x16x32_bf16 v[28:31], v[156:159], v[236:239], v[28:31]
	v_mfma_f32_16x16x32_bf16 v[24:27], v[164:167], v[236:239], v[24:27]
	v_mfma_f32_16x16x32_bf16 v[20:23], v[156:159], v[244:247], v[20:23]
	v_mfma_f32_16x16x32_bf16 v[12:15], v[164:167], v[244:247], v[12:15]
	v_mfma_f32_16x16x32_bf16 v[60:63], v[160:163], v[224:227], v[60:63]
	v_mfma_f32_16x16x32_bf16 v[56:59], v[168:171], v[224:227], v[56:59]
	v_mfma_f32_16x16x32_bf16 v[52:55], v[160:163], v[232:235], v[52:55]
	v_mfma_f32_16x16x32_bf16 v[48:51], v[168:171], v[232:235], v[48:51]
	v_mfma_f32_16x16x32_bf16 v[28:31], v[160:163], v[240:243], v[28:31]
	v_mfma_f32_16x16x32_bf16 v[24:27], v[168:171], v[240:243], v[24:27]
	v_mfma_f32_16x16x32_bf16 v[20:23], v[160:163], v[248:251], v[20:23]
	v_mfma_f32_16x16x32_bf16 v[12:15], v[168:171], v[248:251], v[12:15]
	v_mfma_f32_16x16x32_bf16 v[44:47], v[172:175], v[220:223], v[44:47]
	v_mfma_f32_16x16x32_bf16 v[40:43], v[212:215], v[220:223], v[40:43]
	v_mfma_f32_16x16x32_bf16 v[36:39], v[172:175], v[228:231], v[36:39]
	v_mfma_f32_16x16x32_bf16 v[32:35], v[212:215], v[228:231], v[32:35]
	v_mfma_f32_16x16x32_bf16 v[16:19], v[172:175], v[236:239], v[16:19]
	v_mfma_f32_16x16x32_bf16 v[8:11], v[212:215], v[236:239], v[8:11]
	v_mfma_f32_16x16x32_bf16 v[4:7], v[172:175], v[244:247], v[4:7]
	v_mfma_f32_16x16x32_bf16 v[0:3], v[212:215], v[244:247], v[0:3]
	v_mfma_f32_16x16x32_bf16 v[44:47], v[176:179], v[224:227], v[44:47]
	v_mfma_f32_16x16x32_bf16 v[40:43], v[216:219], v[224:227], v[40:43]
	v_mfma_f32_16x16x32_bf16 v[36:39], v[176:179], v[232:235], v[36:39]
	v_mfma_f32_16x16x32_bf16 v[32:35], v[216:219], v[232:235], v[32:35]
	v_mfma_f32_16x16x32_bf16 v[16:19], v[176:179], v[240:243], v[16:19]
	v_mfma_f32_16x16x32_bf16 v[8:11], v[216:219], v[240:243], v[8:11]
	v_mfma_f32_16x16x32_bf16 v[4:7], v[176:179], v[248:251], v[4:7]
	v_mfma_f32_16x16x32_bf16 v[0:3], v[216:219], v[248:251], v[0:3]
	s_setprio 0
	s_barrier
	s_add_i32 s48, 0, 0x18000
	s_add_i32 s49, 0, 0x1c000
	v_add_u32_e32 v168, s48, v182
	v_add_u32_e32 v204, s49, v182
	ds_read_b128 v[156:159], v168
	ds_read_b128 v[160:163], v168 offset:1024
	ds_read_b128 v[164:167], v168 offset:2048
	ds_read_b128 v[168:171], v168 offset:3072
	ds_read_b128 v[172:175], v204
	ds_read_b128 v[176:179], v204 offset:1024
	ds_read_b128 v[212:215], v204 offset:2048
	ds_read_b128 v[216:219], v204 offset:3072
	s_add_u32 s42, s42, 0x4000
	s_addc_u32 s43, s43, 0
	s_mov_b32 m0, s58
	v_lshl_add_u64 v[204:205], s[42:43], 0, v[128:129]
	ds_read_b128 v[220:223], v199 offset:32768
	ds_read_b128 v[224:227], v199 offset:33792
	ds_read_b128 v[228:231], v199 offset:34816
	ds_read_b128 v[232:235], v199 offset:35840
	ds_read_b128 v[236:239], v199 offset:36864
	ds_read_b128 v[240:243], v199 offset:37888
	ds_read_b128 v[244:247], v199 offset:38912
	ds_read_b128 v[248:251], v199 offset:39936
	global_load_lds_dwordx4 v[204:205], off
	v_lshl_add_u64 v[204:205], s[42:43], 0, v[130:131]
	s_mov_b32 m0, s59
	s_nop 0
	global_load_lds_dwordx4 v[204:205], off
	s_waitcnt vmcnt(8)
	s_waitcnt lgkmcnt(0)
	s_barrier
	s_setprio 1
	s_waitcnt lgkmcnt(0)
	v_mfma_f32_16x16x32_bf16 v[124:127], v[156:159], v[220:223], v[124:127]
	v_mfma_f32_16x16x32_bf16 v[120:123], v[164:167], v[220:223], v[120:123]
	v_mfma_f32_16x16x32_bf16 v[116:119], v[156:159], v[228:231], v[116:119]
	v_mfma_f32_16x16x32_bf16 v[112:115], v[164:167], v[228:231], v[112:115]
	v_mfma_f32_16x16x32_bf16 v[92:95], v[156:159], v[236:239], v[92:95]
	v_mfma_f32_16x16x32_bf16 v[88:91], v[164:167], v[236:239], v[88:91]
	v_mfma_f32_16x16x32_bf16 v[84:87], v[156:159], v[244:247], v[84:87]
	v_mfma_f32_16x16x32_bf16 v[80:83], v[164:167], v[244:247], v[80:83]
	v_mfma_f32_16x16x32_bf16 v[124:127], v[160:163], v[224:227], v[124:127]
	v_mfma_f32_16x16x32_bf16 v[120:123], v[168:171], v[224:227], v[120:123]
	v_mfma_f32_16x16x32_bf16 v[116:119], v[160:163], v[232:235], v[116:119]
	v_mfma_f32_16x16x32_bf16 v[112:115], v[168:171], v[232:235], v[112:115]
	v_mfma_f32_16x16x32_bf16 v[92:95], v[160:163], v[240:243], v[92:95]
	v_mfma_f32_16x16x32_bf16 v[88:91], v[168:171], v[240:243], v[88:91]
	v_mfma_f32_16x16x32_bf16 v[84:87], v[160:163], v[248:251], v[84:87]
	v_mfma_f32_16x16x32_bf16 v[80:83], v[168:171], v[248:251], v[80:83]
	v_mfma_f32_16x16x32_bf16 v[108:111], v[172:175], v[220:223], v[108:111]
	v_mfma_f32_16x16x32_bf16 v[104:107], v[212:215], v[220:223], v[104:107]
	v_mfma_f32_16x16x32_bf16 v[100:103], v[172:175], v[228:231], v[100:103]
	v_mfma_f32_16x16x32_bf16 v[96:99], v[212:215], v[228:231], v[96:99]
	v_mfma_f32_16x16x32_bf16 v[76:79], v[172:175], v[236:239], v[76:79]
	v_mfma_f32_16x16x32_bf16 v[72:75], v[212:215], v[236:239], v[72:75]
	v_mfma_f32_16x16x32_bf16 v[68:71], v[172:175], v[244:247], v[68:71]
	v_mfma_f32_16x16x32_bf16 v[64:67], v[212:215], v[244:247], v[64:67]
	v_mfma_f32_16x16x32_bf16 v[108:111], v[176:179], v[224:227], v[108:111]
	v_mfma_f32_16x16x32_bf16 v[104:107], v[216:219], v[224:227], v[104:107]
	v_mfma_f32_16x16x32_bf16 v[100:103], v[176:179], v[232:235], v[100:103]
	v_mfma_f32_16x16x32_bf16 v[96:99], v[216:219], v[232:235], v[96:99]
	v_mfma_f32_16x16x32_bf16 v[76:79], v[176:179], v[240:243], v[76:79]
	v_mfma_f32_16x16x32_bf16 v[72:75], v[216:219], v[240:243], v[72:75]
	v_mfma_f32_16x16x32_bf16 v[68:71], v[176:179], v[248:251], v[68:71]
	v_mfma_f32_16x16x32_bf16 v[64:67], v[216:219], v[248:251], v[64:67]
	s_setprio 0
	s_barrier
	s_add_u32 s42, s40, 0x8000
	s_addc_u32 s43, s41, 0
	s_add_i32 s48, s48, s55
	v_lshl_add_u64 v[204:205], s[42:43], 0, v[128:129]
	s_mov_b32 m0, s48
	ds_read_b128 v[220:223], v199 offset:49152
	ds_read_b128 v[224:227], v199 offset:50176
	ds_read_b128 v[228:231], v199 offset:51200
	ds_read_b128 v[232:235], v199 offset:52224
	ds_read_b128 v[236:239], v199 offset:53248
	ds_read_b128 v[240:243], v199 offset:54272
	ds_read_b128 v[244:247], v199 offset:55296
	ds_read_b128 v[248:251], v199 offset:56320
	global_load_lds_dwordx4 v[204:205], off
	s_add_i32 m0, s48, 0x2000
	s_add_u32 s40, s40, 0xc000
	v_lshl_add_u64 v[204:205], s[42:43], 0, v[130:131]
	s_addc_u32 s41, s41, 0
	s_add_i32 s42, s49, s55
	global_load_lds_dwordx4 v[204:205], off
	v_lshl_add_u64 v[204:205], s[40:41], 0, v[128:129]
	s_mov_b32 m0, s42
	s_nop 0
	global_load_lds_dwordx4 v[204:205], off
	v_lshl_add_u64 v[204:205], s[40:41], 0, v[130:131]
	s_add_i32 m0, s42, 0x2000
	s_nop 0
	global_load_lds_dwordx4 v[204:205], off
	v_lshl_add_u64 v[204:205], s[38:39], 0, v[128:129]
	s_mov_b32 m0, s65
	s_nop 0
	global_load_lds_dwordx4 v[204:205], off
	v_lshl_add_u64 v[204:205], s[38:39], 0, v[130:131]
	s_mov_b32 m0, s66
	s_nop 0
	global_load_lds_dwordx4 v[204:205], off
	s_waitcnt vmcnt(8)
	s_waitcnt lgkmcnt(0)
	s_barrier
	s_setprio 1
	s_waitcnt lgkmcnt(0)
	v_mfma_f32_16x16x32_bf16 v[60:63], v[156:159], v[220:223], v[60:63]
	v_mfma_f32_16x16x32_bf16 v[56:59], v[164:167], v[220:223], v[56:59]
	v_mfma_f32_16x16x32_bf16 v[52:55], v[156:159], v[228:231], v[52:55]
	v_mfma_f32_16x16x32_bf16 v[48:51], v[164:167], v[228:231], v[48:51]
	v_mfma_f32_16x16x32_bf16 v[28:31], v[156:159], v[236:239], v[28:31]
	v_mfma_f32_16x16x32_bf16 v[24:27], v[164:167], v[236:239], v[24:27]
	v_mfma_f32_16x16x32_bf16 v[20:23], v[156:159], v[244:247], v[20:23]
	v_mfma_f32_16x16x32_bf16 v[12:15], v[164:167], v[244:247], v[12:15]
	v_mfma_f32_16x16x32_bf16 v[60:63], v[160:163], v[224:227], v[60:63]
	v_mfma_f32_16x16x32_bf16 v[56:59], v[168:171], v[224:227], v[56:59]
	v_mfma_f32_16x16x32_bf16 v[52:55], v[160:163], v[232:235], v[52:55]
	v_mfma_f32_16x16x32_bf16 v[48:51], v[168:171], v[232:235], v[48:51]
	v_mfma_f32_16x16x32_bf16 v[28:31], v[160:163], v[240:243], v[28:31]
	v_mfma_f32_16x16x32_bf16 v[24:27], v[168:171], v[240:243], v[24:27]
	v_mfma_f32_16x16x32_bf16 v[20:23], v[160:163], v[248:251], v[20:23]
	v_mfma_f32_16x16x32_bf16 v[12:15], v[168:171], v[248:251], v[12:15]
	v_mfma_f32_16x16x32_bf16 v[44:47], v[172:175], v[220:223], v[44:47]
	v_mfma_f32_16x16x32_bf16 v[40:43], v[212:215], v[220:223], v[40:43]
	v_mfma_f32_16x16x32_bf16 v[36:39], v[172:175], v[228:231], v[36:39]
	v_mfma_f32_16x16x32_bf16 v[32:35], v[212:215], v[228:231], v[32:35]
	v_mfma_f32_16x16x32_bf16 v[16:19], v[172:175], v[236:239], v[16:19]
	v_mfma_f32_16x16x32_bf16 v[8:11], v[212:215], v[236:239], v[8:11]
	v_mfma_f32_16x16x32_bf16 v[4:7], v[172:175], v[244:247], v[4:7]
	v_mfma_f32_16x16x32_bf16 v[0:3], v[212:215], v[244:247], v[0:3]
	v_mfma_f32_16x16x32_bf16 v[44:47], v[176:179], v[224:227], v[44:47]
	v_mfma_f32_16x16x32_bf16 v[40:43], v[216:219], v[224:227], v[40:43]
	v_mfma_f32_16x16x32_bf16 v[36:39], v[176:179], v[232:235], v[36:39]
	v_mfma_f32_16x16x32_bf16 v[32:35], v[216:219], v[232:235], v[32:35]
	v_mfma_f32_16x16x32_bf16 v[16:19], v[176:179], v[240:243], v[16:19]
	v_mfma_f32_16x16x32_bf16 v[8:11], v[216:219], v[240:243], v[8:11]
	v_mfma_f32_16x16x32_bf16 v[4:7], v[176:179], v[248:251], v[4:7]
	v_mfma_f32_16x16x32_bf16 v[0:3], v[216:219], v[248:251], v[0:3]
	s_setprio 0
	s_barrier
	s_add_i32 s47, s47, 2
	s_add_u32 s45, s45, 0x10000
	s_addc_u32 s46, s46, 0
	s_add_u32 s36, s36, 0x10000
	s_addc_u32 s37, s37, 0
	s_cmp_gt_u32 s47, 41
	s_cbranch_scc0 .LBB0_1645
	s_and_b64 vcc, exec, s[2:3]
	s_cbranch_vccz .LBB0_1648
	s_barrier

.LBB0_1729:
	ds_read_b128 v[128:131], v210
	ds_read_b128 v[132:135], v210 offset:1024
	ds_read_b128 v[136:139], v210 offset:2048
	ds_read_b128 v[140:143], v210 offset:3072
	ds_read_b128 v[144:147], v211
	ds_read_b128 v[148:151], v211 offset:1024
	ds_read_b128 v[152:155], v211 offset:2048
	ds_read_b128 v[156:159], v211 offset:3072
	s_add_u32 s26, s6, 0xfffc0080
	s_addc_u32 s27, s7, -1
	s_cmp_eq_u32 s35, 12
	s_cselect_b32 s29, s1, s27
	s_cselect_b32 s28, s19, s26
	s_cselect_b32 s27, s21, s34
	s_cselect_b32 s26, s30, s31
	v_lshl_add_u64 v[198:199], s[6:7], 0, v[188:189]
	s_add_i32 m0, s42, 0xc000
	ds_read_b128 v[160:163], v212
	ds_read_b128 v[164:167], v212 offset:1024
	ds_read_b128 v[194:197], v212 offset:2048
	ds_read_b128 v[214:217], v212 offset:3072
	ds_read_b128 v[218:221], v212 offset:4096
	ds_read_b128 v[222:225], v212 offset:5120
	ds_read_b128 v[226:229], v212 offset:6144
	ds_read_b128 v[230:233], v212 offset:7168
	global_load_lds_dwordx4 v[198:199], off
	v_lshl_add_u64 v[198:199], s[6:7], 0, v[186:187]
	s_add_i32 m0, s42, 0xe000
	s_nop 0
	global_load_lds_dwordx4 v[198:199], off
	s_waitcnt vmcnt(8)
	s_waitcnt lgkmcnt(0)
	s_barrier
	s_setprio 1
	s_waitcnt lgkmcnt(0)
	v_mfma_f32_16x16x32_bf16 v[124:127], v[128:131], v[160:163], v[124:127]
	v_mfma_f32_16x16x32_bf16 v[120:123], v[136:139], v[160:163], v[120:123]
	v_mfma_f32_16x16x32_bf16 v[116:119], v[128:131], v[194:197], v[116:119]
	v_mfma_f32_16x16x32_bf16 v[112:115], v[136:139], v[194:197], v[112:115]
	v_mfma_f32_16x16x32_bf16 v[108:111], v[128:131], v[218:221], v[108:111]
	v_mfma_f32_16x16x32_bf16 v[104:107], v[136:139], v[218:221], v[104:107]
	v_mfma_f32_16x16x32_bf16 v[100:103], v[128:131], v[226:229], v[100:103]
	v_mfma_f32_16x16x32_bf16 v[96:99], v[136:139], v[226:229], v[96:99]
	v_mfma_f32_16x16x32_bf16 v[124:127], v[132:135], v[164:167], v[124:127]
	v_mfma_f32_16x16x32_bf16 v[120:123], v[140:143], v[164:167], v[120:123]
	v_mfma_f32_16x16x32_bf16 v[116:119], v[132:135], v[214:217], v[116:119]
	v_mfma_f32_16x16x32_bf16 v[112:115], v[140:143], v[214:217], v[112:115]
	v_mfma_f32_16x16x32_bf16 v[108:111], v[132:135], v[222:225], v[108:111]
	v_mfma_f32_16x16x32_bf16 v[104:107], v[140:143], v[222:225], v[104:107]
	v_mfma_f32_16x16x32_bf16 v[100:103], v[132:135], v[230:233], v[100:103]
	v_mfma_f32_16x16x32_bf16 v[96:99], v[140:143], v[230:233], v[96:99]
	v_mfma_f32_16x16x32_bf16 v[60:63], v[144:147], v[160:163], v[60:63]
	v_mfma_f32_16x16x32_bf16 v[56:59], v[152:155], v[160:163], v[56:59]
	v_mfma_f32_16x16x32_bf16 v[52:55], v[144:147], v[194:197], v[52:55]
	v_mfma_f32_16x16x32_bf16 v[48:51], v[152:155], v[194:197], v[48:51]
	v_mfma_f32_16x16x32_bf16 v[44:47], v[144:147], v[218:221], v[44:47]
	v_mfma_f32_16x16x32_bf16 v[40:43], v[152:155], v[218:221], v[40:43]
	v_mfma_f32_16x16x32_bf16 v[36:39], v[144:147], v[226:229], v[36:39]
	v_mfma_f32_16x16x32_bf16 v[32:35], v[152:155], v[226:229], v[32:35]
	v_mfma_f32_16x16x32_bf16 v[60:63], v[148:151], v[164:167], v[60:63]
	v_mfma_f32_16x16x32_bf16 v[56:59], v[156:159], v[164:167], v[56:59]
	v_mfma_f32_16x16x32_bf16 v[52:55], v[148:151], v[214:217], v[52:55]
	v_mfma_f32_16x16x32_bf16 v[48:51], v[156:159], v[214:217], v[48:51]
	v_mfma_f32_16x16x32_bf16 v[44:47], v[148:151], v[222:225], v[44:47]
	v_mfma_f32_16x16x32_bf16 v[40:43], v[156:159], v[222:225], v[40:43]
	v_mfma_f32_16x16x32_bf16 v[36:39], v[148:151], v[230:233], v[36:39]
	v_mfma_f32_16x16x32_bf16 v[32:35], v[156:159], v[230:233], v[32:35]
	s_setprio 0
	s_barrier
	s_add_i32 s61, s56, s41
	v_lshl_add_u64 v[198:199], s[26:27], 0, v[170:171]
	s_mov_b32 m0, s61
	ds_read_b128 v[160:163], v212 offset:16384
	ds_read_b128 v[164:167], v212 offset:17408
	ds_read_b128 v[194:197], v212 offset:18432
	ds_read_b128 v[214:217], v212 offset:19456
	ds_read_b128 v[218:221], v212 offset:20480
	ds_read_b128 v[222:225], v212 offset:21504
	ds_read_b128 v[226:229], v212 offset:22528
	ds_read_b128 v[230:233], v212 offset:23552
	global_load_lds_dwordx4 v[198:199], off
	s_add_i32 m0, s61, 0x2000
	s_add_u32 s62, s26, 0x4000
	v_lshl_add_u64 v[198:199], s[26:27], 0, v[174:175]
	s_addc_u32 s63, s27, 0
	s_add_i32 s61, s57, s41
	global_load_lds_dwordx4 v[198:199], off
	v_lshl_add_u64 v[198:199], s[62:63], 0, v[170:171]
	s_mov_b32 m0, s61
	v_lshl_add_u64 v[204:205], s[28:29], 0, v[172:173]
	global_load_lds_dwordx4 v[198:199], off
	v_lshl_add_u64 v[198:199], s[62:63], 0, v[174:175]
	s_add_i32 m0, s61, 0x2000
	s_nop 0
	global_load_lds_dwordx4 v[198:199], off
	v_lshl_add_u64 v[198:199], s[28:29], 0, v[168:169]
	s_mov_b32 m0, s42
	s_nop 0
	global_load_lds_dwordx4 v[198:199], off
	s_mov_b32 m0, s43
	s_nop 0
	global_load_lds_dwordx4 v[204:205], off
	s_waitcnt vmcnt(8)
	s_waitcnt lgkmcnt(0)
	s_barrier
	s_setprio 1
	s_waitcnt lgkmcnt(0)
	v_mfma_f32_16x16x32_bf16 v[92:95], v[128:131], v[160:163], v[92:95]
	v_mfma_f32_16x16x32_bf16 v[88:91], v[136:139], v[160:163], v[88:91]
	v_mfma_f32_16x16x32_bf16 v[84:87], v[128:131], v[194:197], v[84:87]
	v_mfma_f32_16x16x32_bf16 v[80:83], v[136:139], v[194:197], v[80:83]
	v_mfma_f32_16x16x32_bf16 v[76:79], v[128:131], v[218:221], v[76:79]
	v_mfma_f32_16x16x32_bf16 v[72:75], v[136:139], v[218:221], v[72:75]
	v_mfma_f32_16x16x32_bf16 v[68:71], v[128:131], v[226:229], v[68:71]
	v_mfma_f32_16x16x32_bf16 v[64:67], v[136:139], v[226:229], v[64:67]
	v_mfma_f32_16x16x32_bf16 v[92:95], v[132:135], v[164:167], v[92:95]
	v_mfma_f32_16x16x32_bf16 v[88:91], v[140:143], v[164:167], v[88:91]
	v_mfma_f32_16x16x32_bf16 v[84:87], v[132:135], v[214:217], v[84:87]
	v_mfma_f32_16x16x32_bf16 v[80:83], v[140:143], v[214:217], v[80:83]
	v_mfma_f32_16x16x32_bf16 v[76:79], v[132:135], v[222:225], v[76:79]
	v_mfma_f32_16x16x32_bf16 v[72:75], v[140:143], v[222:225], v[72:75]
	v_mfma_f32_16x16x32_bf16 v[68:71], v[132:135], v[230:233], v[68:71]
	v_mfma_f32_16x16x32_bf16 v[64:67], v[140:143], v[230:233], v[64:67]
	v_mfma_f32_16x16x32_bf16 v[28:31], v[144:147], v[160:163], v[28:31]
	v_mfma_f32_16x16x32_bf16 v[24:27], v[152:155], v[160:163], v[24:27]
	v_mfma_f32_16x16x32_bf16 v[20:23], v[144:147], v[194:197], v[20:23]
	v_mfma_f32_16x16x32_bf16 v[16:19], v[152:155], v[194:197], v[16:19]
	v_mfma_f32_16x16x32_bf16 v[12:15], v[144:147], v[218:221], v[12:15]
	v_mfma_f32_16x16x32_bf16 v[8:11], v[152:155], v[218:221], v[8:11]
	v_mfma_f32_16x16x32_bf16 v[4:7], v[144:147], v[226:229], v[4:7]
	v_mfma_f32_16x16x32_bf16 v[0:3], v[152:155], v[226:229], v[0:3]
	v_mfma_f32_16x16x32_bf16 v[28:31], v[148:151], v[164:167], v[28:31]
	v_mfma_f32_16x16x32_bf16 v[24:27], v[156:159], v[164:167], v[24:27]
	v_mfma_f32_16x16x32_bf16 v[20:23], v[148:151], v[214:217], v[20:23]
	v_mfma_f32_16x16x32_bf16 v[16:19], v[156:159], v[214:217], v[16:19]
	v_mfma_f32_16x16x32_bf16 v[12:15], v[148:151], v[222:225], v[12:15]
	v_mfma_f32_16x16x32_bf16 v[8:11], v[156:159], v[222:225], v[8:11]
	v_mfma_f32_16x16x32_bf16 v[4:7], v[148:151], v[230:233], v[4:7]
	v_mfma_f32_16x16x32_bf16 v[0:3], v[156:159], v[230:233], v[0:3]
	s_setprio 0
	s_barrier
	s_add_i32 s61, 0, 0x18000
	s_add_i32 s62, 0, 0x1c000
	v_add_u32_e32 v140, s61, v200
	v_add_u32_e32 v156, s62, v200
	ds_read_b128 v[128:131], v140
	ds_read_b128 v[132:135], v140 offset:1024
	ds_read_b128 v[136:139], v140 offset:2048
	ds_read_b128 v[140:143], v140 offset:3072
	ds_read_b128 v[144:147], v156
	ds_read_b128 v[148:151], v156 offset:1024
	ds_read_b128 v[152:155], v156 offset:2048
	ds_read_b128 v[156:159], v156 offset:3072
	s_add_u32 s28, s28, 0x40000
	s_addc_u32 s29, s29, 0
	s_mov_b32 m0, s44
	v_lshl_add_u64 v[206:207], s[28:29], 0, v[168:169]
	ds_read_b128 v[160:163], v212 offset:32768
	ds_read_b128 v[164:167], v212 offset:33792
	ds_read_b128 v[194:197], v212 offset:34816
	ds_read_b128 v[214:217], v212 offset:35840
	ds_read_b128 v[218:221], v212 offset:36864
	ds_read_b128 v[222:225], v212 offset:37888
	ds_read_b128 v[226:229], v212 offset:38912
	ds_read_b128 v[230:233], v212 offset:39936
	global_load_lds_dwordx4 v[206:207], off
	v_lshl_add_u64 v[206:207], s[28:29], 0, v[172:173]
	s_mov_b32 m0, s45
	s_nop 0
	global_load_lds_dwordx4 v[206:207], off
	s_waitcnt vmcnt(8)
	s_waitcnt lgkmcnt(0)
	s_barrier
	s_setprio 1
	s_waitcnt lgkmcnt(0)
	v_mfma_f32_16x16x32_bf16 v[124:127], v[128:131], v[160:163], v[124:127]
	v_mfma_f32_16x16x32_bf16 v[120:123], v[136:139], v[160:163], v[120:123]
	v_mfma_f32_16x16x32_bf16 v[116:119], v[128:131], v[194:197], v[116:119]
	v_mfma_f32_16x16x32_bf16 v[112:115], v[136:139], v[194:197], v[112:115]
	v_mfma_f32_16x16x32_bf16 v[108:111], v[128:131], v[218:221], v[108:111]
	v_mfma_f32_16x16x32_bf16 v[104:107], v[136:139], v[218:221], v[104:107]
	v_mfma_f32_16x16x32_bf16 v[100:103], v[128:131], v[226:229], v[100:103]
	v_mfma_f32_16x16x32_bf16 v[96:99], v[136:139], v[226:229], v[96:99]
	v_mfma_f32_16x16x32_bf16 v[124:127], v[132:135], v[164:167], v[124:127]
	v_mfma_f32_16x16x32_bf16 v[120:123], v[140:143], v[164:167], v[120:123]
	v_mfma_f32_16x16x32_bf16 v[116:119], v[132:135], v[214:217], v[116:119]
	v_mfma_f32_16x16x32_bf16 v[112:115], v[140:143], v[214:217], v[112:115]
	v_mfma_f32_16x16x32_bf16 v[108:111], v[132:135], v[222:225], v[108:111]
	v_mfma_f32_16x16x32_bf16 v[104:107], v[140:143], v[222:225], v[104:107]
	v_mfma_f32_16x16x32_bf16 v[100:103], v[132:135], v[230:233], v[100:103]
	v_mfma_f32_16x16x32_bf16 v[96:99], v[140:143], v[230:233], v[96:99]
	v_mfma_f32_16x16x32_bf16 v[60:63], v[144:147], v[160:163], v[60:63]
	v_mfma_f32_16x16x32_bf16 v[56:59], v[152:155], v[160:163], v[56:59]
	v_mfma_f32_16x16x32_bf16 v[52:55], v[144:147], v[194:197], v[52:55]
	v_mfma_f32_16x16x32_bf16 v[48:51], v[152:155], v[194:197], v[48:51]
	v_mfma_f32_16x16x32_bf16 v[44:47], v[144:147], v[218:221], v[44:47]
	v_mfma_f32_16x16x32_bf16 v[40:43], v[152:155], v[218:221], v[40:43]
	v_mfma_f32_16x16x32_bf16 v[36:39], v[144:147], v[226:229], v[36:39]
	v_mfma_f32_16x16x32_bf16 v[32:35], v[152:155], v[226:229], v[32:35]
	v_mfma_f32_16x16x32_bf16 v[60:63], v[148:151], v[164:167], v[60:63]
	v_mfma_f32_16x16x32_bf16 v[56:59], v[156:159], v[164:167], v[56:59]
	v_mfma_f32_16x16x32_bf16 v[52:55], v[148:151], v[214:217], v[52:55]
	v_mfma_f32_16x16x32_bf16 v[48:51], v[156:159], v[214:217], v[48:51]
	v_mfma_f32_16x16x32_bf16 v[44:47], v[148:151], v[222:225], v[44:47]
	v_mfma_f32_16x16x32_bf16 v[40:43], v[156:159], v[222:225], v[40:43]
	v_mfma_f32_16x16x32_bf16 v[36:39], v[148:151], v[230:233], v[36:39]
	v_mfma_f32_16x16x32_bf16 v[32:35], v[156:159], v[230:233], v[32:35]
	s_setprio 0
	s_barrier
	s_add_u32 s28, s26, 0x8000
	s_addc_u32 s29, s27, 0
	s_add_i32 s61, s61, s41
	v_lshl_add_u64 v[206:207], s[28:29], 0, v[170:171]
	s_mov_b32 m0, s61
	ds_read_b128 v[160:163], v212 offset:49152
	ds_read_b128 v[164:167], v212 offset:50176
	ds_read_b128 v[194:197], v212 offset:51200
	ds_read_b128 v[214:217], v212 offset:52224
	ds_read_b128 v[218:221], v212 offset:53248
	ds_read_b128 v[222:225], v212 offset:54272
	ds_read_b128 v[226:229], v212 offset:55296
	ds_read_b128 v[230:233], v212 offset:56320
	global_load_lds_dwordx4 v[206:207], off
	s_add_i32 m0, s61, 0x2000
	s_add_u32 s26, s26, 0xc000
	v_lshl_add_u64 v[206:207], s[28:29], 0, v[174:175]
	s_addc_u32 s27, s27, 0
	s_add_i32 s28, s62, s41
	global_load_lds_dwordx4 v[206:207], off
	v_lshl_add_u64 v[206:207], s[26:27], 0, v[170:171]
	s_mov_b32 m0, s28
	v_lshl_add_u64 v[198:199], v[198:199], 0, s[12:13]
	global_load_lds_dwordx4 v[206:207], off
	v_lshl_add_u64 v[206:207], s[26:27], 0, v[174:175]
	s_add_i32 m0, s28, 0x2000
	s_nop 0
	global_load_lds_dwordx4 v[206:207], off
	s_mov_b32 m0, s50
	s_nop 0
	global_load_lds_dwordx4 v[198:199], off
	v_lshl_add_u64 v[198:199], v[204:205], 0, s[12:13]
	s_mov_b32 m0, s51
	s_nop 0
	global_load_lds_dwordx4 v[198:199], off
	s_waitcnt vmcnt(8)
	s_waitcnt lgkmcnt(0)
	s_barrier
	s_setprio 1
	s_waitcnt lgkmcnt(0)
	v_mfma_f32_16x16x32_bf16 v[92:95], v[128:131], v[160:163], v[92:95]
	v_mfma_f32_16x16x32_bf16 v[88:91], v[136:139], v[160:163], v[88:91]
	v_mfma_f32_16x16x32_bf16 v[84:87], v[128:131], v[194:197], v[84:87]
	v_mfma_f32_16x16x32_bf16 v[80:83], v[136:139], v[194:197], v[80:83]
	v_mfma_f32_16x16x32_bf16 v[76:79], v[128:131], v[218:221], v[76:79]
	v_mfma_f32_16x16x32_bf16 v[72:75], v[136:139], v[218:221], v[72:75]
	v_mfma_f32_16x16x32_bf16 v[68:71], v[128:131], v[226:229], v[68:71]
	v_mfma_f32_16x16x32_bf16 v[64:67], v[136:139], v[226:229], v[64:67]
	v_mfma_f32_16x16x32_bf16 v[92:95], v[132:135], v[164:167], v[92:95]
	v_mfma_f32_16x16x32_bf16 v[88:91], v[140:143], v[164:167], v[88:91]
	v_mfma_f32_16x16x32_bf16 v[84:87], v[132:135], v[214:217], v[84:87]
	v_mfma_f32_16x16x32_bf16 v[80:83], v[140:143], v[214:217], v[80:83]
	v_mfma_f32_16x16x32_bf16 v[76:79], v[132:135], v[222:225], v[76:79]
	v_mfma_f32_16x16x32_bf16 v[72:75], v[140:143], v[222:225], v[72:75]
	v_mfma_f32_16x16x32_bf16 v[68:71], v[132:135], v[230:233], v[68:71]
	v_mfma_f32_16x16x32_bf16 v[64:67], v[140:143], v[230:233], v[64:67]
	v_mfma_f32_16x16x32_bf16 v[28:31], v[144:147], v[160:163], v[28:31]
	v_mfma_f32_16x16x32_bf16 v[24:27], v[152:155], v[160:163], v[24:27]
	v_mfma_f32_16x16x32_bf16 v[20:23], v[144:147], v[194:197], v[20:23]
	v_mfma_f32_16x16x32_bf16 v[16:19], v[152:155], v[194:197], v[16:19]
	v_mfma_f32_16x16x32_bf16 v[12:15], v[144:147], v[218:221], v[12:15]
	v_mfma_f32_16x16x32_bf16 v[8:11], v[152:155], v[218:221], v[8:11]
	v_mfma_f32_16x16x32_bf16 v[4:7], v[144:147], v[226:229], v[4:7]
	v_mfma_f32_16x16x32_bf16 v[0:3], v[152:155], v[226:229], v[0:3]
	v_mfma_f32_16x16x32_bf16 v[28:31], v[148:151], v[164:167], v[28:31]
	v_mfma_f32_16x16x32_bf16 v[24:27], v[156:159], v[164:167], v[24:27]
	v_mfma_f32_16x16x32_bf16 v[20:23], v[148:151], v[214:217], v[20:23]
	v_mfma_f32_16x16x32_bf16 v[16:19], v[156:159], v[214:217], v[16:19]
	v_mfma_f32_16x16x32_bf16 v[12:15], v[148:151], v[222:225], v[12:15]
	v_mfma_f32_16x16x32_bf16 v[8:11], v[156:159], v[222:225], v[8:11]
	v_mfma_f32_16x16x32_bf16 v[4:7], v[148:151], v[230:233], v[4:7]
	v_mfma_f32_16x16x32_bf16 v[0:3], v[156:159], v[230:233], v[0:3]
	s_setprio 0
	s_barrier
	s_add_i32 s35, s35, 2
	s_add_u32 s31, s31, 0x10000
	s_addc_u32 s34, s34, 0
	s_add_u32 s6, s6, 0x100
	s_addc_u32 s7, s7, 0
	s_cmp_gt_u32 s35, 13
	s_cbranch_scc0 .LBB0_1729
	s_and_b64 vcc, exec, s[14:15]
	s_cbranch_vccz .LBB0_1740
	s_barrier
	v_lshl_add_u32 v214, s0, 8, v179
	s_cmp_gt_i32 s2, 4
	s_mov_b64 s[0:1], -1
	s_cbranch_scc1 .LBB0_1741

.LBB0_2258:
	ds_read_b128 v[128:131], v170
	ds_read_b128 v[148:151], v170 offset:1024
	ds_read_b128 v[152:155], v170 offset:2048
	ds_read_b128 v[174:177], v170 offset:3072
	ds_read_b128 v[178:181], v171
	ds_read_b128 v[182:185], v171 offset:1024
	ds_read_b128 v[186:189], v171 offset:2048
	ds_read_b128 v[190:193], v171 offset:3072
	s_add_u32 s30, s28, 0xfffe0080
	s_addc_u32 s31, s29, -1
	s_cmp_eq_u32 s56, 4
	s_cselect_b32 s35, s17, s31
	s_cselect_b32 s34, s52, s30
	s_cselect_b32 s31, s19, s55
	s_cselect_b32 s30, s53, s54
	v_lshl_add_u64 v[204:205], s[28:29], 0, v[142:143]
	s_add_i32 m0, s25, 0xc000
	ds_read_b128 v[194:197], v172
	ds_read_b128 v[198:201], v172 offset:1024
	ds_read_b128 v[210:213], v172 offset:2048
	ds_read_b128 v[214:217], v172 offset:3072
	ds_read_b128 v[218:221], v172 offset:4096
	ds_read_b128 v[222:225], v172 offset:5120
	ds_read_b128 v[226:229], v172 offset:6144
	ds_read_b128 v[230:233], v172 offset:7168
	global_load_lds_dwordx4 v[204:205], off
	v_lshl_add_u64 v[204:205], s[28:29], 0, v[140:141]
	s_add_i32 m0, s25, 0xe000
	s_nop 0
	global_load_lds_dwordx4 v[204:205], off
	s_waitcnt vmcnt(8)
	s_waitcnt lgkmcnt(0)
	s_barrier
	s_setprio 1
	s_waitcnt lgkmcnt(0)
	v_mfma_f32_16x16x32_bf16 v[124:127], v[128:131], v[194:197], v[124:127]
	v_mfma_f32_16x16x32_bf16 v[120:123], v[152:155], v[194:197], v[120:123]
	v_mfma_f32_16x16x32_bf16 v[116:119], v[128:131], v[210:213], v[116:119]
	v_mfma_f32_16x16x32_bf16 v[112:115], v[152:155], v[210:213], v[112:115]
	v_mfma_f32_16x16x32_bf16 v[92:95], v[128:131], v[218:221], v[92:95]
	v_mfma_f32_16x16x32_bf16 v[88:91], v[152:155], v[218:221], v[88:91]
	v_mfma_f32_16x16x32_bf16 v[84:87], v[128:131], v[226:229], v[84:87]
	v_mfma_f32_16x16x32_bf16 v[72:75], v[152:155], v[226:229], v[72:75]
	v_mfma_f32_16x16x32_bf16 v[124:127], v[148:151], v[198:201], v[124:127]
	v_mfma_f32_16x16x32_bf16 v[120:123], v[174:177], v[198:201], v[120:123]
	v_mfma_f32_16x16x32_bf16 v[116:119], v[148:151], v[214:217], v[116:119]
	v_mfma_f32_16x16x32_bf16 v[112:115], v[174:177], v[214:217], v[112:115]
	v_mfma_f32_16x16x32_bf16 v[92:95], v[148:151], v[222:225], v[92:95]
	v_mfma_f32_16x16x32_bf16 v[88:91], v[174:177], v[222:225], v[88:91]
	v_mfma_f32_16x16x32_bf16 v[84:87], v[148:151], v[230:233], v[84:87]
	v_mfma_f32_16x16x32_bf16 v[72:75], v[174:177], v[230:233], v[72:75]
	v_mfma_f32_16x16x32_bf16 v[108:111], v[178:181], v[194:197], v[108:111]
	v_mfma_f32_16x16x32_bf16 v[104:107], v[186:189], v[194:197], v[104:107]
	v_mfma_f32_16x16x32_bf16 v[100:103], v[178:181], v[210:213], v[100:103]
	v_mfma_f32_16x16x32_bf16 v[96:99], v[186:189], v[210:213], v[96:99]
	v_mfma_f32_16x16x32_bf16 v[80:83], v[178:181], v[218:221], v[80:83]
	v_mfma_f32_16x16x32_bf16 v[76:79], v[186:189], v[218:221], v[76:79]
	v_mfma_f32_16x16x32_bf16 v[68:71], v[178:181], v[226:229], v[68:71]
	v_mfma_f32_16x16x32_bf16 v[64:67], v[186:189], v[226:229], v[64:67]
	v_mfma_f32_16x16x32_bf16 v[108:111], v[182:185], v[198:201], v[108:111]
	v_mfma_f32_16x16x32_bf16 v[104:107], v[190:193], v[198:201], v[104:107]
	v_mfma_f32_16x16x32_bf16 v[100:103], v[182:185], v[214:217], v[100:103]
	v_mfma_f32_16x16x32_bf16 v[96:99], v[190:193], v[214:217], v[96:99]
	v_mfma_f32_16x16x32_bf16 v[80:83], v[182:185], v[222:225], v[80:83]
	v_mfma_f32_16x16x32_bf16 v[76:79], v[190:193], v[222:225], v[76:79]
	v_mfma_f32_16x16x32_bf16 v[68:71], v[182:185], v[230:233], v[68:71]
	v_mfma_f32_16x16x32_bf16 v[64:67], v[190:193], v[230:233], v[64:67]
	s_setprio 0
	s_barrier
	s_add_i32 s57, s49, s42
	v_lshl_add_u64 v[204:205], s[30:31], 0, v[134:135]
	s_mov_b32 m0, s57
	ds_read_b128 v[194:197], v172 offset:16384
	ds_read_b128 v[198:201], v172 offset:17408
	ds_read_b128 v[210:213], v172 offset:18432
	ds_read_b128 v[214:217], v172 offset:19456
	ds_read_b128 v[218:221], v172 offset:20480
	ds_read_b128 v[222:225], v172 offset:21504
	ds_read_b128 v[226:229], v172 offset:22528
	ds_read_b128 v[230:233], v172 offset:23552
	global_load_lds_dwordx4 v[204:205], off
	s_add_i32 m0, s57, 0x2000
	s_add_u32 s58, s30, 0x4000
	v_lshl_add_u64 v[204:205], s[30:31], 0, v[138:139]
	s_addc_u32 s59, s31, 0
	s_add_i32 s57, s50, s42
	global_load_lds_dwordx4 v[204:205], off
	v_lshl_add_u64 v[204:205], s[58:59], 0, v[134:135]
	s_mov_b32 m0, s57
	v_lshl_add_u64 v[206:207], s[34:35], 0, v[136:137]
	global_load_lds_dwordx4 v[204:205], off
	v_lshl_add_u64 v[204:205], s[58:59], 0, v[138:139]
	s_add_i32 m0, s57, 0x2000
	s_nop 0
	global_load_lds_dwordx4 v[204:205], off
	v_lshl_add_u64 v[204:205], s[34:35], 0, v[132:133]
	s_mov_b32 m0, s25
	s_nop 0
	global_load_lds_dwordx4 v[204:205], off
	s_mov_b32 m0, s27
	s_nop 0
	global_load_lds_dwordx4 v[206:207], off
	s_waitcnt vmcnt(8)
	s_waitcnt lgkmcnt(0)
	s_barrier
	s_setprio 1
	s_waitcnt lgkmcnt(0)
	v_mfma_f32_16x16x32_bf16 v[60:63], v[128:131], v[194:197], v[60:63]
	v_mfma_f32_16x16x32_bf16 v[56:59], v[152:155], v[194:197], v[56:59]
	v_mfma_f32_16x16x32_bf16 v[48:51], v[128:131], v[210:213], v[48:51]
	v_mfma_f32_16x16x32_bf16 v[40:43], v[152:155], v[210:213], v[40:43]
	v_mfma_f32_16x16x32_bf16 v[32:35], v[128:131], v[218:221], v[32:35]
	v_mfma_f32_16x16x32_bf16 v[24:27], v[152:155], v[218:221], v[24:27]
	v_mfma_f32_16x16x32_bf16 v[16:19], v[128:131], v[226:229], v[16:19]
	v_mfma_f32_16x16x32_bf16 v[8:11], v[152:155], v[226:229], v[8:11]
	v_mfma_f32_16x16x32_bf16 v[60:63], v[148:151], v[198:201], v[60:63]
	v_mfma_f32_16x16x32_bf16 v[56:59], v[174:177], v[198:201], v[56:59]
	v_mfma_f32_16x16x32_bf16 v[48:51], v[148:151], v[214:217], v[48:51]
	v_mfma_f32_16x16x32_bf16 v[40:43], v[174:177], v[214:217], v[40:43]
	v_mfma_f32_16x16x32_bf16 v[32:35], v[148:151], v[222:225], v[32:35]
	v_mfma_f32_16x16x32_bf16 v[24:27], v[174:177], v[222:225], v[24:27]
	v_mfma_f32_16x16x32_bf16 v[16:19], v[148:151], v[230:233], v[16:19]
	v_mfma_f32_16x16x32_bf16 v[8:11], v[174:177], v[230:233], v[8:11]
	v_mfma_f32_16x16x32_bf16 v[52:55], v[178:181], v[194:197], v[52:55]
	v_mfma_f32_16x16x32_bf16 v[44:47], v[186:189], v[194:197], v[44:47]
	v_mfma_f32_16x16x32_bf16 v[36:39], v[178:181], v[210:213], v[36:39]
	v_mfma_f32_16x16x32_bf16 v[28:31], v[186:189], v[210:213], v[28:31]
	v_mfma_f32_16x16x32_bf16 v[20:23], v[178:181], v[218:221], v[20:23]
	v_mfma_f32_16x16x32_bf16 v[12:15], v[186:189], v[218:221], v[12:15]
	v_mfma_f32_16x16x32_bf16 v[4:7], v[178:181], v[226:229], v[4:7]
	v_mfma_f32_16x16x32_bf16 v[0:3], v[186:189], v[226:229], v[0:3]
	v_mfma_f32_16x16x32_bf16 v[52:55], v[182:185], v[198:201], v[52:55]
	v_mfma_f32_16x16x32_bf16 v[44:47], v[190:193], v[198:201], v[44:47]
	v_mfma_f32_16x16x32_bf16 v[36:39], v[182:185], v[214:217], v[36:39]
	v_mfma_f32_16x16x32_bf16 v[28:31], v[190:193], v[214:217], v[28:31]
	v_mfma_f32_16x16x32_bf16 v[20:23], v[182:185], v[222:225], v[20:23]
	v_mfma_f32_16x16x32_bf16 v[12:15], v[190:193], v[222:225], v[12:15]
	v_mfma_f32_16x16x32_bf16 v[4:7], v[182:185], v[230:233], v[4:7]
	v_mfma_f32_16x16x32_bf16 v[0:3], v[190:193], v[230:233], v[0:3]
	s_setprio 0
	s_barrier
	s_add_i32 s57, 0, 0x18000
	v_add_u32_e32 v173, s57, v168
	s_add_i32 s58, 0, 0x1c000
	ds_read_b128 v[128:131], v173
	ds_read_b128 v[148:151], v173 offset:1024
	ds_read_b128 v[152:155], v173 offset:2048
	ds_read_b128 v[174:177], v173 offset:3072
	v_add_u32_e32 v173, s58, v168
	ds_read_b128 v[178:181], v173
	ds_read_b128 v[182:185], v173 offset:1024
	ds_read_b128 v[186:189], v173 offset:2048
	ds_read_b128 v[190:193], v173 offset:3072
	s_add_u32 s34, s34, 0x20000
	s_addc_u32 s35, s35, 0
	s_mov_b32 m0, s43
	v_lshl_add_u64 v[234:235], s[34:35], 0, v[132:133]
	ds_read_b128 v[194:197], v172 offset:32768
	ds_read_b128 v[198:201], v172 offset:33792
	ds_read_b128 v[210:213], v172 offset:34816
	ds_read_b128 v[214:217], v172 offset:35840
	ds_read_b128 v[218:221], v172 offset:36864
	ds_read_b128 v[222:225], v172 offset:37888
	ds_read_b128 v[226:229], v172 offset:38912
	ds_read_b128 v[230:233], v172 offset:39936
	global_load_lds_dwordx4 v[234:235], off
	v_lshl_add_u64 v[234:235], s[34:35], 0, v[136:137]
	s_mov_b32 m0, s44
	s_nop 0
	global_load_lds_dwordx4 v[234:235], off
	s_waitcnt vmcnt(8)
	s_waitcnt lgkmcnt(0)
	s_barrier
	s_setprio 1
	s_waitcnt lgkmcnt(0)
	v_mfma_f32_16x16x32_bf16 v[124:127], v[128:131], v[194:197], v[124:127]
	v_mfma_f32_16x16x32_bf16 v[120:123], v[152:155], v[194:197], v[120:123]
	v_mfma_f32_16x16x32_bf16 v[116:119], v[128:131], v[210:213], v[116:119]
	v_mfma_f32_16x16x32_bf16 v[112:115], v[152:155], v[210:213], v[112:115]
	v_mfma_f32_16x16x32_bf16 v[92:95], v[128:131], v[218:221], v[92:95]
	v_mfma_f32_16x16x32_bf16 v[88:91], v[152:155], v[218:221], v[88:91]
	v_mfma_f32_16x16x32_bf16 v[84:87], v[128:131], v[226:229], v[84:87]
	v_mfma_f32_16x16x32_bf16 v[72:75], v[152:155], v[226:229], v[72:75]
	v_mfma_f32_16x16x32_bf16 v[124:127], v[148:151], v[198:201], v[124:127]
	v_mfma_f32_16x16x32_bf16 v[120:123], v[174:177], v[198:201], v[120:123]
	v_mfma_f32_16x16x32_bf16 v[116:119], v[148:151], v[214:217], v[116:119]
	v_mfma_f32_16x16x32_bf16 v[112:115], v[174:177], v[214:217], v[112:115]
	v_mfma_f32_16x16x32_bf16 v[92:95], v[148:151], v[222:225], v[92:95]
	v_mfma_f32_16x16x32_bf16 v[88:91], v[174:177], v[222:225], v[88:91]
	v_mfma_f32_16x16x32_bf16 v[84:87], v[148:151], v[230:233], v[84:87]
	v_mfma_f32_16x16x32_bf16 v[72:75], v[174:177], v[230:233], v[72:75]
	v_mfma_f32_16x16x32_bf16 v[108:111], v[178:181], v[194:197], v[108:111]
	v_mfma_f32_16x16x32_bf16 v[104:107], v[186:189], v[194:197], v[104:107]
	v_mfma_f32_16x16x32_bf16 v[100:103], v[178:181], v[210:213], v[100:103]
	v_mfma_f32_16x16x32_bf16 v[96:99], v[186:189], v[210:213], v[96:99]
	v_mfma_f32_16x16x32_bf16 v[80:83], v[178:181], v[218:221], v[80:83]
	v_mfma_f32_16x16x32_bf16 v[76:79], v[186:189], v[218:221], v[76:79]
	v_mfma_f32_16x16x32_bf16 v[68:71], v[178:181], v[226:229], v[68:71]
	v_mfma_f32_16x16x32_bf16 v[64:67], v[186:189], v[226:229], v[64:67]
	v_mfma_f32_16x16x32_bf16 v[108:111], v[182:185], v[198:201], v[108:111]
	v_mfma_f32_16x16x32_bf16 v[104:107], v[190:193], v[198:201], v[104:107]
	v_mfma_f32_16x16x32_bf16 v[100:103], v[182:185], v[214:217], v[100:103]
	v_mfma_f32_16x16x32_bf16 v[96:99], v[190:193], v[214:217], v[96:99]
	v_mfma_f32_16x16x32_bf16 v[80:83], v[182:185], v[222:225], v[80:83]
	v_mfma_f32_16x16x32_bf16 v[76:79], v[190:193], v[222:225], v[76:79]
	v_mfma_f32_16x16x32_bf16 v[68:71], v[182:185], v[230:233], v[68:71]
	v_mfma_f32_16x16x32_bf16 v[64:67], v[190:193], v[230:233], v[64:67]
	s_setprio 0
	s_barrier
	s_add_u32 s34, s30, 0x8000
	s_addc_u32 s35, s31, 0
	s_add_i32 s57, s57, s42
	v_lshl_add_u64 v[234:235], s[34:35], 0, v[134:135]
	s_mov_b32 m0, s57
	ds_read_b128 v[194:197], v172 offset:49152
	ds_read_b128 v[198:201], v172 offset:50176
	ds_read_b128 v[210:213], v172 offset:51200
	ds_read_b128 v[214:217], v172 offset:52224
	ds_read_b128 v[218:221], v172 offset:53248
	ds_read_b128 v[222:225], v172 offset:54272
	ds_read_b128 v[226:229], v172 offset:55296
	ds_read_b128 v[230:233], v172 offset:56320
	global_load_lds_dwordx4 v[234:235], off
	s_add_i32 m0, s57, 0x2000
	s_add_u32 s30, s30, 0xc000
	v_lshl_add_u64 v[234:235], s[34:35], 0, v[138:139]
	s_addc_u32 s31, s31, 0
	s_add_i32 s34, s58, s42
	global_load_lds_dwordx4 v[234:235], off
	v_lshl_add_u64 v[234:235], s[30:31], 0, v[134:135]
	s_mov_b32 m0, s34
	v_lshl_add_u64 v[204:205], v[204:205], 0, s[12:13]
	global_load_lds_dwordx4 v[234:235], off
	v_lshl_add_u64 v[234:235], s[30:31], 0, v[138:139]
	s_add_i32 m0, s34, 0x2000
	s_nop 0
	global_load_lds_dwordx4 v[234:235], off
	s_mov_b32 m0, s46
	s_nop 0
	global_load_lds_dwordx4 v[204:205], off
	v_lshl_add_u64 v[204:205], v[206:207], 0, s[12:13]
	s_mov_b32 m0, s47
	s_nop 0
	global_load_lds_dwordx4 v[204:205], off
	s_waitcnt vmcnt(8)
	s_waitcnt lgkmcnt(0)
	s_barrier
	s_setprio 1
	s_waitcnt lgkmcnt(0)
	v_mfma_f32_16x16x32_bf16 v[60:63], v[128:131], v[194:197], v[60:63]
	v_mfma_f32_16x16x32_bf16 v[56:59], v[152:155], v[194:197], v[56:59]
	v_mfma_f32_16x16x32_bf16 v[48:51], v[128:131], v[210:213], v[48:51]
	v_mfma_f32_16x16x32_bf16 v[40:43], v[152:155], v[210:213], v[40:43]
	v_mfma_f32_16x16x32_bf16 v[32:35], v[128:131], v[218:221], v[32:35]
	v_mfma_f32_16x16x32_bf16 v[24:27], v[152:155], v[218:221], v[24:27]
	v_mfma_f32_16x16x32_bf16 v[16:19], v[128:131], v[226:229], v[16:19]
	v_mfma_f32_16x16x32_bf16 v[8:11], v[152:155], v[226:229], v[8:11]
	v_mfma_f32_16x16x32_bf16 v[60:63], v[148:151], v[198:201], v[60:63]
	v_mfma_f32_16x16x32_bf16 v[56:59], v[174:177], v[198:201], v[56:59]
	v_mfma_f32_16x16x32_bf16 v[48:51], v[148:151], v[214:217], v[48:51]
	v_mfma_f32_16x16x32_bf16 v[40:43], v[174:177], v[214:217], v[40:43]
	v_mfma_f32_16x16x32_bf16 v[32:35], v[148:151], v[222:225], v[32:35]
	v_mfma_f32_16x16x32_bf16 v[24:27], v[174:177], v[222:225], v[24:27]
	v_mfma_f32_16x16x32_bf16 v[16:19], v[148:151], v[230:233], v[16:19]
	v_mfma_f32_16x16x32_bf16 v[8:11], v[174:177], v[230:233], v[8:11]
	v_mfma_f32_16x16x32_bf16 v[52:55], v[178:181], v[194:197], v[52:55]
	v_mfma_f32_16x16x32_bf16 v[44:47], v[186:189], v[194:197], v[44:47]
	v_mfma_f32_16x16x32_bf16 v[36:39], v[178:181], v[210:213], v[36:39]
	v_mfma_f32_16x16x32_bf16 v[28:31], v[186:189], v[210:213], v[28:31]
	v_mfma_f32_16x16x32_bf16 v[20:23], v[178:181], v[218:221], v[20:23]
	v_mfma_f32_16x16x32_bf16 v[12:15], v[186:189], v[218:221], v[12:15]
	v_mfma_f32_16x16x32_bf16 v[4:7], v[178:181], v[226:229], v[4:7]
	v_mfma_f32_16x16x32_bf16 v[0:3], v[186:189], v[226:229], v[0:3]
	v_mfma_f32_16x16x32_bf16 v[52:55], v[182:185], v[198:201], v[52:55]
	v_mfma_f32_16x16x32_bf16 v[44:47], v[190:193], v[198:201], v[44:47]
	v_mfma_f32_16x16x32_bf16 v[36:39], v[182:185], v[214:217], v[36:39]
	v_mfma_f32_16x16x32_bf16 v[28:31], v[190:193], v[214:217], v[28:31]
	v_mfma_f32_16x16x32_bf16 v[20:23], v[182:185], v[222:225], v[20:23]
	v_mfma_f32_16x16x32_bf16 v[12:15], v[190:193], v[222:225], v[12:15]
	v_mfma_f32_16x16x32_bf16 v[4:7], v[182:185], v[230:233], v[4:7]
	v_mfma_f32_16x16x32_bf16 v[0:3], v[190:193], v[230:233], v[0:3]
	s_setprio 0
	s_barrier
	s_add_i32 s56, s56, 2
	s_add_u32 s54, s54, 0x10000
	s_addc_u32 s55, s55, 0
	s_add_u32 s28, s28, 0x100
	s_addc_u32 s29, s29, 0
	s_cmp_gt_u32 s56, 5
	s_cbranch_scc0 .LBB0_2258
	s_and_b64 vcc, exec, s[14:15]
	s_cbranch_vccz .LBB0_2261
	s_barrier

.LBB0_2282:
	ds_read_b128 v[144:147], v155
	ds_read_b128 v[148:151], v155 offset:1024
	ds_read_b128 v[158:161], v155 offset:2048
	ds_read_b128 v[162:165], v155 offset:3072
	ds_read_b128 v[166:169], v156
	ds_read_b128 v[170:173], v156 offset:1024
	ds_read_b128 v[174:177], v156 offset:2048
	ds_read_b128 v[178:181], v156 offset:3072
	s_add_u32 s28, s26, 0xfffe0080
	s_addc_u32 s29, s27, -1
	s_cmp_eq_u32 s54, 4
	s_cselect_b32 s31, s15, s29
	s_cselect_b32 s30, s50, s28
	s_cselect_b32 s29, s17, s53
	s_cselect_b32 s28, s51, s52
	v_lshl_add_u64 v[204:205], s[26:27], 0, v[130:131]
	s_add_i32 m0, s23, 0xc000
	ds_read_b128 v[182:185], v157
	ds_read_b128 v[186:189], v157 offset:1024
	ds_read_b128 v[190:193], v157 offset:2048
	ds_read_b128 v[194:197], v157 offset:3072
	ds_read_b128 v[198:201], v157 offset:4096
	ds_read_b128 v[210:213], v157 offset:5120
	ds_read_b128 v[214:217], v157 offset:6144
	ds_read_b128 v[218:221], v157 offset:7168
	global_load_lds_dwordx4 v[204:205], off
	v_lshl_add_u64 v[204:205], s[26:27], 0, v[128:129]
	s_add_i32 m0, s23, 0xe000
	s_nop 0
	global_load_lds_dwordx4 v[204:205], off
	s_waitcnt vmcnt(8)
	s_waitcnt lgkmcnt(0)
	s_barrier
	s_setprio 1
	s_waitcnt lgkmcnt(0)
	v_mfma_f32_16x16x32_bf16 v[124:127], v[144:147], v[182:185], v[124:127]
	v_mfma_f32_16x16x32_bf16 v[120:123], v[158:161], v[182:185], v[120:123]
	v_mfma_f32_16x16x32_bf16 v[112:115], v[144:147], v[190:193], v[112:115]
	v_mfma_f32_16x16x32_bf16 v[104:107], v[158:161], v[190:193], v[104:107]
	v_mfma_f32_16x16x32_bf16 v[92:95], v[144:147], v[198:201], v[92:95]
	v_mfma_f32_16x16x32_bf16 v[88:91], v[158:161], v[198:201], v[88:91]
	v_mfma_f32_16x16x32_bf16 v[80:83], v[144:147], v[214:217], v[80:83]
	v_mfma_f32_16x16x32_bf16 v[72:75], v[158:161], v[214:217], v[72:75]
	v_mfma_f32_16x16x32_bf16 v[124:127], v[148:151], v[186:189], v[124:127]
	v_mfma_f32_16x16x32_bf16 v[120:123], v[162:165], v[186:189], v[120:123]
	v_mfma_f32_16x16x32_bf16 v[112:115], v[148:151], v[194:197], v[112:115]
	v_mfma_f32_16x16x32_bf16 v[104:107], v[162:165], v[194:197], v[104:107]
	v_mfma_f32_16x16x32_bf16 v[92:95], v[148:151], v[210:213], v[92:95]
	v_mfma_f32_16x16x32_bf16 v[88:91], v[162:165], v[210:213], v[88:91]
	v_mfma_f32_16x16x32_bf16 v[80:83], v[148:151], v[218:221], v[80:83]
	v_mfma_f32_16x16x32_bf16 v[72:75], v[162:165], v[218:221], v[72:75]
	v_mfma_f32_16x16x32_bf16 v[116:119], v[166:169], v[182:185], v[116:119]
	v_mfma_f32_16x16x32_bf16 v[108:111], v[174:177], v[182:185], v[108:111]
	v_mfma_f32_16x16x32_bf16 v[100:103], v[166:169], v[190:193], v[100:103]
	v_mfma_f32_16x16x32_bf16 v[96:99], v[174:177], v[190:193], v[96:99]
	v_mfma_f32_16x16x32_bf16 v[84:87], v[166:169], v[198:201], v[84:87]
	v_mfma_f32_16x16x32_bf16 v[76:79], v[174:177], v[198:201], v[76:79]
	v_mfma_f32_16x16x32_bf16 v[68:71], v[166:169], v[214:217], v[68:71]
	v_mfma_f32_16x16x32_bf16 v[64:67], v[174:177], v[214:217], v[64:67]
	v_mfma_f32_16x16x32_bf16 v[116:119], v[170:173], v[186:189], v[116:119]
	v_mfma_f32_16x16x32_bf16 v[108:111], v[178:181], v[186:189], v[108:111]
	v_mfma_f32_16x16x32_bf16 v[100:103], v[170:173], v[194:197], v[100:103]
	v_mfma_f32_16x16x32_bf16 v[96:99], v[178:181], v[194:197], v[96:99]
	v_mfma_f32_16x16x32_bf16 v[84:87], v[170:173], v[210:213], v[84:87]
	v_mfma_f32_16x16x32_bf16 v[76:79], v[178:181], v[210:213], v[76:79]
	v_mfma_f32_16x16x32_bf16 v[68:71], v[170:173], v[218:221], v[68:71]
	v_mfma_f32_16x16x32_bf16 v[64:67], v[178:181], v[218:221], v[64:67]
	s_setprio 0
	s_barrier
	s_add_i32 s55, s47, s40
	v_lshl_add_u64 v[204:205], s[28:29], 0, v[134:135]
	s_mov_b32 m0, s55
	ds_read_b128 v[182:185], v157 offset:16384
	ds_read_b128 v[186:189], v157 offset:17408
	ds_read_b128 v[190:193], v157 offset:18432
	ds_read_b128 v[194:197], v157 offset:19456
	ds_read_b128 v[198:201], v157 offset:20480
	ds_read_b128 v[210:213], v157 offset:21504
	ds_read_b128 v[214:217], v157 offset:22528
	ds_read_b128 v[218:221], v157 offset:23552
	global_load_lds_dwordx4 v[204:205], off
	s_add_i32 m0, s55, 0x2000
	s_add_u32 s56, s28, 0x4000
	v_lshl_add_u64 v[204:205], s[28:29], 0, v[138:139]
	s_addc_u32 s57, s29, 0
	s_add_i32 s55, s48, s40
	global_load_lds_dwordx4 v[204:205], off
	v_lshl_add_u64 v[204:205], s[56:57], 0, v[134:135]
	s_mov_b32 m0, s55
	v_lshl_add_u64 v[206:207], s[30:31], 0, v[136:137]
	global_load_lds_dwordx4 v[204:205], off
	v_lshl_add_u64 v[204:205], s[56:57], 0, v[138:139]
	s_add_i32 m0, s55, 0x2000
	s_nop 0
	global_load_lds_dwordx4 v[204:205], off
	v_lshl_add_u64 v[204:205], s[30:31], 0, v[132:133]
	s_mov_b32 m0, s23
	s_nop 0
	global_load_lds_dwordx4 v[204:205], off
	s_mov_b32 m0, s25
	s_nop 0
	global_load_lds_dwordx4 v[206:207], off
	s_waitcnt vmcnt(8)
	s_waitcnt lgkmcnt(0)
	s_barrier
	s_setprio 1
	s_waitcnt lgkmcnt(0)
	v_mfma_f32_16x16x32_bf16 v[60:63], v[144:147], v[182:185], v[60:63]
	v_mfma_f32_16x16x32_bf16 v[56:59], v[158:161], v[182:185], v[56:59]
	v_mfma_f32_16x16x32_bf16 v[48:51], v[144:147], v[190:193], v[48:51]
	v_mfma_f32_16x16x32_bf16 v[40:43], v[158:161], v[190:193], v[40:43]
	v_mfma_f32_16x16x32_bf16 v[28:31], v[144:147], v[198:201], v[28:31]
	v_mfma_f32_16x16x32_bf16 v[24:27], v[158:161], v[198:201], v[24:27]
	v_mfma_f32_16x16x32_bf16 v[16:19], v[144:147], v[214:217], v[16:19]
	v_mfma_f32_16x16x32_bf16 v[8:11], v[158:161], v[214:217], v[8:11]
	v_mfma_f32_16x16x32_bf16 v[60:63], v[148:151], v[186:189], v[60:63]
	v_mfma_f32_16x16x32_bf16 v[56:59], v[162:165], v[186:189], v[56:59]
	v_mfma_f32_16x16x32_bf16 v[48:51], v[148:151], v[194:197], v[48:51]
	v_mfma_f32_16x16x32_bf16 v[40:43], v[162:165], v[194:197], v[40:43]
	v_mfma_f32_16x16x32_bf16 v[28:31], v[148:151], v[210:213], v[28:31]
	v_mfma_f32_16x16x32_bf16 v[24:27], v[162:165], v[210:213], v[24:27]
	v_mfma_f32_16x16x32_bf16 v[16:19], v[148:151], v[218:221], v[16:19]
	v_mfma_f32_16x16x32_bf16 v[8:11], v[162:165], v[218:221], v[8:11]
	v_mfma_f32_16x16x32_bf16 v[52:55], v[166:169], v[182:185], v[52:55]
	v_mfma_f32_16x16x32_bf16 v[44:47], v[174:177], v[182:185], v[44:47]
	v_mfma_f32_16x16x32_bf16 v[36:39], v[166:169], v[190:193], v[36:39]
	v_mfma_f32_16x16x32_bf16 v[32:35], v[174:177], v[190:193], v[32:35]
	v_mfma_f32_16x16x32_bf16 v[20:23], v[166:169], v[198:201], v[20:23]
	v_mfma_f32_16x16x32_bf16 v[12:15], v[174:177], v[198:201], v[12:15]
	v_mfma_f32_16x16x32_bf16 v[4:7], v[166:169], v[214:217], v[4:7]
	v_mfma_f32_16x16x32_bf16 v[0:3], v[174:177], v[214:217], v[0:3]
	v_mfma_f32_16x16x32_bf16 v[52:55], v[170:173], v[186:189], v[52:55]
	v_mfma_f32_16x16x32_bf16 v[44:47], v[178:181], v[186:189], v[44:47]
	v_mfma_f32_16x16x32_bf16 v[36:39], v[170:173], v[194:197], v[36:39]
	v_mfma_f32_16x16x32_bf16 v[32:35], v[178:181], v[194:197], v[32:35]
	v_mfma_f32_16x16x32_bf16 v[20:23], v[170:173], v[210:213], v[20:23]
	v_mfma_f32_16x16x32_bf16 v[12:15], v[178:181], v[210:213], v[12:15]
	v_mfma_f32_16x16x32_bf16 v[4:7], v[170:173], v[218:221], v[4:7]
	v_mfma_f32_16x16x32_bf16 v[0:3], v[178:181], v[218:221], v[0:3]
	s_setprio 0
	s_barrier
	s_add_i32 s55, 0, 0x18000
	s_add_i32 s56, 0, 0x1c000
	v_add_u32_e32 v162, s55, v153
	v_add_u32_e32 v178, s56, v153
	ds_read_b128 v[144:147], v162
	ds_read_b128 v[148:151], v162 offset:1024
	ds_read_b128 v[158:161], v162 offset:2048
	ds_read_b128 v[162:165], v162 offset:3072
	ds_read_b128 v[166:169], v178
	ds_read_b128 v[170:173], v178 offset:1024
	ds_read_b128 v[174:177], v178 offset:2048
	ds_read_b128 v[178:181], v178 offset:3072
	s_add_u32 s30, s30, 0x20000
	s_addc_u32 s31, s31, 0
	s_mov_b32 m0, s41
	v_lshl_add_u64 v[222:223], s[30:31], 0, v[132:133]
	ds_read_b128 v[182:185], v157 offset:32768
	ds_read_b128 v[186:189], v157 offset:33792
	ds_read_b128 v[190:193], v157 offset:34816
	ds_read_b128 v[194:197], v157 offset:35840
	ds_read_b128 v[198:201], v157 offset:36864
	ds_read_b128 v[210:213], v157 offset:37888
	ds_read_b128 v[214:217], v157 offset:38912
	ds_read_b128 v[218:221], v157 offset:39936
	global_load_lds_dwordx4 v[222:223], off
	v_lshl_add_u64 v[222:223], s[30:31], 0, v[136:137]
	s_mov_b32 m0, s42
	s_nop 0
	global_load_lds_dwordx4 v[222:223], off
	s_waitcnt vmcnt(8)
	s_waitcnt lgkmcnt(0)
	s_barrier
	s_setprio 1
	s_waitcnt lgkmcnt(0)
	v_mfma_f32_16x16x32_bf16 v[124:127], v[144:147], v[182:185], v[124:127]
	v_mfma_f32_16x16x32_bf16 v[120:123], v[158:161], v[182:185], v[120:123]
	v_mfma_f32_16x16x32_bf16 v[112:115], v[144:147], v[190:193], v[112:115]
	v_mfma_f32_16x16x32_bf16 v[104:107], v[158:161], v[190:193], v[104:107]
	v_mfma_f32_16x16x32_bf16 v[92:95], v[144:147], v[198:201], v[92:95]
	v_mfma_f32_16x16x32_bf16 v[88:91], v[158:161], v[198:201], v[88:91]
	v_mfma_f32_16x16x32_bf16 v[80:83], v[144:147], v[214:217], v[80:83]
	v_mfma_f32_16x16x32_bf16 v[72:75], v[158:161], v[214:217], v[72:75]
	v_mfma_f32_16x16x32_bf16 v[124:127], v[148:151], v[186:189], v[124:127]
	v_mfma_f32_16x16x32_bf16 v[120:123], v[162:165], v[186:189], v[120:123]
	v_mfma_f32_16x16x32_bf16 v[112:115], v[148:151], v[194:197], v[112:115]
	v_mfma_f32_16x16x32_bf16 v[104:107], v[162:165], v[194:197], v[104:107]
	v_mfma_f32_16x16x32_bf16 v[92:95], v[148:151], v[210:213], v[92:95]
	v_mfma_f32_16x16x32_bf16 v[88:91], v[162:165], v[210:213], v[88:91]
	v_mfma_f32_16x16x32_bf16 v[80:83], v[148:151], v[218:221], v[80:83]
	v_mfma_f32_16x16x32_bf16 v[72:75], v[162:165], v[218:221], v[72:75]
	v_mfma_f32_16x16x32_bf16 v[116:119], v[166:169], v[182:185], v[116:119]
	v_mfma_f32_16x16x32_bf16 v[108:111], v[174:177], v[182:185], v[108:111]
	v_mfma_f32_16x16x32_bf16 v[100:103], v[166:169], v[190:193], v[100:103]
	v_mfma_f32_16x16x32_bf16 v[96:99], v[174:177], v[190:193], v[96:99]
	v_mfma_f32_16x16x32_bf16 v[84:87], v[166:169], v[198:201], v[84:87]
	v_mfma_f32_16x16x32_bf16 v[76:79], v[174:177], v[198:201], v[76:79]
	v_mfma_f32_16x16x32_bf16 v[68:71], v[166:169], v[214:217], v[68:71]
	v_mfma_f32_16x16x32_bf16 v[64:67], v[174:177], v[214:217], v[64:67]
	v_mfma_f32_16x16x32_bf16 v[116:119], v[170:173], v[186:189], v[116:119]
	v_mfma_f32_16x16x32_bf16 v[108:111], v[178:181], v[186:189], v[108:111]
	v_mfma_f32_16x16x32_bf16 v[100:103], v[170:173], v[194:197], v[100:103]
	v_mfma_f32_16x16x32_bf16 v[96:99], v[178:181], v[194:197], v[96:99]
	v_mfma_f32_16x16x32_bf16 v[84:87], v[170:173], v[210:213], v[84:87]
	v_mfma_f32_16x16x32_bf16 v[76:79], v[178:181], v[210:213], v[76:79]
	v_mfma_f32_16x16x32_bf16 v[68:71], v[170:173], v[218:221], v[68:71]
	v_mfma_f32_16x16x32_bf16 v[64:67], v[178:181], v[218:221], v[64:67]
	s_setprio 0
	s_barrier
	s_add_u32 s30, s28, 0x8000
	s_addc_u32 s31, s29, 0
	s_add_i32 s55, s55, s40
	v_lshl_add_u64 v[222:223], s[30:31], 0, v[134:135]
	s_mov_b32 m0, s55
	ds_read_b128 v[182:185], v157 offset:49152
	ds_read_b128 v[186:189], v157 offset:50176
	ds_read_b128 v[190:193], v157 offset:51200
	ds_read_b128 v[194:197], v157 offset:52224
	ds_read_b128 v[198:201], v157 offset:53248
	ds_read_b128 v[210:213], v157 offset:54272
	ds_read_b128 v[214:217], v157 offset:55296
	ds_read_b128 v[218:221], v157 offset:56320
	global_load_lds_dwordx4 v[222:223], off
	s_add_i32 m0, s55, 0x2000
	s_add_u32 s28, s28, 0xc000
	v_lshl_add_u64 v[222:223], s[30:31], 0, v[138:139]
	s_addc_u32 s29, s29, 0
	s_add_i32 s30, s56, s40
	global_load_lds_dwordx4 v[222:223], off
	v_lshl_add_u64 v[222:223], s[28:29], 0, v[134:135]
	s_mov_b32 m0, s30
	v_lshl_add_u64 v[204:205], v[204:205], 0, s[8:9]
	global_load_lds_dwordx4 v[222:223], off
	v_lshl_add_u64 v[222:223], s[28:29], 0, v[138:139]
	s_add_i32 m0, s30, 0x2000
	s_nop 0
	global_load_lds_dwordx4 v[222:223], off
	s_mov_b32 m0, s44
	s_nop 0
	global_load_lds_dwordx4 v[204:205], off
	v_lshl_add_u64 v[204:205], v[206:207], 0, s[8:9]
	s_mov_b32 m0, s45
	s_nop 0
	global_load_lds_dwordx4 v[204:205], off
	s_waitcnt vmcnt(8)
	s_waitcnt lgkmcnt(0)
	s_barrier
	s_setprio 1
	s_waitcnt lgkmcnt(0)
	v_mfma_f32_16x16x32_bf16 v[60:63], v[144:147], v[182:185], v[60:63]
	v_mfma_f32_16x16x32_bf16 v[56:59], v[158:161], v[182:185], v[56:59]
	v_mfma_f32_16x16x32_bf16 v[48:51], v[144:147], v[190:193], v[48:51]
	v_mfma_f32_16x16x32_bf16 v[40:43], v[158:161], v[190:193], v[40:43]
	v_mfma_f32_16x16x32_bf16 v[28:31], v[144:147], v[198:201], v[28:31]
	v_mfma_f32_16x16x32_bf16 v[24:27], v[158:161], v[198:201], v[24:27]
	v_mfma_f32_16x16x32_bf16 v[16:19], v[144:147], v[214:217], v[16:19]
	v_mfma_f32_16x16x32_bf16 v[8:11], v[158:161], v[214:217], v[8:11]
	v_mfma_f32_16x16x32_bf16 v[60:63], v[148:151], v[186:189], v[60:63]
	v_mfma_f32_16x16x32_bf16 v[56:59], v[162:165], v[186:189], v[56:59]
	v_mfma_f32_16x16x32_bf16 v[48:51], v[148:151], v[194:197], v[48:51]
	v_mfma_f32_16x16x32_bf16 v[40:43], v[162:165], v[194:197], v[40:43]
	v_mfma_f32_16x16x32_bf16 v[28:31], v[148:151], v[210:213], v[28:31]
	v_mfma_f32_16x16x32_bf16 v[24:27], v[162:165], v[210:213], v[24:27]
	v_mfma_f32_16x16x32_bf16 v[16:19], v[148:151], v[218:221], v[16:19]
	v_mfma_f32_16x16x32_bf16 v[8:11], v[162:165], v[218:221], v[8:11]
	v_mfma_f32_16x16x32_bf16 v[52:55], v[166:169], v[182:185], v[52:55]
	v_mfma_f32_16x16x32_bf16 v[44:47], v[174:177], v[182:185], v[44:47]
	v_mfma_f32_16x16x32_bf16 v[36:39], v[166:169], v[190:193], v[36:39]
	v_mfma_f32_16x16x32_bf16 v[32:35], v[174:177], v[190:193], v[32:35]
	v_mfma_f32_16x16x32_bf16 v[20:23], v[166:169], v[198:201], v[20:23]
	v_mfma_f32_16x16x32_bf16 v[12:15], v[174:177], v[198:201], v[12:15]
	v_mfma_f32_16x16x32_bf16 v[4:7], v[166:169], v[214:217], v[4:7]
	v_mfma_f32_16x16x32_bf16 v[0:3], v[174:177], v[214:217], v[0:3]
	v_mfma_f32_16x16x32_bf16 v[52:55], v[170:173], v[186:189], v[52:55]
	v_mfma_f32_16x16x32_bf16 v[44:47], v[178:181], v[186:189], v[44:47]
	v_mfma_f32_16x16x32_bf16 v[36:39], v[170:173], v[194:197], v[36:39]
	v_mfma_f32_16x16x32_bf16 v[32:35], v[178:181], v[194:197], v[32:35]
	v_mfma_f32_16x16x32_bf16 v[20:23], v[170:173], v[210:213], v[20:23]
	v_mfma_f32_16x16x32_bf16 v[12:15], v[178:181], v[210:213], v[12:15]
	v_mfma_f32_16x16x32_bf16 v[4:7], v[170:173], v[218:221], v[4:7]
	v_mfma_f32_16x16x32_bf16 v[0:3], v[178:181], v[218:221], v[0:3]
	s_setprio 0
	s_barrier
	s_add_i32 s54, s54, 2
	s_add_u32 s52, s52, 0x10000
	s_addc_u32 s53, s53, 0
	s_add_u32 s26, s26, 0x100
	s_addc_u32 s27, s27, 0
	s_cmp_gt_u32 s54, 5
	s_cbranch_scc0 .LBB0_2282
	s_and_b64 vcc, exec, s[10:11]
	s_cbranch_vccz .LBB0_2285
	s_barrier

.LBB0_2358:
	v_add_u32_e32 v168, s77, v182
	v_add_u32_e32 v204, s78, v182
	ds_read_b128 v[156:159], v168
	ds_read_b128 v[160:163], v168 offset:1024
	ds_read_b128 v[164:167], v168 offset:2048
	ds_read_b128 v[168:171], v168 offset:3072
	ds_read_b128 v[172:175], v204
	ds_read_b128 v[176:179], v204 offset:1024
	ds_read_b128 v[212:215], v204 offset:2048
	ds_read_b128 v[216:219], v204 offset:3072
	s_add_u32 s48, s46, 0xfffc0080
	s_addc_u32 s49, s47, -1
	s_cmp_eq_u32 s54, 12
	s_cselect_b32 s51, s35, s49
	s_cselect_b32 s50, s43, s48
	s_cselect_b32 s49, s37, s53
	s_cselect_b32 s48, s45, s52
	v_lshl_add_u64 v[204:205], s[46:47], 0, v[154:155]
	s_add_i32 m0, s65, 0xc000
	ds_read_b128 v[220:223], v199
	ds_read_b128 v[224:227], v199 offset:1024
	ds_read_b128 v[228:231], v199 offset:2048
	ds_read_b128 v[232:235], v199 offset:3072
	ds_read_b128 v[236:239], v199 offset:4096
	ds_read_b128 v[240:243], v199 offset:5120
	ds_read_b128 v[244:247], v199 offset:6144
	ds_read_b128 v[248:251], v199 offset:7168
	global_load_lds_dwordx4 v[204:205], off
	v_lshl_add_u64 v[204:205], s[46:47], 0, v[152:153]
	s_add_i32 m0, s65, 0xe000
	s_nop 0
	global_load_lds_dwordx4 v[204:205], off
	s_waitcnt vmcnt(8)
	s_waitcnt lgkmcnt(0)
	s_barrier
	s_setprio 1
	s_waitcnt lgkmcnt(0)
	v_mfma_f32_16x16x32_bf16 v[124:127], v[156:159], v[220:223], v[124:127]
	v_mfma_f32_16x16x32_bf16 v[120:123], v[164:167], v[220:223], v[120:123]
	v_mfma_f32_16x16x32_bf16 v[116:119], v[156:159], v[228:231], v[116:119]
	v_mfma_f32_16x16x32_bf16 v[112:115], v[164:167], v[228:231], v[112:115]
	v_mfma_f32_16x16x32_bf16 v[92:95], v[156:159], v[236:239], v[92:95]
	v_mfma_f32_16x16x32_bf16 v[88:91], v[164:167], v[236:239], v[88:91]
	v_mfma_f32_16x16x32_bf16 v[84:87], v[156:159], v[244:247], v[84:87]
	v_mfma_f32_16x16x32_bf16 v[80:83], v[164:167], v[244:247], v[80:83]
	v_mfma_f32_16x16x32_bf16 v[124:127], v[160:163], v[224:227], v[124:127]
	v_mfma_f32_16x16x32_bf16 v[120:123], v[168:171], v[224:227], v[120:123]
	v_mfma_f32_16x16x32_bf16 v[116:119], v[160:163], v[232:235], v[116:119]
	v_mfma_f32_16x16x32_bf16 v[112:115], v[168:171], v[232:235], v[112:115]
	v_mfma_f32_16x16x32_bf16 v[92:95], v[160:163], v[240:243], v[92:95]
	v_mfma_f32_16x16x32_bf16 v[88:91], v[168:171], v[240:243], v[88:91]
	v_mfma_f32_16x16x32_bf16 v[84:87], v[160:163], v[248:251], v[84:87]
	v_mfma_f32_16x16x32_bf16 v[80:83], v[168:171], v[248:251], v[80:83]
	v_mfma_f32_16x16x32_bf16 v[108:111], v[172:175], v[220:223], v[108:111]
	v_mfma_f32_16x16x32_bf16 v[104:107], v[212:215], v[220:223], v[104:107]
	v_mfma_f32_16x16x32_bf16 v[100:103], v[172:175], v[228:231], v[100:103]
	v_mfma_f32_16x16x32_bf16 v[96:99], v[212:215], v[228:231], v[96:99]
	v_mfma_f32_16x16x32_bf16 v[76:79], v[172:175], v[236:239], v[76:79]
	v_mfma_f32_16x16x32_bf16 v[72:75], v[212:215], v[236:239], v[72:75]
	v_mfma_f32_16x16x32_bf16 v[68:71], v[172:175], v[244:247], v[68:71]
	v_mfma_f32_16x16x32_bf16 v[64:67], v[212:215], v[244:247], v[64:67]
	v_mfma_f32_16x16x32_bf16 v[108:111], v[176:179], v[224:227], v[108:111]
	v_mfma_f32_16x16x32_bf16 v[104:107], v[216:219], v[224:227], v[104:107]
	v_mfma_f32_16x16x32_bf16 v[100:103], v[176:179], v[232:235], v[100:103]
	v_mfma_f32_16x16x32_bf16 v[96:99], v[216:219], v[232:235], v[96:99]
	v_mfma_f32_16x16x32_bf16 v[76:79], v[176:179], v[240:243], v[76:79]
	v_mfma_f32_16x16x32_bf16 v[72:75], v[216:219], v[240:243], v[72:75]
	v_mfma_f32_16x16x32_bf16 v[68:71], v[176:179], v[248:251], v[68:71]
	v_mfma_f32_16x16x32_bf16 v[64:67], v[216:219], v[248:251], v[64:67]
	s_setprio 0
	s_barrier
	s_add_i32 s55, s77, s64
	v_lshl_add_u64 v[204:205], s[48:49], 0, v[130:131]
	s_mov_b32 m0, s55
	ds_read_b128 v[220:223], v199 offset:16384
	ds_read_b128 v[224:227], v199 offset:17408
	ds_read_b128 v[228:231], v199 offset:18432
	ds_read_b128 v[232:235], v199 offset:19456
	ds_read_b128 v[236:239], v199 offset:20480
	ds_read_b128 v[240:243], v199 offset:21504
	ds_read_b128 v[244:247], v199 offset:22528
	ds_read_b128 v[248:251], v199 offset:23552
	global_load_lds_dwordx4 v[204:205], off
	s_add_i32 m0, s55, 0x2000
	s_add_u32 s56, s48, 0x4000
	v_lshl_add_u64 v[204:205], s[48:49], 0, v[134:135]
	s_addc_u32 s57, s49, 0
	s_add_i32 s55, s78, s64
	global_load_lds_dwordx4 v[204:205], off
	v_lshl_add_u64 v[204:205], s[56:57], 0, v[130:131]
	s_mov_b32 m0, s55
	v_lshl_add_u64 v[206:207], s[50:51], 0, v[132:133]
	global_load_lds_dwordx4 v[204:205], off
	v_lshl_add_u64 v[204:205], s[56:57], 0, v[134:135]
	s_add_i32 m0, s55, 0x2000
	s_nop 0
	global_load_lds_dwordx4 v[204:205], off
	v_lshl_add_u64 v[204:205], s[50:51], 0, v[128:129]
	s_mov_b32 m0, s65
	s_nop 0
	global_load_lds_dwordx4 v[204:205], off
	s_mov_b32 m0, s66
	s_nop 0
	global_load_lds_dwordx4 v[206:207], off
	s_waitcnt vmcnt(8)
	s_waitcnt lgkmcnt(0)
	s_barrier
	s_setprio 1
	s_waitcnt lgkmcnt(0)
	v_mfma_f32_16x16x32_bf16 v[60:63], v[156:159], v[220:223], v[60:63]
	v_mfma_f32_16x16x32_bf16 v[56:59], v[164:167], v[220:223], v[56:59]
	v_mfma_f32_16x16x32_bf16 v[52:55], v[156:159], v[228:231], v[52:55]
	v_mfma_f32_16x16x32_bf16 v[48:51], v[164:167], v[228:231], v[48:51]
	v_mfma_f32_16x16x32_bf16 v[28:31], v[156:159], v[236:239], v[28:31]
	v_mfma_f32_16x16x32_bf16 v[24:27], v[164:167], v[236:239], v[24:27]
	v_mfma_f32_16x16x32_bf16 v[20:23], v[156:159], v[244:247], v[20:23]
	v_mfma_f32_16x16x32_bf16 v[12:15], v[164:167], v[244:247], v[12:15]
	v_mfma_f32_16x16x32_bf16 v[60:63], v[160:163], v[224:227], v[60:63]
	v_mfma_f32_16x16x32_bf16 v[56:59], v[168:171], v[224:227], v[56:59]
	v_mfma_f32_16x16x32_bf16 v[52:55], v[160:163], v[232:235], v[52:55]
	v_mfma_f32_16x16x32_bf16 v[48:51], v[168:171], v[232:235], v[48:51]
	v_mfma_f32_16x16x32_bf16 v[28:31], v[160:163], v[240:243], v[28:31]
	v_mfma_f32_16x16x32_bf16 v[24:27], v[168:171], v[240:243], v[24:27]
	v_mfma_f32_16x16x32_bf16 v[20:23], v[160:163], v[248:251], v[20:23]
	v_mfma_f32_16x16x32_bf16 v[12:15], v[168:171], v[248:251], v[12:15]
	v_mfma_f32_16x16x32_bf16 v[44:47], v[172:175], v[220:223], v[44:47]
	v_mfma_f32_16x16x32_bf16 v[40:43], v[212:215], v[220:223], v[40:43]
	v_mfma_f32_16x16x32_bf16 v[36:39], v[172:175], v[228:231], v[36:39]
	v_mfma_f32_16x16x32_bf16 v[32:35], v[212:215], v[228:231], v[32:35]
	v_mfma_f32_16x16x32_bf16 v[16:19], v[172:175], v[236:239], v[16:19]
	v_mfma_f32_16x16x32_bf16 v[8:11], v[212:215], v[236:239], v[8:11]
	v_mfma_f32_16x16x32_bf16 v[4:7], v[172:175], v[244:247], v[4:7]
	v_mfma_f32_16x16x32_bf16 v[0:3], v[212:215], v[244:247], v[0:3]
	v_mfma_f32_16x16x32_bf16 v[44:47], v[176:179], v[224:227], v[44:47]
	v_mfma_f32_16x16x32_bf16 v[40:43], v[216:219], v[224:227], v[40:43]
	v_mfma_f32_16x16x32_bf16 v[36:39], v[176:179], v[232:235], v[36:39]
	v_mfma_f32_16x16x32_bf16 v[32:35], v[216:219], v[232:235], v[32:35]
	v_mfma_f32_16x16x32_bf16 v[16:19], v[176:179], v[240:243], v[16:19]
	v_mfma_f32_16x16x32_bf16 v[8:11], v[216:219], v[240:243], v[8:11]
	v_mfma_f32_16x16x32_bf16 v[4:7], v[176:179], v[248:251], v[4:7]
	v_mfma_f32_16x16x32_bf16 v[0:3], v[216:219], v[248:251], v[0:3]
	s_setprio 0
	s_barrier
	s_add_i32 s55, 0, 0x18000
	s_add_i32 s56, 0, 0x1c000
	v_add_u32_e32 v168, s55, v182
	v_add_u32_e32 v216, s56, v182
	ds_read_b128 v[156:159], v168
	ds_read_b128 v[160:163], v168 offset:1024
	ds_read_b128 v[164:167], v168 offset:2048
	ds_read_b128 v[168:171], v168 offset:3072
	ds_read_b128 v[172:175], v216
	ds_read_b128 v[176:179], v216 offset:1024
	ds_read_b128 v[212:215], v216 offset:2048
	ds_read_b128 v[216:219], v216 offset:3072
	s_add_u32 s50, s50, 0x40000
	s_addc_u32 s51, s51, 0
	s_mov_b32 m0, s67
	v_lshl_add_u64 v[252:253], s[50:51], 0, v[128:129]
	ds_read_b128 v[220:223], v199 offset:32768
	ds_read_b128 v[224:227], v199 offset:33792
	ds_read_b128 v[228:231], v199 offset:34816
	ds_read_b128 v[232:235], v199 offset:35840
	ds_read_b128 v[236:239], v199 offset:36864
	ds_read_b128 v[240:243], v199 offset:37888
	ds_read_b128 v[244:247], v199 offset:38912
	ds_read_b128 v[248:251], v199 offset:39936
	global_load_lds_dwordx4 v[252:253], off
	v_lshl_add_u64 v[252:253], s[50:51], 0, v[132:133]
	s_mov_b32 m0, s68
	s_nop 0
	global_load_lds_dwordx4 v[252:253], off
	s_waitcnt vmcnt(8)
	s_waitcnt lgkmcnt(0)
	s_barrier
	s_setprio 1
	s_waitcnt lgkmcnt(0)
	v_mfma_f32_16x16x32_bf16 v[124:127], v[156:159], v[220:223], v[124:127]
	v_mfma_f32_16x16x32_bf16 v[120:123], v[164:167], v[220:223], v[120:123]
	v_mfma_f32_16x16x32_bf16 v[116:119], v[156:159], v[228:231], v[116:119]
	v_mfma_f32_16x16x32_bf16 v[112:115], v[164:167], v[228:231], v[112:115]
	v_mfma_f32_16x16x32_bf16 v[92:95], v[156:159], v[236:239], v[92:95]
	v_mfma_f32_16x16x32_bf16 v[88:91], v[164:167], v[236:239], v[88:91]
	v_mfma_f32_16x16x32_bf16 v[84:87], v[156:159], v[244:247], v[84:87]
	v_mfma_f32_16x16x32_bf16 v[80:83], v[164:167], v[244:247], v[80:83]
	v_mfma_f32_16x16x32_bf16 v[124:127], v[160:163], v[224:227], v[124:127]
	v_mfma_f32_16x16x32_bf16 v[120:123], v[168:171], v[224:227], v[120:123]
	v_mfma_f32_16x16x32_bf16 v[116:119], v[160:163], v[232:235], v[116:119]
	v_mfma_f32_16x16x32_bf16 v[112:115], v[168:171], v[232:235], v[112:115]
	v_mfma_f32_16x16x32_bf16 v[92:95], v[160:163], v[240:243], v[92:95]
	v_mfma_f32_16x16x32_bf16 v[88:91], v[168:171], v[240:243], v[88:91]
	v_mfma_f32_16x16x32_bf16 v[84:87], v[160:163], v[248:251], v[84:87]
	v_mfma_f32_16x16x32_bf16 v[80:83], v[168:171], v[248:251], v[80:83]
	v_mfma_f32_16x16x32_bf16 v[108:111], v[172:175], v[220:223], v[108:111]
	v_mfma_f32_16x16x32_bf16 v[104:107], v[212:215], v[220:223], v[104:107]
	v_mfma_f32_16x16x32_bf16 v[100:103], v[172:175], v[228:231], v[100:103]
	v_mfma_f32_16x16x32_bf16 v[96:99], v[212:215], v[228:231], v[96:99]
	v_mfma_f32_16x16x32_bf16 v[76:79], v[172:175], v[236:239], v[76:79]
	v_mfma_f32_16x16x32_bf16 v[72:75], v[212:215], v[236:239], v[72:75]
	v_mfma_f32_16x16x32_bf16 v[68:71], v[172:175], v[244:247], v[68:71]
	v_mfma_f32_16x16x32_bf16 v[64:67], v[212:215], v[244:247], v[64:67]
	v_mfma_f32_16x16x32_bf16 v[108:111], v[176:179], v[224:227], v[108:111]
	v_mfma_f32_16x16x32_bf16 v[104:107], v[216:219], v[224:227], v[104:107]
	v_mfma_f32_16x16x32_bf16 v[100:103], v[176:179], v[232:235], v[100:103]
	v_mfma_f32_16x16x32_bf16 v[96:99], v[216:219], v[232:235], v[96:99]
	v_mfma_f32_16x16x32_bf16 v[76:79], v[176:179], v[240:243], v[76:79]
	v_mfma_f32_16x16x32_bf16 v[72:75], v[216:219], v[240:243], v[72:75]
	v_mfma_f32_16x16x32_bf16 v[68:71], v[176:179], v[248:251], v[68:71]
	v_mfma_f32_16x16x32_bf16 v[64:67], v[216:219], v[248:251], v[64:67]
	s_setprio 0
	s_barrier
	s_add_u32 s50, s48, 0x8000
	s_addc_u32 s51, s49, 0
	s_add_i32 s55, s55, s64
	v_lshl_add_u64 v[252:253], s[50:51], 0, v[130:131]
	s_mov_b32 m0, s55
	ds_read_b128 v[220:223], v199 offset:49152
	ds_read_b128 v[224:227], v199 offset:50176
	ds_read_b128 v[228:231], v199 offset:51200
	ds_read_b128 v[232:235], v199 offset:52224
	ds_read_b128 v[236:239], v199 offset:53248
	ds_read_b128 v[240:243], v199 offset:54272
	ds_read_b128 v[244:247], v199 offset:55296
	ds_read_b128 v[248:251], v199 offset:56320
	global_load_lds_dwordx4 v[252:253], off
	s_add_i32 m0, s55, 0x2000
	s_add_u32 s48, s48, 0xc000
	v_lshl_add_u64 v[252:253], s[50:51], 0, v[134:135]
	s_addc_u32 s49, s49, 0
	s_add_i32 s50, s56, s64
	global_load_lds_dwordx4 v[252:253], off
	v_lshl_add_u64 v[252:253], s[48:49], 0, v[130:131]
	s_mov_b32 m0, s50
	v_lshl_add_u64 v[204:205], v[204:205], 0, s[14:15]
	global_load_lds_dwordx4 v[252:253], off
	v_lshl_add_u64 v[252:253], s[48:49], 0, v[134:135]
	s_add_i32 m0, s50, 0x2000
	s_nop 0
	global_load_lds_dwordx4 v[252:253], off
	s_mov_b32 m0, s74
	s_nop 0
	global_load_lds_dwordx4 v[204:205], off
	v_lshl_add_u64 v[204:205], v[206:207], 0, s[14:15]
	s_mov_b32 m0, s75
	s_nop 0
	global_load_lds_dwordx4 v[204:205], off
	s_waitcnt vmcnt(8)
	s_waitcnt lgkmcnt(0)
	s_barrier
	s_setprio 1
	s_waitcnt lgkmcnt(0)
	v_mfma_f32_16x16x32_bf16 v[60:63], v[156:159], v[220:223], v[60:63]
	v_mfma_f32_16x16x32_bf16 v[56:59], v[164:167], v[220:223], v[56:59]
	v_mfma_f32_16x16x32_bf16 v[52:55], v[156:159], v[228:231], v[52:55]
	v_mfma_f32_16x16x32_bf16 v[48:51], v[164:167], v[228:231], v[48:51]
	v_mfma_f32_16x16x32_bf16 v[28:31], v[156:159], v[236:239], v[28:31]
	v_mfma_f32_16x16x32_bf16 v[24:27], v[164:167], v[236:239], v[24:27]
	v_mfma_f32_16x16x32_bf16 v[20:23], v[156:159], v[244:247], v[20:23]
	v_mfma_f32_16x16x32_bf16 v[12:15], v[164:167], v[244:247], v[12:15]
	v_mfma_f32_16x16x32_bf16 v[60:63], v[160:163], v[224:227], v[60:63]
	v_mfma_f32_16x16x32_bf16 v[56:59], v[168:171], v[224:227], v[56:59]
	v_mfma_f32_16x16x32_bf16 v[52:55], v[160:163], v[232:235], v[52:55]
	v_mfma_f32_16x16x32_bf16 v[48:51], v[168:171], v[232:235], v[48:51]
	v_mfma_f32_16x16x32_bf16 v[28:31], v[160:163], v[240:243], v[28:31]
	v_mfma_f32_16x16x32_bf16 v[24:27], v[168:171], v[240:243], v[24:27]
	v_mfma_f32_16x16x32_bf16 v[20:23], v[160:163], v[248:251], v[20:23]
	v_mfma_f32_16x16x32_bf16 v[12:15], v[168:171], v[248:251], v[12:15]
	v_mfma_f32_16x16x32_bf16 v[44:47], v[172:175], v[220:223], v[44:47]
	v_mfma_f32_16x16x32_bf16 v[40:43], v[212:215], v[220:223], v[40:43]
	v_mfma_f32_16x16x32_bf16 v[36:39], v[172:175], v[228:231], v[36:39]
	v_mfma_f32_16x16x32_bf16 v[32:35], v[212:215], v[228:231], v[32:35]
	v_mfma_f32_16x16x32_bf16 v[16:19], v[172:175], v[236:239], v[16:19]
	v_mfma_f32_16x16x32_bf16 v[8:11], v[212:215], v[236:239], v[8:11]
	v_mfma_f32_16x16x32_bf16 v[4:7], v[172:175], v[244:247], v[4:7]
	v_mfma_f32_16x16x32_bf16 v[0:3], v[212:215], v[244:247], v[0:3]
	v_mfma_f32_16x16x32_bf16 v[44:47], v[176:179], v[224:227], v[44:47]
	v_mfma_f32_16x16x32_bf16 v[40:43], v[216:219], v[224:227], v[40:43]
	v_mfma_f32_16x16x32_bf16 v[36:39], v[176:179], v[232:235], v[36:39]
	v_mfma_f32_16x16x32_bf16 v[32:35], v[216:219], v[232:235], v[32:35]
	v_mfma_f32_16x16x32_bf16 v[16:19], v[176:179], v[240:243], v[16:19]
	v_mfma_f32_16x16x32_bf16 v[8:11], v[216:219], v[240:243], v[8:11]
	v_mfma_f32_16x16x32_bf16 v[4:7], v[176:179], v[248:251], v[4:7]
	v_mfma_f32_16x16x32_bf16 v[0:3], v[216:219], v[248:251], v[0:3]
	s_setprio 0
	s_barrier
	s_add_i32 s54, s54, 2
	s_add_u32 s52, s52, 0x10000
	s_addc_u32 s53, s53, 0
	s_add_u32 s46, s46, 0x100
	s_addc_u32 s47, s47, 0
	s_cmp_gt_u32 s54, 13
	s_cbranch_scc0 .LBB0_2358
	s_and_b64 vcc, exec, s[16:17]
	s_cbranch_vccz .LBB0_2361
	s_barrier

.LBB0_2519:
	ds_read_b128 v[144:147], v178
	ds_read_b128 v[148:151], v178 offset:1024
	ds_read_b128 v[152:155], v178 offset:2048
	ds_read_b128 v[156:159], v178 offset:3072
	ds_read_b128 v[160:163], v179
	ds_read_b128 v[164:167], v179 offset:1024
	ds_read_b128 v[182:185], v179 offset:2048
	ds_read_b128 v[186:189], v179 offset:3072
	s_add_u32 s34, s30, 0x4000
	s_addc_u32 s35, s31, 0
	s_cmp_eq_u32 s64, 40
	s_cselect_b32 s38, s4, s34
	s_cselect_b32 s39, s5, s35
	s_cselect_b32 s36, s28, s62
	s_cselect_b32 s37, s29, s63
	s_add_u32 s34, s38, 0x8000
	s_addc_u32 s35, s39, 0
	v_lshl_add_u64 v[222:223], s[30:31], 0, v[138:139]
	s_add_i32 m0, s42, 0xc000
	ds_read_b128 v[190:193], v180
	ds_read_b128 v[194:197], v180 offset:1024
	ds_read_b128 v[198:201], v180 offset:2048
	ds_read_b128 v[202:205], v180 offset:3072
	ds_read_b128 v[206:209], v180 offset:4096
	ds_read_b128 v[210:213], v180 offset:5120
	ds_read_b128 v[214:217], v180 offset:6144
	ds_read_b128 v[218:221], v180 offset:7168
	global_load_lds_dwordx4 v[222:223], off
	v_lshl_add_u64 v[222:223], s[30:31], 0, v[136:137]
	s_add_i32 m0, s42, 0xe000
	s_nop 0
	global_load_lds_dwordx4 v[222:223], off
	s_waitcnt vmcnt(8)
	s_waitcnt lgkmcnt(0)
	s_barrier
	s_setprio 1
	s_waitcnt lgkmcnt(0)
	v_mfma_f32_16x16x32_bf16 v[124:127], v[144:147], v[190:193], v[124:127]
	v_mfma_f32_16x16x32_bf16 v[120:123], v[152:155], v[190:193], v[120:123]
	v_mfma_f32_16x16x32_bf16 v[116:119], v[144:147], v[198:201], v[116:119]
	v_mfma_f32_16x16x32_bf16 v[112:115], v[152:155], v[198:201], v[112:115]
	v_mfma_f32_16x16x32_bf16 v[92:95], v[144:147], v[206:209], v[92:95]
	v_mfma_f32_16x16x32_bf16 v[88:91], v[152:155], v[206:209], v[88:91]
	v_mfma_f32_16x16x32_bf16 v[84:87], v[144:147], v[214:217], v[84:87]
	v_mfma_f32_16x16x32_bf16 v[80:83], v[152:155], v[214:217], v[80:83]
	v_mfma_f32_16x16x32_bf16 v[124:127], v[148:151], v[194:197], v[124:127]
	v_mfma_f32_16x16x32_bf16 v[120:123], v[156:159], v[194:197], v[120:123]
	v_mfma_f32_16x16x32_bf16 v[116:119], v[148:151], v[202:205], v[116:119]
	v_mfma_f32_16x16x32_bf16 v[112:115], v[156:159], v[202:205], v[112:115]
	v_mfma_f32_16x16x32_bf16 v[92:95], v[148:151], v[210:213], v[92:95]
	v_mfma_f32_16x16x32_bf16 v[88:91], v[156:159], v[210:213], v[88:91]
	v_mfma_f32_16x16x32_bf16 v[84:87], v[148:151], v[218:221], v[84:87]
	v_mfma_f32_16x16x32_bf16 v[80:83], v[156:159], v[218:221], v[80:83]
	v_mfma_f32_16x16x32_bf16 v[108:111], v[160:163], v[190:193], v[108:111]
	v_mfma_f32_16x16x32_bf16 v[104:107], v[182:185], v[190:193], v[104:107]
	v_mfma_f32_16x16x32_bf16 v[100:103], v[160:163], v[198:201], v[100:103]
	v_mfma_f32_16x16x32_bf16 v[96:99], v[182:185], v[198:201], v[96:99]
	v_mfma_f32_16x16x32_bf16 v[76:79], v[160:163], v[206:209], v[76:79]
	v_mfma_f32_16x16x32_bf16 v[72:75], v[182:185], v[206:209], v[72:75]
	v_mfma_f32_16x16x32_bf16 v[68:71], v[160:163], v[214:217], v[68:71]
	v_mfma_f32_16x16x32_bf16 v[64:67], v[182:185], v[214:217], v[64:67]
	v_mfma_f32_16x16x32_bf16 v[108:111], v[164:167], v[194:197], v[108:111]
	v_mfma_f32_16x16x32_bf16 v[104:107], v[186:189], v[194:197], v[104:107]
	v_mfma_f32_16x16x32_bf16 v[100:103], v[164:167], v[202:205], v[100:103]
	v_mfma_f32_16x16x32_bf16 v[96:99], v[186:189], v[202:205], v[96:99]
	v_mfma_f32_16x16x32_bf16 v[76:79], v[164:167], v[210:213], v[76:79]
	v_mfma_f32_16x16x32_bf16 v[72:75], v[186:189], v[210:213], v[72:75]
	v_mfma_f32_16x16x32_bf16 v[68:71], v[164:167], v[218:221], v[68:71]
	v_mfma_f32_16x16x32_bf16 v[64:67], v[186:189], v[218:221], v[64:67]
	s_setprio 0
	s_barrier
	s_add_i32 s65, s55, s41
	v_lshl_add_u64 v[222:223], s[36:37], 0, v[128:129]
	s_mov_b32 m0, s65
	ds_read_b128 v[190:193], v180 offset:16384
	ds_read_b128 v[194:197], v180 offset:17408
	ds_read_b128 v[198:201], v180 offset:18432
	ds_read_b128 v[202:205], v180 offset:19456
	ds_read_b128 v[206:209], v180 offset:20480
	ds_read_b128 v[210:213], v180 offset:21504
	ds_read_b128 v[214:217], v180 offset:22528
	ds_read_b128 v[218:221], v180 offset:23552
	global_load_lds_dwordx4 v[222:223], off
	s_add_i32 m0, s65, 0x2000
	s_add_u32 s66, s36, 0x4000
	v_lshl_add_u64 v[222:223], s[36:37], 0, v[130:131]
	s_addc_u32 s67, s37, 0
	s_add_i32 s65, s56, s41
	global_load_lds_dwordx4 v[222:223], off
	v_lshl_add_u64 v[222:223], s[66:67], 0, v[128:129]
	s_mov_b32 m0, s65
	s_nop 0
	global_load_lds_dwordx4 v[222:223], off
	v_lshl_add_u64 v[222:223], s[66:67], 0, v[130:131]
	s_add_i32 m0, s65, 0x2000
	s_nop 0
	global_load_lds_dwordx4 v[222:223], off
	v_lshl_add_u64 v[222:223], s[38:39], 0, v[128:129]
	s_mov_b32 m0, s42
	s_nop 0
	global_load_lds_dwordx4 v[222:223], off
	v_lshl_add_u64 v[222:223], s[38:39], 0, v[130:131]
	s_mov_b32 m0, s43
	s_nop 0
	global_load_lds_dwordx4 v[222:223], off
	s_waitcnt vmcnt(8)
	s_waitcnt lgkmcnt(0)
	s_barrier
	s_setprio 1
	s_waitcnt lgkmcnt(0)
	v_mfma_f32_16x16x32_bf16 v[60:63], v[144:147], v[190:193], v[60:63]
	v_mfma_f32_16x16x32_bf16 v[56:59], v[152:155], v[190:193], v[56:59]
	v_mfma_f32_16x16x32_bf16 v[52:55], v[144:147], v[198:201], v[52:55]
	v_mfma_f32_16x16x32_bf16 v[48:51], v[152:155], v[198:201], v[48:51]
	v_mfma_f32_16x16x32_bf16 v[28:31], v[144:147], v[206:209], v[28:31]
	v_mfma_f32_16x16x32_bf16 v[24:27], v[152:155], v[206:209], v[24:27]
	v_mfma_f32_16x16x32_bf16 v[20:23], v[144:147], v[214:217], v[20:23]
	v_mfma_f32_16x16x32_bf16 v[12:15], v[152:155], v[214:217], v[12:15]
	v_mfma_f32_16x16x32_bf16 v[60:63], v[148:151], v[194:197], v[60:63]
	v_mfma_f32_16x16x32_bf16 v[56:59], v[156:159], v[194:197], v[56:59]
	v_mfma_f32_16x16x32_bf16 v[52:55], v[148:151], v[202:205], v[52:55]
	v_mfma_f32_16x16x32_bf16 v[48:51], v[156:159], v[202:205], v[48:51]
	v_mfma_f32_16x16x32_bf16 v[28:31], v[148:151], v[210:213], v[28:31]
	v_mfma_f32_16x16x32_bf16 v[24:27], v[156:159], v[210:213], v[24:27]
	v_mfma_f32_16x16x32_bf16 v[20:23], v[148:151], v[218:221], v[20:23]
	v_mfma_f32_16x16x32_bf16 v[12:15], v[156:159], v[218:221], v[12:15]
	v_mfma_f32_16x16x32_bf16 v[44:47], v[160:163], v[190:193], v[44:47]
	v_mfma_f32_16x16x32_bf16 v[40:43], v[182:185], v[190:193], v[40:43]
	v_mfma_f32_16x16x32_bf16 v[36:39], v[160:163], v[198:201], v[36:39]
	v_mfma_f32_16x16x32_bf16 v[32:35], v[182:185], v[198:201], v[32:35]
	v_mfma_f32_16x16x32_bf16 v[16:19], v[160:163], v[206:209], v[16:19]
	v_mfma_f32_16x16x32_bf16 v[8:11], v[182:185], v[206:209], v[8:11]
	v_mfma_f32_16x16x32_bf16 v[4:7], v[160:163], v[214:217], v[4:7]
	v_mfma_f32_16x16x32_bf16 v[0:3], v[182:185], v[214:217], v[0:3]
	v_mfma_f32_16x16x32_bf16 v[44:47], v[164:167], v[194:197], v[44:47]
	v_mfma_f32_16x16x32_bf16 v[40:43], v[186:189], v[194:197], v[40:43]
	v_mfma_f32_16x16x32_bf16 v[36:39], v[164:167], v[202:205], v[36:39]
	v_mfma_f32_16x16x32_bf16 v[32:35], v[186:189], v[202:205], v[32:35]
	v_mfma_f32_16x16x32_bf16 v[16:19], v[164:167], v[210:213], v[16:19]
	v_mfma_f32_16x16x32_bf16 v[8:11], v[186:189], v[210:213], v[8:11]
	v_mfma_f32_16x16x32_bf16 v[4:7], v[164:167], v[218:221], v[4:7]
	v_mfma_f32_16x16x32_bf16 v[0:3], v[186:189], v[218:221], v[0:3]
	s_setprio 0
	s_barrier
	s_add_i32 s65, 0, 0x18000
	s_add_i32 s66, 0, 0x1c000
	v_add_u32_e32 v156, s65, v170
	v_add_u32_e32 v186, s66, v170
	ds_read_b128 v[144:147], v156
	ds_read_b128 v[148:151], v156 offset:1024
	ds_read_b128 v[152:155], v156 offset:2048
	ds_read_b128 v[156:159], v156 offset:3072
	ds_read_b128 v[160:163], v186
	ds_read_b128 v[164:167], v186 offset:1024
	ds_read_b128 v[182:185], v186 offset:2048
	ds_read_b128 v[186:189], v186 offset:3072
	s_add_u32 s38, s38, 0x4000
	s_addc_u32 s39, s39, 0
	s_mov_b32 m0, s44
	v_lshl_add_u64 v[222:223], s[38:39], 0, v[128:129]
	ds_read_b128 v[190:193], v180 offset:32768
	ds_read_b128 v[194:197], v180 offset:33792
	ds_read_b128 v[198:201], v180 offset:34816
	ds_read_b128 v[202:205], v180 offset:35840
	ds_read_b128 v[206:209], v180 offset:36864
	ds_read_b128 v[210:213], v180 offset:37888
	ds_read_b128 v[214:217], v180 offset:38912
	ds_read_b128 v[218:221], v180 offset:39936
	global_load_lds_dwordx4 v[222:223], off
	v_lshl_add_u64 v[222:223], s[38:39], 0, v[130:131]
	s_mov_b32 m0, s45
	s_nop 0
	global_load_lds_dwordx4 v[222:223], off
	s_waitcnt vmcnt(8)
	s_waitcnt lgkmcnt(0)
	s_barrier
	s_setprio 1
	s_waitcnt lgkmcnt(0)
	v_mfma_f32_16x16x32_bf16 v[124:127], v[144:147], v[190:193], v[124:127]
	v_mfma_f32_16x16x32_bf16 v[120:123], v[152:155], v[190:193], v[120:123]
	v_mfma_f32_16x16x32_bf16 v[116:119], v[144:147], v[198:201], v[116:119]
	v_mfma_f32_16x16x32_bf16 v[112:115], v[152:155], v[198:201], v[112:115]
	v_mfma_f32_16x16x32_bf16 v[92:95], v[144:147], v[206:209], v[92:95]
	v_mfma_f32_16x16x32_bf16 v[88:91], v[152:155], v[206:209], v[88:91]
	v_mfma_f32_16x16x32_bf16 v[84:87], v[144:147], v[214:217], v[84:87]
	v_mfma_f32_16x16x32_bf16 v[80:83], v[152:155], v[214:217], v[80:83]
	v_mfma_f32_16x16x32_bf16 v[124:127], v[148:151], v[194:197], v[124:127]
	v_mfma_f32_16x16x32_bf16 v[120:123], v[156:159], v[194:197], v[120:123]
	v_mfma_f32_16x16x32_bf16 v[116:119], v[148:151], v[202:205], v[116:119]
	v_mfma_f32_16x16x32_bf16 v[112:115], v[156:159], v[202:205], v[112:115]
	v_mfma_f32_16x16x32_bf16 v[92:95], v[148:151], v[210:213], v[92:95]
	v_mfma_f32_16x16x32_bf16 v[88:91], v[156:159], v[210:213], v[88:91]
	v_mfma_f32_16x16x32_bf16 v[84:87], v[148:151], v[218:221], v[84:87]
	v_mfma_f32_16x16x32_bf16 v[80:83], v[156:159], v[218:221], v[80:83]
	v_mfma_f32_16x16x32_bf16 v[108:111], v[160:163], v[190:193], v[108:111]
	v_mfma_f32_16x16x32_bf16 v[104:107], v[182:185], v[190:193], v[104:107]
	v_mfma_f32_16x16x32_bf16 v[100:103], v[160:163], v[198:201], v[100:103]
	v_mfma_f32_16x16x32_bf16 v[96:99], v[182:185], v[198:201], v[96:99]
	v_mfma_f32_16x16x32_bf16 v[76:79], v[160:163], v[206:209], v[76:79]
	v_mfma_f32_16x16x32_bf16 v[72:75], v[182:185], v[206:209], v[72:75]
	v_mfma_f32_16x16x32_bf16 v[68:71], v[160:163], v[214:217], v[68:71]
	v_mfma_f32_16x16x32_bf16 v[64:67], v[182:185], v[214:217], v[64:67]
	v_mfma_f32_16x16x32_bf16 v[108:111], v[164:167], v[194:197], v[108:111]
	v_mfma_f32_16x16x32_bf16 v[104:107], v[186:189], v[194:197], v[104:107]
	v_mfma_f32_16x16x32_bf16 v[100:103], v[164:167], v[202:205], v[100:103]
	v_mfma_f32_16x16x32_bf16 v[96:99], v[186:189], v[202:205], v[96:99]
	v_mfma_f32_16x16x32_bf16 v[76:79], v[164:167], v[210:213], v[76:79]
	v_mfma_f32_16x16x32_bf16 v[72:75], v[186:189], v[210:213], v[72:75]
	v_mfma_f32_16x16x32_bf16 v[68:71], v[164:167], v[218:221], v[68:71]
	v_mfma_f32_16x16x32_bf16 v[64:67], v[186:189], v[218:221], v[64:67]
	s_setprio 0
	s_barrier
	s_add_u32 s38, s36, 0x8000
	s_addc_u32 s39, s37, 0
	s_add_i32 s65, s65, s41
	v_lshl_add_u64 v[222:223], s[38:39], 0, v[128:129]
	s_mov_b32 m0, s65
	ds_read_b128 v[190:193], v180 offset:49152
	ds_read_b128 v[194:197], v180 offset:50176
	ds_read_b128 v[198:201], v180 offset:51200
	ds_read_b128 v[202:205], v180 offset:52224
	ds_read_b128 v[206:209], v180 offset:53248
	ds_read_b128 v[210:213], v180 offset:54272
	ds_read_b128 v[214:217], v180 offset:55296
	ds_read_b128 v[218:221], v180 offset:56320
	global_load_lds_dwordx4 v[222:223], off
	s_add_i32 m0, s65, 0x2000
	s_add_u32 s36, s36, 0xc000
	v_lshl_add_u64 v[222:223], s[38:39], 0, v[130:131]
	s_addc_u32 s37, s37, 0
	s_add_i32 s38, s66, s41
	global_load_lds_dwordx4 v[222:223], off
	v_lshl_add_u64 v[222:223], s[36:37], 0, v[128:129]
	s_mov_b32 m0, s38
	s_nop 0
	global_load_lds_dwordx4 v[222:223], off
	v_lshl_add_u64 v[222:223], s[36:37], 0, v[130:131]
	s_add_i32 m0, s38, 0x2000
	s_nop 0
	global_load_lds_dwordx4 v[222:223], off
	v_lshl_add_u64 v[222:223], s[34:35], 0, v[128:129]
	s_mov_b32 m0, s51
	s_nop 0
	global_load_lds_dwordx4 v[222:223], off
	v_lshl_add_u64 v[222:223], s[34:35], 0, v[130:131]
	s_mov_b32 m0, s52
	s_nop 0
	global_load_lds_dwordx4 v[222:223], off
	s_waitcnt vmcnt(8)
	s_waitcnt lgkmcnt(0)
	s_barrier
	s_setprio 1
	s_waitcnt lgkmcnt(0)
	v_mfma_f32_16x16x32_bf16 v[60:63], v[144:147], v[190:193], v[60:63]
	v_mfma_f32_16x16x32_bf16 v[56:59], v[152:155], v[190:193], v[56:59]
	v_mfma_f32_16x16x32_bf16 v[52:55], v[144:147], v[198:201], v[52:55]
	v_mfma_f32_16x16x32_bf16 v[48:51], v[152:155], v[198:201], v[48:51]
	v_mfma_f32_16x16x32_bf16 v[28:31], v[144:147], v[206:209], v[28:31]
	v_mfma_f32_16x16x32_bf16 v[24:27], v[152:155], v[206:209], v[24:27]
	v_mfma_f32_16x16x32_bf16 v[20:23], v[144:147], v[214:217], v[20:23]
	v_mfma_f32_16x16x32_bf16 v[12:15], v[152:155], v[214:217], v[12:15]
	v_mfma_f32_16x16x32_bf16 v[60:63], v[148:151], v[194:197], v[60:63]
	v_mfma_f32_16x16x32_bf16 v[56:59], v[156:159], v[194:197], v[56:59]
	v_mfma_f32_16x16x32_bf16 v[52:55], v[148:151], v[202:205], v[52:55]
	v_mfma_f32_16x16x32_bf16 v[48:51], v[156:159], v[202:205], v[48:51]
	v_mfma_f32_16x16x32_bf16 v[28:31], v[148:151], v[210:213], v[28:31]
	v_mfma_f32_16x16x32_bf16 v[24:27], v[156:159], v[210:213], v[24:27]
	v_mfma_f32_16x16x32_bf16 v[20:23], v[148:151], v[218:221], v[20:23]
	v_mfma_f32_16x16x32_bf16 v[12:15], v[156:159], v[218:221], v[12:15]
	v_mfma_f32_16x16x32_bf16 v[44:47], v[160:163], v[190:193], v[44:47]
	v_mfma_f32_16x16x32_bf16 v[40:43], v[182:185], v[190:193], v[40:43]
	v_mfma_f32_16x16x32_bf16 v[36:39], v[160:163], v[198:201], v[36:39]
	v_mfma_f32_16x16x32_bf16 v[32:35], v[182:185], v[198:201], v[32:35]
	v_mfma_f32_16x16x32_bf16 v[16:19], v[160:163], v[206:209], v[16:19]
	v_mfma_f32_16x16x32_bf16 v[8:11], v[182:185], v[206:209], v[8:11]
	v_mfma_f32_16x16x32_bf16 v[4:7], v[160:163], v[214:217], v[4:7]
	v_mfma_f32_16x16x32_bf16 v[0:3], v[182:185], v[214:217], v[0:3]
	v_mfma_f32_16x16x32_bf16 v[44:47], v[164:167], v[194:197], v[44:47]
	v_mfma_f32_16x16x32_bf16 v[40:43], v[186:189], v[194:197], v[40:43]
	v_mfma_f32_16x16x32_bf16 v[36:39], v[164:167], v[202:205], v[36:39]
	v_mfma_f32_16x16x32_bf16 v[32:35], v[186:189], v[202:205], v[32:35]
	v_mfma_f32_16x16x32_bf16 v[16:19], v[164:167], v[210:213], v[16:19]
	v_mfma_f32_16x16x32_bf16 v[8:11], v[186:189], v[210:213], v[8:11]
	v_mfma_f32_16x16x32_bf16 v[4:7], v[164:167], v[218:221], v[4:7]
	v_mfma_f32_16x16x32_bf16 v[0:3], v[186:189], v[218:221], v[0:3]
	s_setprio 0
	s_barrier
	s_add_i32 s64, s64, 2
	s_add_u32 s62, s62, 0x10000
	s_addc_u32 s63, s63, 0
	s_add_u32 s30, s30, 0x10000
	s_addc_u32 s31, s31, 0
	s_cmp_gt_u32 s64, 41
	s_cbranch_scc0 .LBB0_2519
	s_and_b64 vcc, exec, s[14:15]
	s_cbranch_vccz .LBB0_2522
	s_barrier
